# G1 mLSTM q/k conv+silu epilogue rewritten by hand (weights prefetched per group, interleaved packed chains); G1 rotary epilogue rotates all rows before storing; gn gains staged in LDS for mix2 final p
# speedup vs baseline: 1.0784x; 1.0147x over previous
; __device__ void mix_sweep(const Params& P, LAS unsigned char* lds, int tok0, int pos0, int seqlen, int hd, int dir, bool state_only, bool final_pass,
;                           f32x4 (&Cacc)[9], float& m_state, float& aseg_sum, float lgam) {
;     ...
;     FragB FB; fragb_init(FB, w, fr, fg);
;     unsigned ktb0, ktb1; { const unsigned q = fr >> 2, p = fr & 3, L = (q << 2) | ((fg & 1u) << 1) | (p >> 1); ktb0 = 256u * (8u * fg + q) + 8u * (p & 1u) + 16u * (L ^ (2u * w)); ktb1 = 256u * (8u * fg + q) + 8u * (p & 1u) + 16u * (L ^ (2u * w + 1u)); asm volatile("" : "+v"(ktb0)); asm volatile("" : "+v"(ktb1)); }
;     __syncthreads();
;     if (!state_only) {
; #pragma unroll
;         for (int nt = 0; nt < 8; ++nt) { u32x2 v; v.x = cvt_pk_bf16(Cacc[nt][0], Cacc[nt][1]); v.y = cvt_pk_bf16(Cacc[nt][2], Cacc[nt][3]);
;             { LAUNDER_X16 *(LAS u32x2*)(lds + IMG_C + CWA(nt)) = v; } }
;         { u32x2 v; v.x = cvt_pk_bf16(Cacc[8][0], Cacc[8][1]); v.y = cvt_pk_bf16(Cacc[8][2], Cacc[8][3]); *(LAS u32x2*)(lds + IMG_CX + 32 * (16 * w + fr) + 8 * fg) = v; }
;     }
;     if (tid < 128) { unsigned zz = 0u; asm volatile("" : "+v"(zz)); u32x4 v0 = (u32x4){is_m ? 0x3F80u : zz, zz, zz, zz}; u32x4 z = (u32x4){zz, zz, zz, zz}; *(LAS u32x4*)(lds + IMG_VX + 32 * tid) = v0; *(LAS u32x4*)(lds + IMG_VX + 32 * tid + 16) = z; }
;     LAS float* PV = (LAS float*)(lds + 141888); LAS float* PS = PV + 8 * 3 * 128;
;     if (is_m) { const int c = dir ? 7 - w : w; const int tokc = tok0 + c * 128;
;         const int u0 = 2 * lane, u1 = 2 * lane + 1; const int j0 = dir ? 127 - u0 : u0, j1 = dir ? 127 - u1 : u1;
;         const float x0 = gates[(size_t)(tokc + j0) * 16 + 8 + dir * 4 + h], x1 = gates[(size_t)(tokc + j1) * 16 + 8 + dir * 4 + h];
;         const float i0 = gates[(size_t)(tokc + j0) * 16 + dir * 4 + h], i1 = gates[(size_t)(tokc + j1) * 16 + dir * 4 + h];
;         const float ps = x0 + x1; float sc = ps;
; #pragma unroll
;         for (int o = 1; o < 64; o <<= 1) { const float t = __shfl_up(sc, o); if (lane >= o) sc += t; }
;         const float excl = sc - ps, A0 = excl + x0, A1 = excl + ps, Atot = __shfl(sc, 63);
;         const float b0 = i0 - A0, b1 = i1 - A1; const float pm = fmaxf(b0, b1); float scm = pm;
; #pragma unroll
;         for (int o = 1; o < 64; o <<= 1) { const float t = __shfl_up(scm, o); if (lane >= o) scm = fmaxf(scm, t); }
.LBB0_96:
	s_and_b64 s[14:15], s[8:9], exec
	v_and_b32_e32 v0, 0x78, v0
	s_cselect_b32 s14, 0, 0x380
	v_lshlrev_b32_e32 v0, 1, v0
	s_or_b32 s14, s14, s79
	s_waitcnt lgkmcnt(2)
	v_lshl_add_u64 v[2:3], s[22:23], 0, v[0:1]
	v_ashrrev_i32_e32 v0, 4, v161
	v_add_u32_e32 v40, s14, v0
	v_add_u32_e32 v0, 0x200, v161
	v_ashrrev_i32_e32 v0, 4, v0
	v_add_u32_e32 v42, s14, v0
	v_add_u32_e32 v0, 0x400, v161
	v_ashrrev_i32_e32 v0, 4, v0
	v_add_u32_e32 v50, s14, v0
	v_add_u32_e32 v0, 0x600, v161
	v_ashrrev_i32_e32 v0, 4, v0
	v_add_u32_e32 v52, s14, v0
	v_ashrrev_i32_e32 v41, 31, v40
	s_lshl_b32 s38, s80, 1
	v_ashrrev_i32_e32 v43, 31, v42
	v_ashrrev_i32_e32 v51, 31, v50
	v_ashrrev_i32_e32 v53, 31, v52
	s_lshl_b32 s14, s81, 1
	s_mov_b32 s15, s39
	v_lshlrev_b64 v[56:57], 13, v[40:41]
	v_lshl_add_u64 v[48:49], v[2:3], 0, s[38:39]
	v_lshlrev_b64 v[58:59], 13, v[42:43]
	v_lshlrev_b64 v[64:65], 13, v[50:51]
	v_lshlrev_b64 v[66:67], 13, v[52:53]
	v_lshl_add_u64 v[2:3], v[2:3], 0, s[14:15]
	v_lshl_add_u64 v[40:41], v[48:49], 0, v[56:57]
	v_lshl_add_u64 v[44:45], v[48:49], 0, v[58:59]
	v_lshl_add_u64 v[50:51], v[48:49], 0, v[64:65]
	v_lshl_add_u64 v[52:53], v[48:49], 0, v[66:67]
	v_lshl_add_u64 v[56:57], v[2:3], 0, v[56:57]
	v_lshl_add_u64 v[60:61], v[2:3], 0, v[58:59]
	v_lshl_add_u64 v[64:65], v[2:3], 0, v[64:65]
	global_load_dwordx4 v[40:43], v[40:41], off
	s_nop 0
	global_load_dwordx4 v[44:47], v[44:45], off
	s_nop 0
	global_load_dwordx4 v[48:51], v[50:51], off
	s_nop 0
	global_load_dwordx4 v[52:55], v[52:53], off
	s_nop 0
	global_load_dwordx4 v[56:59], v[56:57], off
	s_nop 0
	global_load_dwordx4 v[60:63], v[60:61], off
	v_lshl_add_u64 v[2:3], v[2:3], 0, v[66:67]
	global_load_dwordx4 v[64:67], v[64:65], off
	s_nop 0
	global_load_dwordx4 v[68:71], v[2:3], off
	v_lshlrev_b32_e32 v79, 2, v161
	s_add_i32 s15, 0, 0x22000
	v_add_u32_e32 v182, s15, v79
	s_add_i32 s15, 0, 0x22200
	v_lshlrev_b32_e32 v0, 4, v73
	v_add_u32_e32 v183, s15, v79
	v_add_u32_e32 v190, s15, v0
	v_readlane_b32 s15, v253, 49
	s_add_i32 s19, 0, 0x22400
	v_add_u32_e32 v184, s19, v79
	v_add_u32_e32 v194, s15, v75
	s_add_i32 s15, 0, 0x1a000
	v_add_u32_e32 v195, s15, v75
	v_readlane_b32 s15, v253, 50
	s_add_i32 s19, 0, 0x22600
	s_add_i32 s46, 0, 0x22800
	v_add_u32_e32 v196, s15, v75
	s_add_i32 s15, 0, 0x1c000
	v_add_u32_e32 v197, s15, v75
	v_readlane_b32 s15, v253, 51
	v_lshlrev_b32_e32 v189, 2, v73
	v_mov_b32_e32 v73, v1
	v_add_u32_e32 v198, s15, v75
	s_add_i32 s15, 0, 0x1e000
	v_add_u32_e32 v199, s15, v75
	v_readlane_b32 s15, v253, 52
	s_add_i32 s85, 0, 0x10000
	s_mov_b32 s7, 0
	v_add_u32_e32 v200, s15, v75
	v_readlane_b32 s15, v253, 53
	s_mov_b32 s83, 1
	v_add_u32_e32 v185, s19, v79
	v_add_u32_e32 v247, s15, v75
	s_add_i32 s15, 0, 0x12000
	v_add_u32_e32 v248, s15, v75
	v_readlane_b32 s15, v253, 54
	v_add_u32_e32 v187, s46, v79
	v_cmp_eq_u32_e64 s[46:47], 0, v161
	v_add_u32_e32 v249, s15, v75
	s_add_i32 s15, 0, 0x14000
	v_add_u32_e32 v250, s15, v75
	v_readlane_b32 s15, v253, 55
	v_lshl_or_b32 v219, s16, 4, v169
	s_add_i32 s84, s17, 0
	v_add_u32_e32 v251, s15, v75
	s_add_i32 s15, 0, 0x16000
	v_add_u32_e32 v252, s15, v75
	v_readlane_b32 s15, v253, 56
	v_add_u32_e32 v191, 0, v78
	v_lshl_add_u32 v192, v72, 2, s19
	v_lshl_add_u64 v[2:3], s[2:3], 0, v[72:73]
	v_lshl_add_u64 v[152:153], s[4:5], 0, v[72:73]
	v_lshl_add_u64 v[154:155], s[94:95], 0, v[0:1]
	v_add_u32_e32 v193, s18, v75
	v_or_b32_e32 v201, 2, v189
	v_or_b32_e32 v202, 3, v189
	v_or_b32_e32 v204, 16, v189
	v_or_b32_e32 v205, 17, v189
	v_or_b32_e32 v206, 18, v189
	v_or_b32_e32 v207, 19, v189
	v_or_b32_e32 v222, 32, v189
	v_or_b32_e32 v223, 33, v189
	v_or_b32_e32 v224, 34, v189
	v_or_b32_e32 v225, 35, v189
	v_or_b32_e32 v226, 48, v189
	v_or_b32_e32 v227, 49, v189
	v_or_b32_e32 v228, 50, v189
	v_or_b32_e32 v229, 51, v189
	v_or_b32_e32 v230, 64, v189
	v_or_b32_e32 v231, 0x41, v189
	v_or_b32_e32 v232, 0x42, v189
	v_or_b32_e32 v233, 0x43, v189
	v_or_b32_e32 v234, 0x50, v189
	v_or_b32_e32 v235, 0x51, v189
	v_or_b32_e32 v236, 0x52, v189
	v_or_b32_e32 v237, 0x53, v189
	v_or_b32_e32 v238, 0x60, v189
	v_or_b32_e32 v239, 0x61, v189
	v_or_b32_e32 v240, 0x62, v189
	v_or_b32_e32 v241, 0x63, v189
	v_or_b32_e32 v242, 0x70, v189
	v_or_b32_e32 v243, 0x71, v189
	v_or_b32_e32 v244, 0x72, v189
	v_or_b32_e32 v245, 0x73, v189
	v_add_u32_e32 v246, s85, v75
	v_add_u32_e32 v211, s15, v75
	v_add_u32_e32 v164, 0, v79
	s_mov_b32 s86, 6
	s_movk_i32 s87, 0xd000
	v_add_u32_e32 v165, 0, v76
	v_add_u32_e32 v166, 0, v77
	v_add_u32_e32 v167, 0, v74
	v_readlane_b32 s88, v253, 57
	v_lshrrev_b32_e32 v80, 6, v161
	v_lshlrev_b32_e32 v80, 6, v80
	v_mov_b32_e32 v81, 0
	v_lshl_add_u64 v[82:83], v[154:155], 0, v[80:81]
	global_load_dwordx4 v[84:87], v[82:83], off
	v_bfe_u32 v81, v161, 4, 2
	v_lshl_add_u32 v80, v81, 4, v80
	v_add_u32_e32 v80, 0x25a80, v80
	s_waitcnt vmcnt(0)
	ds_write_b128 v80, v[84:87]
	s_branch .LBB0_98

; __device__ __forceinline__ float bf_lo(unsigned w) { return __uint_as_float(w << 16); }
; __device__ __forceinline__ float bf_hi(unsigned w) { return __uint_as_float(w & 0xffff0000u); }
; __device__ void mix_sweep(const Params& P, LAS unsigned char* lds, int tok0, int pos0, int seqlen, int hd, int dir, bool state_only, bool final_pass,
;                           f32x4 (&Cacc)[9], float& m_state, float& aseg_sum, float lgam) {
;     ...
;                 float sum = 0.f;
;                 const bf16_t* grow = proj + (size_t)(tok + irow) * NPROJ + gcol + 4 * fg;
;                 u32x2 hbv[8], gvv[8];
; #pragma unroll
;                 for (int nt = 0; nt < 8; ++nt) { hbv[nt] = *(const u32x2*)(mrow + 16 * nt); gvv[nt] = *(const u32x2*)(grow + 16 * nt); }
;                 __builtin_amdgcn_sched_barrier(0);
; #pragma unroll
;                 for (int nt = 0; nt < 8; ++nt) { const u32x2 hb = hbv[nt];
;                     O[nt][0] = O[nt][0] * hs + bf_lo(hb.x); O[nt][1] = O[nt][1] * hs + bf_hi(hb.x); O[nt][2] = O[nt][2] * hs + bf_lo(hb.y); O[nt][3] = O[nt][3] * hs + bf_hi(hb.y);
;                     sum += O[nt][0] + O[nt][1] + O[nt][2] + O[nt][3]; }
;                 sum += __shfl_xor(sum, 16); sum += __shfl_xor(sum, 32);
;                 const float mu = sum * (1.0f / 128.0f); float sq = 0.f;
; #pragma unroll
;                 for (int nt = 0; nt < 8; ++nt)
; #pragma unroll
;                     for (int e = 0; e < 4; ++e) { const float d = O[nt][e] - mu; sq += d * d; }
;                 sq += __shfl_xor(sq, 16); sq += __shfl_xor(sq, 32);
;                 const float rs = rsqrtf(sq * (1.0f / 128.0f) + 1e-5f);
; #pragma unroll
;                 for (int nt = 0; nt < 8; ++nt) { const u32x2 gv = gvv[nt]; const f32x4 gw = *(const f32x4*)(gnw + 16 * nt + 4 * fg);
.LBB0_369:
	s_andn2_b64 vcc, exec, s[16:17]
	s_cbranch_vccnz .LBB0_97
	v_lshlrev_b64 v[74:75], 13, v[74:75]
	v_lshl_add_u64 v[74:75], v[152:153], 0, v[74:75]
	global_load_dwordx2 v[88:89], v[72:73], off
	global_load_dwordx2 v[92:93], v[72:73], off offset:32
	global_load_dwordx2 v[96:97], v[72:73], off offset:64
	global_load_dwordx2 v[98:99], v[72:73], off offset:96
	global_load_dwordx2 v[148:149], v[74:75], off
	global_load_dwordx2 v[146:147], v[74:75], off offset:32
	global_load_dwordx2 v[110:111], v[74:75], off offset:64
	global_load_dwordx2 v[104:105], v[74:75], off offset:96
	global_load_dwordx2 v[150:151], v[72:73], off offset:128
	global_load_dwordx2 v[156:157], v[72:73], off offset:160
	global_load_dwordx2 v[158:159], v[72:73], off offset:192
	global_load_dwordx2 v[170:171], v[72:73], off offset:224
	global_load_dwordx2 v[94:95], v[74:75], off offset:128
	global_load_dwordx2 v[84:85], v[74:75], off offset:160
	global_load_dwordx2 v[76:77], v[74:75], off offset:192
	s_nop 0
	global_load_dwordx2 v[74:75], v[74:75], off offset:224
	v_mov_b32_e32 v100, v80
	v_mov_b32_e32 v101, v112
	s_waitcnt vmcnt(14)
	v_lshlrev_b32_e32 v103, 16, v92
	v_lshlrev_b32_e32 v102, 16, v88
	v_mov_b32_e32 v112, v81
	v_and_b32_e32 v81, 0xffff0000, v92
	v_and_b32_e32 v80, 0xffff0000, v88
	v_pk_fma_f32 v[144:145], v[100:101], v[0:1], v[102:103] op_sel_hi:[1,0,1]
	v_pk_fma_f32 v[142:143], v[112:113], v[0:1], v[80:81] op_sel_hi:[1,0,1]
	v_mov_b32_e32 v80, v82
	v_mov_b32_e32 v81, v114
	v_lshlrev_b32_e32 v101, 16, v93
	v_lshlrev_b32_e32 v100, 16, v89
	v_pk_fma_f32 v[140:141], v[80:81], v[0:1], v[100:101] op_sel_hi:[1,0,1]
	v_mov_b32_e32 v114, v83
	v_and_b32_e32 v81, 0xffff0000, v93
	v_and_b32_e32 v80, 0xffff0000, v89
	v_pk_fma_f32 v[114:115], v[114:115], v[0:1], v[80:81] op_sel_hi:[1,0,1]
	v_pk_add_f32 v[80:81], v[144:145], v[142:143]
	s_waitcnt vmcnt(12)
	v_lshlrev_b32_e32 v90, 16, v98
	v_pk_add_f32 v[80:81], v[140:141], v[80:81]
	v_and_b32_e32 v106, 0xffff0000, v98
	v_pk_add_f32 v[80:81], v[114:115], v[80:81]
	v_fmac_f32_e32 v90, v128, v0
	v_add_f32_e32 v80, 0, v80
	v_add_f32_e32 v86, v80, v81
	v_lshlrev_b32_e32 v80, 16, v96
	v_and_b32_e32 v81, 0xffff0000, v96
	v_pk_fma_f32 v[112:113], v[120:121], v[0:1], v[80:81] op_sel_hi:[1,0,1]
	v_and_b32_e32 v81, 0xffff0000, v97
	v_lshlrev_b32_e32 v80, 16, v97
	v_pk_fma_f32 v[108:109], v[122:123], v[0:1], v[80:81] op_sel_hi:[1,0,1]
	v_pk_add_f32 v[80:81], v[112:113], v[112:113] op_sel:[0,1] op_sel_hi:[1,0]
	v_fmac_f32_e32 v106, v129, v0
	v_pk_add_f32 v[80:81], v[108:109], v[80:81]
	s_waitcnt vmcnt(7)
	v_and_b32_e32 v107, 0xffff0000, v150
	v_and_b32_e32 v92, 0xffff0000, v151
	v_mov_b32_e32 v82, v130
	v_mov_b32_e32 v83, v136
	v_lshlrev_b32_e32 v89, 16, v150
	v_lshlrev_b32_e32 v88, 16, v99
	v_pk_add_f32 v[80:81], v[108:109], v[80:81] op_sel:[1,0] op_sel_hi:[0,1]
	v_pk_fma_f32 v[102:103], v[82:83], v[0:1], v[88:89] op_sel_hi:[1,0,1]
	v_pk_add_f32 v[100:101], v[90:91], v[106:107]
	v_pk_mov_b32 v[82:83], v[130:131], v[138:139] op_sel:[1,0]
	v_and_b32_e32 v88, 0xffff0000, v99
	v_lshlrev_b32_e32 v89, 16, v151
	v_mov_b32_e32 v81, v92
	v_pk_fma_f32 v[96:97], v[82:83], v[0:1], v[88:89] op_sel_hi:[1,0,1]
	v_pk_add_f32 v[92:93], v[86:87], v[80:81]
	v_pk_add_f32 v[80:81], v[102:103], v[100:101]
	s_waitcnt vmcnt(4)
	v_and_b32_e32 v91, 0xffff0000, v171
	v_pk_add_f32 v[80:81], v[96:97], v[80:81]
	v_mov_b32_e32 v120, v126
	v_pk_add_f32 v[82:83], v[92:93], v[80:81]
	v_lshlrev_b32_e32 v80, 16, v156
	v_and_b32_e32 v81, 0xffff0000, v156
	v_pk_fma_f32 v[86:87], v[132:133], v[0:1], v[80:81] op_sel_hi:[1,0,1]
	v_and_b32_e32 v81, 0xffff0000, v157
	v_lshlrev_b32_e32 v80, 16, v157
	v_pk_fma_f32 v[80:81], v[134:135], v[0:1], v[80:81] op_sel_hi:[1,0,1]
	v_pk_add_f32 v[88:89], v[86:87], v[86:87] op_sel:[0,1] op_sel_hi:[1,0]
	v_pk_add_f32 v[82:83], v[82:83], v[82:83] op_sel:[0,1] op_sel_hi:[1,0]
	v_pk_add_f32 v[88:89], v[80:81], v[88:89]
	v_mov_b32_e32 v121, v116
	v_pk_add_f32 v[88:89], v[80:81], v[88:89] op_sel:[1,0] op_sel_hi:[0,1]
	v_lshlrev_b32_e32 v117, 16, v170
	v_lshlrev_b32_e32 v116, 16, v159
	v_mov_b32_e32 v83, v78
	v_mov_b32_e32 v89, v91
	v_pk_fma_f32 v[120:121], v[120:121], v[0:1], v[116:117] op_sel_hi:[1,0,1]
	v_pk_mov_b32 v[116:117], v[126:127], v[118:119] op_sel:[1,0]
	v_pk_add_f32 v[126:127], v[82:83], v[88:89]
	v_and_b32_e32 v82, 64, v203
	v_xor_b32_e32 v78, 16, v203
	v_add_u32_e32 v91, 64, v82
	v_cmp_lt_i32_e32 vcc, v78, v91
	v_and_b32_e32 v83, 0xffff0000, v158
	v_lshlrev_b32_e32 v82, 16, v158
	v_cndmask_b32_e32 v78, v203, v78, vcc
	v_pk_fma_f32 v[82:83], v[124:125], v[0:1], v[82:83] op_sel_hi:[1,0,1]
	v_and_b32_e32 v99, 0xffff0000, v170
	v_lshlrev_b32_e32 v100, 2, v78
	v_mov_b32_e32 v78, v82
	v_mov_b32_e32 v98, v83
	v_and_b32_e32 v118, 0xffff0000, v159
	v_lshlrev_b32_e32 v119, 16, v171
	v_pk_add_f32 v[78:79], v[78:79], v[98:99]
	v_pk_fma_f32 v[122:123], v[116:117], v[0:1], v[118:119] op_sel_hi:[1,0,1]
	v_pk_add_f32 v[88:89], v[120:121], v[78:79]
	v_bfe_u32 v116, v161, 4, 2
	v_lshlrev_b32_e32 v116, 4, v116
	v_add_u32_e32 v116, 0x25a80, v116
	ds_read_b128 v[116:119], v116
	v_pk_add_f32 v[88:89], v[122:123], v[88:89]
	s_nop 0
	v_pk_add_f32 v[88:89], v[126:127], v[88:89]
	s_nop 0
	v_add_f32_e32 v0, v88, v89
	ds_bpermute_b32 v78, v100, v0
	v_xor_b32_e32 v88, 32, v203
	v_cmp_lt_i32_e32 vcc, v88, v91
	s_waitcnt lgkmcnt(0)
	v_add_f32_e32 v0, v0, v78
	v_cndmask_b32_e32 v88, v203, v88, vcc
	v_lshlrev_b32_e32 v107, 2, v88
	ds_bpermute_b32 v78, v107, v0
	s_waitcnt lgkmcnt(0)
; __device__ __forceinline__ unsigned cvt_pk_bf16(float lo, float hi) { unsigned r; asm volatile("v_cvt_pk_bf16_f32 %0, %1, %2" : "=v"(r) : "v"(lo), "v"(hi)); return r; }
; __device__ __forceinline__ float bf_lo(unsigned w) { return __uint_as_float(w << 16); }
; __device__ __forceinline__ float bf_hi(unsigned w) { return __uint_as_float(w & 0xffff0000u); }
; __device__ __forceinline__ float sigmoidf_(float x) { return 1.0f / (1.0f + __expf(-x)); }
; __device__ void mix_sweep(const Params& P, LAS unsigned char* lds, int tok0, int pos0, int seqlen, int hd, int dir, bool state_only, bool final_pass,
;                           f32x4 (&Cacc)[9], float& m_state, float& aseg_sum, float lgam) {
;     ...
;                 const float mu = sum * (1.0f / 128.0f); float sq = 0.f;
; #pragma unroll
;                 for (int nt = 0; nt < 8; ++nt)
; #pragma unroll
;                     for (int e = 0; e < 4; ++e) { const float d = O[nt][e] - mu; sq += d * d; }
;                 sq += __shfl_xor(sq, 16); sq += __shfl_xor(sq, 32);
;                 const float rs = rsqrtf(sq * (1.0f / 128.0f) + 1e-5f);
; #pragma unroll
;                 for (int nt = 0; nt < 8; ++nt) { const u32x2 gv = gvv[nt]; const f32x4 gw = *(const f32x4*)(gnw + 16 * nt + 4 * fg);
;                     float gt[4] = {bf_lo(gv.x), bf_hi(gv.x), bf_lo(gv.y), bf_hi(gv.y)}; float y[4];
; #pragma unroll
;                     for (int e = 0; e < 4; ++e) { const float sg = sigmoidf_(gt[e]); const float gate = is_m ? sg : gt[e] * sg; y[e] = (O[nt][e] - mu) * rs * gw[e] * gate; }
;                     u32x2 v; v.x = cvt_pk_bf16(y[0], y[1]); v.y = cvt_pk_bf16(y[2], y[3]); *(u32x2*)(mrow + 16 * nt) = v; }
	v_add_f32_e32 v78, v0, v78
	v_fmamk_f32 v125, v78, 0xbc000000, v142
	v_fmamk_f32 v124, v78, 0xbc000000, v144
	v_mul_f32_e32 v88, v125, v125
	v_fmac_f32_e32 v88, v124, v124
	v_fmamk_f32 v126, v78, 0xbc000000, v140
	v_fmac_f32_e32 v88, v126, v126
	v_fmamk_f32 v114, v78, 0xbc000000, v114
	v_fmac_f32_e32 v88, v114, v114
	v_fmac_f32_e32 v145, 0xbc000000, v78
	v_fmac_f32_e32 v88, v145, v145
	v_fmac_f32_e32 v143, 0xbc000000, v78
	v_fmac_f32_e32 v88, v143, v143
	v_fmac_f32_e32 v141, 0xbc000000, v78
	v_fmac_f32_e32 v88, v141, v141
	v_fmac_f32_e32 v115, 0xbc000000, v78
	v_fmac_f32_e32 v88, v115, v115
	v_fmamk_f32 v112, v78, 0xbc000000, v112
	v_fmac_f32_e32 v88, v112, v112
	v_fmac_f32_e32 v113, 0xbc000000, v78
	v_fmac_f32_e32 v88, v113, v113
	v_fmamk_f32 v108, v78, 0xbc000000, v108
	v_fmac_f32_e32 v88, v108, v108
	v_fmac_f32_e32 v109, 0xbc000000, v78
	v_fmac_f32_e32 v88, v109, v109
	v_fmac_f32_e32 v90, 0xbc000000, v78
	v_fmac_f32_e32 v88, v90, v90
	v_fmac_f32_e32 v106, 0xbc000000, v78
	v_fmac_f32_e32 v88, v106, v106
	v_fmamk_f32 v92, v78, 0xbc000000, v102
	v_fmac_f32_e32 v88, v92, v92
	v_fmamk_f32 v91, v78, 0xbc000000, v96
	v_fmac_f32_e32 v88, v91, v91
	v_fmac_f32_e32 v103, 0xbc000000, v78
	v_fmac_f32_e32 v88, v103, v103
	v_fmac_f32_e32 v101, 0xbc000000, v78
	v_fmac_f32_e32 v88, v101, v101
	v_fmac_f32_e32 v97, 0xbc000000, v78
	v_fmac_f32_e32 v88, v97, v97
	v_fmac_f32_e32 v93, 0xbc000000, v78
	v_fmac_f32_e32 v88, v93, v93
	v_fmamk_f32 v86, v78, 0xbc000000, v86
	v_fmac_f32_e32 v88, v86, v86
	v_fmac_f32_e32 v87, 0xbc000000, v78
	v_mul_f32_e32 v0, 0x3c000000, v78
	v_fmac_f32_e32 v88, v87, v87
	v_fmamk_f32 v80, v78, 0xbc000000, v80
	v_fmac_f32_e32 v88, v80, v80
	v_fmac_f32_e32 v81, 0xbc000000, v78
	v_pk_add_f32 v[98:99], v[82:83], v[0:1] op_sel_hi:[1,0] neg_lo:[0,1] neg_hi:[0,1]
	v_fmac_f32_e32 v88, v81, v81
	v_pk_mul_f32 v[82:83], v[98:99], v[98:99]
	s_nop 0
	v_add_f32_e32 v78, v82, v88
	v_add_f32_e32 v78, v83, v78
	v_mov_b32_e32 v82, v122
	v_mov_b32_e32 v83, v120
	v_pk_add_f32 v[88:89], v[82:83], v[0:1] op_sel_hi:[1,0] neg_lo:[0,1] neg_hi:[0,1]
	v_mov_b32_e32 v120, v79
	v_pk_mul_f32 v[82:83], v[88:89], v[88:89]
	v_mov_b32_e32 v122, v127
	v_add_f32_e32 v78, v83, v78
	v_add_f32_e32 v96, v82, v78
	v_pk_add_f32 v[82:83], v[120:121], v[0:1] op_sel_hi:[1,0] neg_lo:[0,1] neg_hi:[0,1]
	s_nop 0
	v_pk_mul_f32 v[78:79], v[82:83], v[82:83]
	s_nop 0
	v_add_f32_e32 v79, v79, v96
	v_add_f32_e32 v96, v78, v79
	v_pk_add_f32 v[78:79], v[122:123], v[0:1] op_sel_hi:[1,0] neg_lo:[0,1] neg_hi:[0,1]
	v_and_b32_e32 v122, 0xffff0000, v149
	v_pk_mul_f32 v[120:121], v[78:79], v[78:79]
	s_nop 0
	v_add_f32_e32 v0, v121, v96
	v_add_f32_e32 v0, v120, v0
	ds_bpermute_b32 v96, v100, v0
	v_and_b32_e32 v120, 0xffff0000, v148
	v_lshlrev_b32_e32 v121, 16, v149
	s_waitcnt lgkmcnt(0)
	v_add_f32_e32 v0, v0, v96
	ds_bpermute_b32 v96, v107, v0
	s_waitcnt lgkmcnt(0)
	v_add_f32_e32 v0, v0, v96
	v_mov_b32_e32 v96, 0x3727c5ac
	v_fmamk_f32 v0, v0, 0x3c000000, v96
	v_mul_f32_e32 v96, 0x4b800000, v0
	v_cmp_gt_f32_e32 vcc, s30, v0
	s_nop 1
	v_cndmask_b32_e32 v0, v0, v96, vcc
	v_lshlrev_b32_e32 v96, 16, v148
	v_mul_f32_e32 v100, 0xbfb8aa3b, v96
	v_rsq_f32_e32 v0, v0
	v_exp_f32_e32 v100, v100
	v_mul_f32_e32 v102, 0x45800000, v0
	v_add_f32_e32 v100, 1.0, v100
	v_cndmask_b32_e32 v0, v0, v102, vcc
	v_mul_f32_e32 v114, v114, v0
	s_waitcnt vmcnt(0) lgkmcnt(0)
	v_mul_f32_e32 v114, v119, v114
	v_mul_f32_e32 v112, v112, v0
	v_mul_f32_e32 v107, 0xbfb8aa3b, v120
	v_exp_f32_e32 v107, v107
	v_rcp_f32_e32 v102, v100
	s_nop 0
	v_fma_f32 v127, -v100, v102, 1.0
	v_fma_f32 v100, v127, v102, v102
	v_mul_f32_e32 v96, v100, v96
	v_cndmask_b32_e64 v96, v96, v100, s[40:41]
	v_add_f32_e32 v100, 1.0, v107
	v_div_scale_f32 v102, s[16:17], v100, v100, 1.0
	v_rcp_f32_e32 v107, v102
	v_mul_f32_e32 v123, v124, v0
	v_mul_f32_e32 v116, v116, v123
	v_mul_f32_e32 v96, v96, v116
	v_fma_f32 v116, -v102, v107, 1.0
	v_fmac_f32_e32 v107, v116, v107
	v_div_scale_f32 v116, vcc, 1.0, v100, 1.0
	v_mul_f32_e32 v123, v116, v107
	v_fma_f32 v124, -v102, v123, v116
	v_fmac_f32_e32 v123, v124, v107
	v_fma_f32 v102, -v102, v123, v116
	v_div_fmas_f32 v102, v102, v107, v123
	v_mul_f32_e32 v107, 0xbfb8aa3b, v121
	v_exp_f32_e32 v107, v107
	v_div_fixup_f32 v100, v102, v100, 1.0
	v_mul_f32_e32 v102, v100, v120
	v_cndmask_b32_e64 v100, v102, v100, s[40:41]
	v_add_f32_e32 v102, 1.0, v107
	v_mul_f32_e32 v120, v125, v0
	v_mul_f32_e32 v117, v117, v120
	v_mul_f32_e32 v100, v100, v117
	v_mul_f32_e32 v116, 0xbfb8aa3b, v122
	v_exp_f32_e32 v116, v116
	v_rcp_f32_e32 v107, v102
	s_nop 0
	v_fma_f32 v123, -v102, v107, 1.0
	v_fma_f32 v102, v123, v107, v107
	v_mul_f32_e32 v107, v102, v121
	v_cndmask_b32_e64 v102, v107, v102, s[40:41]
	v_add_f32_e32 v107, 1.0, v116
	v_mul_f32_e32 v120, v126, v0
	v_mul_f32_e32 v118, v118, v120
	v_mul_f32_e32 v102, v102, v118
	v_rcp_f32_e32 v116, v107
	s_nop 0
	v_fma_f32 v121, -v107, v116, 1.0
	v_fma_f32 v107, v121, v116, v116
	v_mul_f32_e32 v116, v107, v122
	v_cndmask_b32_e64 v107, v116, v107, s[40:41]
	v_mul_f32_e32 v107, v107, v114
	v_cvt_pk_bf16_f32 v116, v96, v100
	v_cvt_pk_bf16_f32 v117, v102, v107
	global_store_dwordx2 v[72:73], v[116:117], off
	v_bfe_u32 v116, v161, 4, 2
	v_lshlrev_b32_e32 v116, 4, v116
	v_add_u32_e32 v116, 0x25a80, v116
	ds_read_b128 v[116:119], v116 offset:64
	v_lshlrev_b32_e32 v96, 16, v146
	v_mul_f32_e32 v100, 0xbfb8aa3b, v96
	v_exp_f32_e32 v100, v100
	v_and_b32_e32 v114, 0xffff0000, v146
	v_lshlrev_b32_e32 v120, 16, v147
	v_and_b32_e32 v121, 0xffff0000, v147
	v_add_f32_e32 v100, 1.0, v100
	v_mul_f32_e32 v108, v108, v0
	v_mul_f32_e32 v90, v90, v0
	v_mul_f32_e32 v106, v106, v0
	v_mul_f32_e32 v107, 0xbfb8aa3b, v114
	v_exp_f32_e32 v107, v107
	v_rcp_f32_e32 v102, v100
	s_nop 0
	v_fma_f32 v123, -v100, v102, 1.0
	v_fma_f32 v100, v123, v102, v102
	v_mul_f32_e32 v96, v100, v96
	v_cndmask_b32_e64 v96, v96, v100, s[40:41]
	v_add_f32_e32 v100, 1.0, v107
	v_mul_f32_e32 v122, v145, v0
	v_mul_f32_e32 v92, v92, v0
	v_mul_f32_e32 v91, v91, v0
	v_mul_f32_e32 v101, v101, v0
	v_mul_f32_e32 v97, v97, v0
	v_mul_f32_e32 v93, v93, v0
	v_mul_f32_e32 v86, v86, v0
	v_mul_f32_e32 v87, v87, v0
	v_mul_f32_e32 v80, v80, v0
	v_mul_f32_e32 v81, v81, v0
	v_mul_f32_e32 v89, v89, v0
	v_mul_f32_e32 v83, v83, v0
	v_mul_f32_e32 v82, v82, v0
	v_mul_f32_e32 v79, v79, v0
	s_waitcnt lgkmcnt(0)
; __device__ __forceinline__ unsigned cvt_pk_bf16(float lo, float hi) { unsigned r; asm volatile("v_cvt_pk_bf16_f32 %0, %1, %2" : "=v"(r) : "v"(lo), "v"(hi)); return r; }
; __device__ __forceinline__ float bf_lo(unsigned w) { return __uint_as_float(w << 16); }
; __device__ __forceinline__ float bf_hi(unsigned w) { return __uint_as_float(w & 0xffff0000u); }
; __device__ __forceinline__ float sigmoidf_(float x) { return 1.0f / (1.0f + __expf(-x)); }
; __device__ void mix_sweep(const Params& P, LAS unsigned char* lds, int tok0, int pos0, int seqlen, int hd, int dir, bool state_only, bool final_pass,
;                           f32x4 (&Cacc)[9], float& m_state, float& aseg_sum, float lgam) {
;     ...
;                 for (int nt = 0; nt < 8; ++nt) { const u32x2 gv = gvv[nt]; const f32x4 gw = *(const f32x4*)(gnw + 16 * nt + 4 * fg);
;                     float gt[4] = {bf_lo(gv.x), bf_hi(gv.x), bf_lo(gv.y), bf_hi(gv.y)}; float y[4];
; #pragma unroll
;                     for (int e = 0; e < 4; ++e) { const float sg = sigmoidf_(gt[e]); const float gate = is_m ? sg : gt[e] * sg; y[e] = (O[nt][e] - mu) * rs * gw[e] * gate; }
;                     u32x2 v; v.x = cvt_pk_bf16(y[0], y[1]); v.y = cvt_pk_bf16(y[2], y[3]); *(u32x2*)(mrow + 16 * nt) = v; }
	v_mul_f32_e32 v116, v116, v122
	v_mul_f32_e32 v96, v96, v116
	v_mul_f32_e32 v107, 0xbfb8aa3b, v120
	v_exp_f32_e32 v107, v107
	v_rcp_f32_e32 v102, v100
	s_nop 0
	v_fma_f32 v123, -v100, v102, 1.0
	v_fma_f32 v100, v123, v102, v102
	v_mul_f32_e32 v102, v100, v114
	v_cndmask_b32_e64 v100, v102, v100, s[40:41]
	v_add_f32_e32 v102, 1.0, v107
	v_mul_f32_e32 v116, v143, v0
	v_mul_f32_e32 v116, v117, v116
	v_mul_f32_e32 v100, v100, v116
	v_mul_f32_e32 v114, 0xbfb8aa3b, v121
	v_exp_f32_e32 v114, v114
	v_rcp_f32_e32 v107, v102
	s_nop 0
	v_fma_f32 v122, -v102, v107, 1.0
	v_fma_f32 v102, v122, v107, v107
	v_mul_f32_e32 v107, v102, v120
	v_cndmask_b32_e64 v102, v107, v102, s[40:41]
	v_add_f32_e32 v107, 1.0, v114
	v_mul_f32_e32 v117, v141, v0
	v_mul_f32_e32 v117, v118, v117
	v_mul_f32_e32 v102, v102, v117
	v_rcp_f32_e32 v114, v107
	s_nop 0
	v_fma_f32 v120, -v107, v114, 1.0
	v_fma_f32 v107, v120, v114, v114
	v_mul_f32_e32 v114, v107, v121
	v_cndmask_b32_e64 v107, v114, v107, s[40:41]
	v_mul_f32_e32 v114, v115, v0
	v_mul_f32_e32 v114, v119, v114
	v_mul_f32_e32 v107, v107, v114
	v_cvt_pk_bf16_f32 v114, v96, v100
	v_cvt_pk_bf16_f32 v115, v102, v107
	global_store_dwordx2 v[72:73], v[114:115], off offset:32
	v_bfe_u32 v114, v161, 4, 2
	v_lshlrev_b32_e32 v114, 4, v114
	v_add_u32_e32 v114, 0x25a80, v114
	ds_read_b128 v[114:117], v114 offset:128
	v_lshlrev_b32_e32 v96, 16, v110
	v_mul_f32_e32 v100, 0xbfb8aa3b, v96
	v_exp_f32_e32 v100, v100
	v_and_b32_e32 v110, 0xffff0000, v110
	v_lshlrev_b32_e32 v118, 16, v111
	v_and_b32_e32 v111, 0xffff0000, v111
	v_add_f32_e32 v100, 1.0, v100
	s_waitcnt lgkmcnt(0)
	v_mul_f32_e32 v112, v114, v112
	v_mul_f32_e32 v107, 0xbfb8aa3b, v110
	v_exp_f32_e32 v107, v107
	v_rcp_f32_e32 v102, v100
	s_nop 0
	v_fma_f32 v120, -v100, v102, 1.0
	v_fma_f32 v100, v120, v102, v102
	v_mul_f32_e32 v96, v100, v96
	v_cndmask_b32_e64 v96, v96, v100, s[40:41]
	v_add_f32_e32 v100, 1.0, v107
	v_mul_f32_e32 v96, v96, v112
	v_mul_f32_e32 v108, v116, v108
	v_mul_f32_e32 v107, 0xbfb8aa3b, v118
	v_exp_f32_e32 v107, v107
	v_rcp_f32_e32 v102, v100
	s_nop 0
	v_fma_f32 v114, -v100, v102, 1.0
	v_fma_f32 v100, v114, v102, v102
	v_mul_f32_e32 v102, v100, v110
	v_cndmask_b32_e64 v100, v102, v100, s[40:41]
	v_add_f32_e32 v102, 1.0, v107
	v_mul_f32_e32 v112, v113, v0
	v_mul_f32_e32 v112, v115, v112
	v_mul_f32_e32 v100, v100, v112
	v_mul_f32_e32 v110, 0xbfb8aa3b, v111
	v_exp_f32_e32 v110, v110
	v_rcp_f32_e32 v107, v102
	s_nop 0
	v_fma_f32 v114, -v102, v107, 1.0
	v_fma_f32 v102, v114, v107, v107
	v_mul_f32_e32 v107, v102, v118
	v_cndmask_b32_e64 v102, v107, v102, s[40:41]
	v_add_f32_e32 v107, 1.0, v110
	v_mul_f32_e32 v102, v102, v108
	v_rcp_f32_e32 v113, v107
	s_nop 0
	v_fma_f32 v114, -v107, v113, 1.0
	v_fma_f32 v107, v114, v113, v113
	v_mul_f32_e32 v108, v107, v111
	v_cndmask_b32_e64 v107, v108, v107, s[40:41]
	v_mul_f32_e32 v108, v109, v0
	v_mul_f32_e32 v108, v117, v108
	v_mul_f32_e32 v107, v107, v108
	v_cvt_pk_bf16_f32 v108, v96, v100
	v_cvt_pk_bf16_f32 v109, v102, v107
	global_store_dwordx2 v[72:73], v[108:109], off offset:64
	v_bfe_u32 v108, v161, 4, 2
	v_lshlrev_b32_e32 v108, 4, v108
	v_add_u32_e32 v108, 0x25a80, v108
	ds_read_b128 v[108:111], v108 offset:192
	v_lshlrev_b32_e32 v96, 16, v104
	v_mul_f32_e32 v100, 0xbfb8aa3b, v96
	v_exp_f32_e32 v100, v100
	v_and_b32_e32 v104, 0xffff0000, v104
	v_lshlrev_b32_e32 v112, 16, v105
	v_and_b32_e32 v105, 0xffff0000, v105
	v_add_f32_e32 v100, 1.0, v100
	s_waitcnt lgkmcnt(0)
	v_mul_f32_e32 v90, v108, v90
	v_mul_f32_e32 v107, 0xbfb8aa3b, v104
	v_exp_f32_e32 v107, v107
	v_rcp_f32_e32 v102, v100
	s_nop 0
	v_fma_f32 v114, -v100, v102, 1.0
	v_fma_f32 v100, v114, v102, v102
	v_mul_f32_e32 v96, v100, v96
	v_cndmask_b32_e64 v96, v96, v100, s[40:41]
	v_add_f32_e32 v100, 1.0, v107
	v_mul_f32_e32 v90, v96, v90
	v_mul_f32_e32 v106, v109, v106
	v_mul_f32_e32 v92, v110, v92
	v_mul_f32_e32 v102, 0xbfb8aa3b, v112
	v_exp_f32_e32 v102, v102
	v_rcp_f32_e32 v108, v100
	s_nop 0
	v_fma_f32 v113, -v100, v108, 1.0
	v_fma_f32 v96, v113, v108, v108
	v_mul_f32_e32 v100, v96, v104
	v_cndmask_b32_e64 v96, v100, v96, s[40:41]
	v_add_f32_e32 v100, 1.0, v102
	v_mul_f32_e32 v96, v96, v106
	v_mul_f32_e32 v91, v111, v91
	v_cvt_pk_bf16_f32 v90, v90, v96
	v_mul_f32_e32 v104, 0xbfb8aa3b, v105
	v_exp_f32_e32 v104, v104
	v_rcp_f32_e32 v102, v100
	s_nop 0
	v_fma_f32 v107, -v100, v102, 1.0
	v_fma_f32 v100, v107, v102, v102
	v_mul_f32_e32 v102, v100, v112
	v_cndmask_b32_e64 v100, v102, v100, s[40:41]
	v_add_f32_e32 v102, 1.0, v104
	v_mul_f32_e32 v92, v100, v92
	v_rcp_f32_e32 v107, v102
	s_nop 0
	v_fma_f32 v108, -v102, v107, 1.0
	v_fma_f32 v100, v108, v107, v107
	v_mul_f32_e32 v102, v100, v105
	v_cndmask_b32_e64 v100, v102, v100, s[40:41]
	v_mul_f32_e32 v91, v100, v91
	v_cvt_pk_bf16_f32 v91, v92, v91
	global_store_dwordx2 v[72:73], v[90:91], off offset:96
	v_bfe_u32 v104, v161, 4, 2
	v_lshlrev_b32_e32 v104, 4, v104
	v_add_u32_e32 v104, 0x25a80, v104
	ds_read_b128 v[104:107], v104 offset:256
	v_lshlrev_b32_e32 v90, 16, v94
	v_mul_f32_e32 v91, 0xbfb8aa3b, v90
	v_exp_f32_e32 v91, v91
	v_and_b32_e32 v94, 0xffff0000, v94
	v_lshlrev_b32_e32 v100, 16, v95
	v_and_b32_e32 v95, 0xffff0000, v95
	v_add_f32_e32 v91, 1.0, v91
	s_waitcnt lgkmcnt(0)
; __device__ __forceinline__ unsigned cvt_pk_bf16(float lo, float hi) { unsigned r; asm volatile("v_cvt_pk_bf16_f32 %0, %1, %2" : "=v"(r) : "v"(lo), "v"(hi)); return r; }
; __device__ __forceinline__ float bf_lo(unsigned w) { return __uint_as_float(w << 16); }
; __device__ __forceinline__ float bf_hi(unsigned w) { return __uint_as_float(w & 0xffff0000u); }
; __device__ __forceinline__ float sigmoidf_(float x) { return 1.0f / (1.0f + __expf(-x)); }
; __device__ void mix_sweep(const Params& P, LAS unsigned char* lds, int tok0, int pos0, int seqlen, int hd, int dir, bool state_only, bool final_pass,
;                           f32x4 (&Cacc)[9], float& m_state, float& aseg_sum, float lgam) {
;     ...
; #pragma unroll
;                 for (int nt = 0; nt < 8; ++nt) { const u32x2 gv = gvv[nt]; const f32x4 gw = *(const f32x4*)(gnw + 16 * nt + 4 * fg);
;                     float gt[4] = {bf_lo(gv.x), bf_hi(gv.x), bf_lo(gv.y), bf_hi(gv.y)}; float y[4];
; #pragma unroll
;                     for (int e = 0; e < 4; ++e) { const float sg = sigmoidf_(gt[e]); const float gate = is_m ? sg : gt[e] * sg; y[e] = (O[nt][e] - mu) * rs * gw[e] * gate; }
;                     u32x2 v; v.x = cvt_pk_bf16(y[0], y[1]); v.y = cvt_pk_bf16(y[2], y[3]); *(u32x2*)(mrow + 16 * nt) = v; }
	v_mul_f32_e32 v101, v105, v101
	v_mul_f32_e32 v96, 0xbfb8aa3b, v94
	v_exp_f32_e32 v96, v96
	v_rcp_f32_e32 v92, v91
	s_nop 0
	v_fma_f32 v108, -v91, v92, 1.0
	v_fma_f32 v91, v108, v92, v92
	v_mul_f32_e32 v90, v91, v90
	v_cndmask_b32_e64 v90, v90, v91, s[40:41]
	v_add_f32_e32 v91, 1.0, v96
	v_div_scale_f32 v92, s[16:17], v91, v91, 1.0
	v_rcp_f32_e32 v96, v92
	v_mul_f32_e32 v102, v103, v0
	v_mul_f32_e32 v102, v104, v102
	v_mul_f32_e32 v90, v90, v102
	v_fma_f32 v102, -v92, v96, 1.0
	v_fmac_f32_e32 v96, v102, v96
	v_div_scale_f32 v102, vcc, 1.0, v91, 1.0
	v_mul_f32_e32 v103, v102, v96
	v_fma_f32 v104, -v92, v103, v102
	v_fmac_f32_e32 v103, v104, v96
	v_fma_f32 v92, -v92, v103, v102
	v_div_fmas_f32 v92, v92, v96, v103
	v_mul_f32_e32 v96, 0xbfb8aa3b, v100
	v_exp_f32_e32 v96, v96
	v_div_fixup_f32 v91, v92, v91, 1.0
	v_mul_f32_e32 v92, v91, v94
	v_cndmask_b32_e64 v91, v92, v91, s[40:41]
	v_add_f32_e32 v92, 1.0, v96
	v_mul_f32_e32 v91, v91, v101
	v_mul_f32_e32 v97, v106, v97
	v_mul_f32_e32 v93, v107, v93
	v_mul_f32_e32 v96, 0xbfb8aa3b, v95
	v_exp_f32_e32 v96, v96
	v_rcp_f32_e32 v94, v92
	s_nop 0
	v_fma_f32 v102, -v92, v94, 1.0
	v_fma_f32 v92, v102, v94, v94
	v_mul_f32_e32 v94, v92, v100
	v_cndmask_b32_e64 v92, v94, v92, s[40:41]
	v_add_f32_e32 v94, 1.0, v96
	v_mul_f32_e32 v92, v92, v97
	v_cvt_pk_bf16_f32 v90, v90, v91
	v_rcp_f32_e32 v96, v94
	s_nop 0
	v_fma_f32 v101, -v94, v96, 1.0
	v_fma_f32 v94, v101, v96, v96
	v_mul_f32_e32 v95, v94, v95
	v_cndmask_b32_e64 v94, v95, v94, s[40:41]
	v_mul_f32_e32 v93, v94, v93
	v_cvt_pk_bf16_f32 v91, v92, v93
	global_store_dwordx2 v[72:73], v[90:91], off offset:128
	v_bfe_u32 v90, v161, 4, 2
	v_lshlrev_b32_e32 v90, 4, v90
	v_add_u32_e32 v90, 0x25a80, v90
	ds_read_b128 v[90:93], v90 offset:320
	v_lshlrev_b32_e32 v94, 16, v84
	v_mul_f32_e32 v95, 0xbfb8aa3b, v94
	v_exp_f32_e32 v95, v95
	v_and_b32_e32 v84, 0xffff0000, v84
	v_lshlrev_b32_e32 v100, 16, v85
	v_and_b32_e32 v85, 0xffff0000, v85
	v_add_f32_e32 v95, 1.0, v95
	s_waitcnt lgkmcnt(0)
	v_mul_f32_e32 v86, v90, v86
	v_mul_f32_e32 v97, 0xbfb8aa3b, v84
	v_exp_f32_e32 v97, v97
	v_rcp_f32_e32 v96, v95
	s_nop 0
	v_fma_f32 v102, -v95, v96, 1.0
	v_fma_f32 v95, v102, v96, v96
	v_mul_f32_e32 v94, v95, v94
	v_cndmask_b32_e64 v94, v94, v95, s[40:41]
	v_add_f32_e32 v95, 1.0, v97
	v_mul_f32_e32 v86, v94, v86
	v_mul_f32_e32 v87, v91, v87
	v_mul_f32_e32 v80, v92, v80
	v_mul_f32_e32 v94, 0xbfb8aa3b, v100
	v_exp_f32_e32 v94, v94
	v_rcp_f32_e32 v101, v95
	s_nop 0
	v_fma_f32 v97, -v95, v101, 1.0
	v_fma_f32 v90, v97, v101, v101
	v_mul_f32_e32 v84, v90, v84
	v_cndmask_b32_e64 v84, v84, v90, s[40:41]
	v_add_f32_e32 v90, 1.0, v94
	v_mul_f32_e32 v84, v84, v87
	v_mul_f32_e32 v81, v93, v81
	v_mul_f32_e32 v91, 0xbfb8aa3b, v85
	v_exp_f32_e32 v91, v91
	v_rcp_f32_e32 v96, v90
	s_nop 0
	v_fma_f32 v95, -v90, v96, 1.0
	v_fma_f32 v87, v95, v96, v96
	v_mul_f32_e32 v90, v87, v100
	v_cndmask_b32_e64 v87, v90, v87, s[40:41]
	v_add_f32_e32 v90, 1.0, v91
	v_mul_f32_e32 v87, v87, v80
	v_rcp_f32_e32 v92, v90
	s_nop 0
	v_fma_f32 v95, -v90, v92, 1.0
	v_fma_f32 v80, v95, v92, v92
	v_mul_f32_e32 v85, v80, v85
	v_cndmask_b32_e64 v80, v85, v80, s[40:41]
	v_mul_f32_e32 v81, v80, v81
	v_cvt_pk_bf16_f32 v80, v86, v84
	v_cvt_pk_bf16_f32 v81, v87, v81
	global_store_dwordx2 v[72:73], v[80:81], off offset:160
	v_bfe_u32 v84, v161, 4, 2
	v_lshlrev_b32_e32 v84, 4, v84
	v_add_u32_e32 v84, 0x25a80, v84
	ds_read_b128 v[84:87], v84 offset:384
	v_lshlrev_b32_e32 v80, 16, v76
	v_mul_f32_e32 v81, 0xbfb8aa3b, v80
	v_exp_f32_e32 v81, v81
	v_and_b32_e32 v76, 0xffff0000, v76
	v_lshlrev_b32_e32 v92, 16, v77
	v_and_b32_e32 v77, 0xffff0000, v77
	v_add_f32_e32 v81, 1.0, v81
	s_waitcnt lgkmcnt(0)
	v_mul_f32_e32 v86, v86, v89
	v_mul_f32_e32 v91, 0xbfb8aa3b, v76
	v_exp_f32_e32 v91, v91
	v_rcp_f32_e32 v90, v81
	s_nop 0
	v_fma_f32 v94, -v81, v90, 1.0
	v_fma_f32 v81, v94, v90, v90
	v_mul_f32_e32 v80, v81, v80
	v_cndmask_b32_e64 v80, v80, v81, s[40:41]
	v_add_f32_e32 v81, 1.0, v91
	v_mul_f32_e32 v93, v98, v0
	v_mul_f32_e32 v84, v84, v93
	v_mul_f32_e32 v80, v80, v84
	v_mul_f32_e32 v90, 0xbfb8aa3b, v92
	v_exp_f32_e32 v90, v90
	v_rcp_f32_e32 v94, v81
	s_nop 0
	v_fma_f32 v91, -v81, v94, 1.0
	v_fma_f32 v81, v91, v94, v94
	v_mul_f32_e32 v76, v81, v76
	v_cndmask_b32_e64 v76, v76, v81, s[40:41]
	v_add_f32_e32 v81, 1.0, v90
	v_mul_f32_e32 v91, v99, v0
	v_mul_f32_e32 v85, v85, v91
	v_mul_f32_e32 v76, v76, v85
	v_mul_f32_e32 v85, 0xbfb8aa3b, v77
	v_exp_f32_e32 v85, v85
	v_rcp_f32_e32 v84, v81
	s_nop 0
	v_fma_f32 v93, -v81, v84, 1.0
	v_fma_f32 v81, v93, v84, v84
	v_mul_f32_e32 v84, v81, v92
	v_cndmask_b32_e64 v81, v84, v81, s[40:41]
	v_add_f32_e32 v84, 1.0, v85
	v_mul_f32_e32 v81, v81, v86
	v_cvt_pk_bf16_f32 v76, v80, v76
	v_rcp_f32_e32 v85, v84
	s_nop 0
	v_fma_f32 v89, -v84, v85, 1.0
	v_fma_f32 v84, v89, v85, v85
	v_mul_f32_e32 v77, v84, v77
	v_cndmask_b32_e64 v77, v77, v84, s[40:41]
	v_mul_f32_e32 v84, v88, v0
	v_mul_f32_e32 v84, v87, v84
	v_mul_f32_e32 v77, v77, v84
	v_cvt_pk_bf16_f32 v77, v81, v77
	global_store_dwordx2 v[72:73], v[76:77], off offset:192
	v_bfe_u32 v84, v161, 4, 2
	v_lshlrev_b32_e32 v84, 4, v84
	v_add_u32_e32 v84, 0x25a80, v84
	ds_read_b128 v[84:87], v84 offset:448
	v_lshlrev_b32_e32 v76, 16, v74
	v_mul_f32_e32 v77, 0xbfb8aa3b, v76
	v_exp_f32_e32 v77, v77
	v_and_b32_e32 v74, 0xffff0000, v74
	v_lshlrev_b32_e32 v88, 16, v75
	v_and_b32_e32 v75, 0xffff0000, v75
	v_add_f32_e32 v77, 1.0, v77
	v_mul_f32_e32 v0, v78, v0
	v_mul_f32_e32 v81, 0xbfb8aa3b, v74
	v_exp_f32_e32 v81, v81
	v_rcp_f32_e32 v80, v77
	s_nop 0
	v_fma_f32 v90, -v77, v80, 1.0
	v_fma_f32 v77, v90, v80, v80
	v_mul_f32_e32 v76, v77, v76
	v_cndmask_b32_e64 v76, v76, v77, s[40:41]
	v_add_f32_e32 v77, 1.0, v81
	s_waitcnt lgkmcnt(0)
	v_mul_f32_e32 v83, v84, v83
	v_mul_f32_e32 v76, v76, v83
	v_mul_f32_e32 v81, 0xbfb8aa3b, v88
	v_exp_f32_e32 v81, v81
	v_rcp_f32_e32 v80, v77
	s_nop 0
	v_fma_f32 v89, -v77, v80, 1.0
	v_fma_f32 v77, v89, v80, v80
	v_mul_f32_e32 v74, v77, v74
	v_cndmask_b32_e64 v74, v74, v77, s[40:41]
	v_add_f32_e32 v77, 1.0, v81
	v_mul_f32_e32 v82, v85, v82
	v_mul_f32_e32 v74, v74, v82
	v_mul_f32_e32 v79, v86, v79
	v_mul_f32_e32 v81, 0xbfb8aa3b, v75
	v_exp_f32_e32 v81, v81
	v_rcp_f32_e32 v80, v77
	s_nop 0
	v_fma_f32 v83, -v77, v80, 1.0
	v_fma_f32 v77, v83, v80, v80
	v_mul_f32_e32 v80, v77, v88
	v_cndmask_b32_e64 v77, v80, v77, s[40:41]
	v_add_f32_e32 v80, 1.0, v81
	v_mul_f32_e32 v77, v77, v79
	v_mul_f32_e32 v0, v87, v0
	v_cvt_pk_bf16_f32 v74, v76, v74
	v_rcp_f32_e32 v83, v80
	s_nop 0
	v_fma_f32 v84, -v80, v83, 1.0
	v_fma_f32 v79, v84, v83, v83
	v_mul_f32_e32 v75, v79, v75
	v_cndmask_b32_e64 v75, v75, v79, s[40:41]
	v_mul_f32_e32 v0, v75, v0
	v_cvt_pk_bf16_f32 v75, v77, v0
	global_store_dwordx2 v[72:73], v[74:75], off offset:224
	s_branch .LBB0_97

; __device__ __forceinline__ unsigned cvt_pk_bf16(float lo, float hi) { unsigned r; asm volatile("v_cvt_pk_bf16_f32 %0, %1, %2" : "=v"(r) : "v"(lo), "v"(hi)); return r; }
;     __device__ __forceinline__ void operator()(AccT& acc, const Unit& u, int wr, int wc, int fr, int fq) const {
;     ...
;             for (int m = 0; m < 4; ++m) { const int row = row0 + ai * 128 + m * 16; bf16_t* rowp = O + (size_t)row * NPROJ + col0;
;                 f32x4 cs0 = (f32x4){1.f, 0.f, 1.f, 0.f}, cs1 = cs0;
;                 if (rot) { const int pos = row < HALF_TOK ? (row & 8191) : ((row - HALF_TOK) & 2047); const f32x2* rp = rope + (size_t)pos * 64 + i0; cs0 = *(const f32x4*)rp; cs1 = *(const f32x4*)(rp + 2); }
; #pragma unroll
;                 for (int bj = 0; bj < 2; ++bj) { f32x4 v0 = acc[ai][bj][m][0], v1 = acc[ai][bj][m][1];
;                     if (rot) { const f32x4 a = v0, b = v1;
;                         v0[0] = a[0] * cs0[0] - a[1] * cs0[1]; v0[1] = a[1] * cs0[0] + a[0] * cs0[1]; v0[2] = a[2] * cs0[2] - a[3] * cs0[3]; v0[3] = a[3] * cs0[2] + a[2] * cs0[3];
;                         v1[0] = b[0] * cs1[0] - b[1] * cs1[1]; v1[1] = b[1] * cs1[0] + b[0] * cs1[1]; v1[2] = b[2] * cs1[2] - b[3] * cs1[3]; v1[3] = b[3] * cs1[2] + b[2] * cs1[3]; }
;                     u32x4 w; w.x = cvt_pk_bf16(v0[0], v0[1]); w.y = cvt_pk_bf16(v0[2], v0[3]); w.z = cvt_pk_bf16(v1[0], v1[1]); w.w = cvt_pk_bf16(v1[2], v1[3]);
;                     *(u32x4*)(rowp + bj * 128) = w; }
.Lg1_rot:
	s_movk_i32 s4, 0x4000
	v_lshl_add_u32 v138, v0, 2, s79
	v_cmp_gt_i32_e32 vcc, s4, v140
	v_mov_b32_e32 v0, 0x7ff
	v_mov_b32_e32 v160, 0x1fff
	v_ashrrev_i32_e32 v139, 31, v138
	v_cndmask_b32_e32 v0, v0, v160, vcc
	v_and_b32_e32 v0, v0, v140
	v_lshlrev_b32_e32 v0, 9, v0
	v_lshl_add_u64 v[160:161], s[46:47], 0, v[0:1]
	v_lshl_add_u64 v[138:139], v[138:139], 3, v[160:161]
	s_mov_b32 s42, 0x2000
	s_mov_b32 s43, 0
	global_load_dwordx4 v[134:137], v[138:139], off
	global_load_dwordx4 v[130:133], v[138:139], off offset:16
	s_nop 0
	v_lshl_add_u64 v[138:139], v[138:139], 0, s[42:43]
	global_load_dwordx4 v[182:185], v[138:139], off
	global_load_dwordx4 v[192:195], v[138:139], off offset:16
	s_nop 0
	v_lshl_add_u64 v[138:139], v[138:139], 0, s[42:43]
	global_load_dwordx4 v[196:199], v[138:139], off
	global_load_dwordx4 v[204:207], v[138:139], off offset:16
	s_nop 0
	v_lshl_add_u64 v[138:139], v[138:139], 0, s[42:43]
	global_load_dwordx4 v[222:225], v[138:139], off
	global_load_dwordx4 v[226:229], v[138:139], off offset:16
	s_nop 0
	v_lshl_add_u64 v[138:139], v[138:139], 0, s[42:43]
	v_lshl_add_u64 v[138:139], v[138:139], 0, s[42:43]
	v_lshl_add_u64 v[138:139], v[138:139], 0, s[42:43]
	v_lshl_add_u64 v[138:139], v[138:139], 0, s[42:43]
	v_lshl_add_u64 v[138:139], v[138:139], 0, s[42:43]
	s_waitcnt vmcnt(6)
	v_mul_f32_e32 v0, v127, v135
	v_mul_f32_e32 v172, v111, v131
	v_mul_f32_e32 v160, v126, v135
	v_mul_f32_e32 v173, v110, v131
	v_mul_f32_e32 v161, v126, v134
	v_mul_f32_e32 v174, v110, v130
	v_mul_f32_e32 v170, v137, v129
	v_mul_f32_e32 v175, v133, v113
	v_mul_f32_e32 v171, v128, v137
	v_mul_f32_e32 v176, v112, v133
	v_fma_f32 v127, v127, v134, v160
	v_fma_f32 v111, v111, v130, v173
	v_sub_f32_e32 v126, v161, v0
	v_sub_f32_e32 v110, v174, v172
	v_fma_f32 v128, v136, v128, -v170
	v_fma_f32 v112, v132, v112, -v175
	v_fma_f32 v129, v129, v136, v171
	v_fma_f32 v113, v113, v132, v176
	v_mul_f32_e32 v0, v95, v135
	v_mul_f32_e32 v172, v79, v131
	v_mul_f32_e32 v160, v94, v135
	v_mul_f32_e32 v173, v78, v131
	v_mul_f32_e32 v161, v94, v134
	v_mul_f32_e32 v174, v78, v130
	v_mul_f32_e32 v170, v137, v97
	v_mul_f32_e32 v175, v133, v81
	v_mul_f32_e32 v171, v96, v137
	v_mul_f32_e32 v176, v80, v133
	v_fma_f32 v95, v95, v134, v160
	v_fma_f32 v79, v79, v130, v173
	v_sub_f32_e32 v94, v161, v0
	v_sub_f32_e32 v78, v174, v172
	v_fma_f32 v96, v136, v96, -v170
	v_fma_f32 v80, v132, v80, -v175
	v_fma_f32 v97, v97, v136, v171
	v_fma_f32 v81, v81, v132, v176
	global_load_dwordx4 v[134:137], v[138:139], off
	global_load_dwordx4 v[130:133], v[138:139], off offset:16
	s_nop 0
	v_lshl_add_u64 v[138:139], v[138:139], 0, s[42:43]
	s_waitcnt vmcnt(6)
	v_mul_f32_e32 v0, v123, v183
	v_mul_f32_e32 v172, v107, v193
	v_mul_f32_e32 v160, v122, v183
	v_mul_f32_e32 v173, v106, v193
	v_mul_f32_e32 v161, v122, v182
	v_mul_f32_e32 v174, v106, v192
	v_mul_f32_e32 v170, v185, v125
	v_mul_f32_e32 v175, v195, v109
	v_mul_f32_e32 v171, v124, v185
	v_mul_f32_e32 v176, v108, v195
	v_fma_f32 v123, v123, v182, v160
	v_fma_f32 v107, v107, v192, v173
	v_sub_f32_e32 v122, v161, v0
	v_sub_f32_e32 v106, v174, v172
	v_fma_f32 v124, v184, v124, -v170
	v_fma_f32 v108, v194, v108, -v175
	v_fma_f32 v125, v125, v184, v171
	v_fma_f32 v109, v109, v194, v176
	v_mul_f32_e32 v0, v91, v183
	v_mul_f32_e32 v172, v75, v193
	v_mul_f32_e32 v160, v90, v183
	v_mul_f32_e32 v173, v74, v193
	v_mul_f32_e32 v161, v90, v182
	v_mul_f32_e32 v174, v74, v192
	v_mul_f32_e32 v170, v185, v93
	v_mul_f32_e32 v175, v195, v77
	v_mul_f32_e32 v171, v92, v185
	v_mul_f32_e32 v176, v76, v195
	v_fma_f32 v91, v91, v182, v160
	v_fma_f32 v75, v75, v192, v173
	v_sub_f32_e32 v90, v161, v0
	v_sub_f32_e32 v74, v174, v172
	v_fma_f32 v92, v184, v92, -v170
	v_fma_f32 v76, v194, v76, -v175
	v_fma_f32 v93, v93, v184, v171
	v_fma_f32 v77, v77, v194, v176
	global_load_dwordx4 v[182:185], v[138:139], off
	global_load_dwordx4 v[192:195], v[138:139], off offset:16
	s_nop 0
	v_lshl_add_u64 v[138:139], v[138:139], 0, s[42:43]
	s_waitcnt vmcnt(6)
	v_mul_f32_e32 v0, v119, v197
	v_mul_f32_e32 v172, v103, v205
	v_mul_f32_e32 v160, v118, v197
	v_mul_f32_e32 v173, v102, v205
	v_mul_f32_e32 v161, v118, v196
	v_mul_f32_e32 v174, v102, v204
	v_mul_f32_e32 v170, v199, v121
	v_mul_f32_e32 v175, v207, v105
	v_mul_f32_e32 v171, v120, v199
	v_mul_f32_e32 v176, v104, v207
	v_fma_f32 v119, v119, v196, v160
	v_fma_f32 v103, v103, v204, v173
	v_sub_f32_e32 v118, v161, v0
	v_sub_f32_e32 v102, v174, v172
	v_fma_f32 v120, v198, v120, -v170
	v_fma_f32 v104, v206, v104, -v175
	v_fma_f32 v121, v121, v198, v171
	v_fma_f32 v105, v105, v206, v176
	v_mul_f32_e32 v0, v87, v197
	v_mul_f32_e32 v172, v71, v205
	v_mul_f32_e32 v160, v86, v197
	v_mul_f32_e32 v173, v70, v205
	v_mul_f32_e32 v161, v86, v196
	v_mul_f32_e32 v174, v70, v204
	v_mul_f32_e32 v170, v199, v89
	v_mul_f32_e32 v175, v207, v73
	v_mul_f32_e32 v171, v88, v199
	v_mul_f32_e32 v176, v72, v207
	v_fma_f32 v87, v87, v196, v160
	v_fma_f32 v71, v71, v204, v173
	v_sub_f32_e32 v86, v161, v0
	v_sub_f32_e32 v70, v174, v172
	v_fma_f32 v88, v198, v88, -v170
	v_fma_f32 v72, v206, v72, -v175
	v_fma_f32 v89, v89, v198, v171
	v_fma_f32 v73, v73, v206, v176
	global_load_dwordx4 v[196:199], v[138:139], off
	global_load_dwordx4 v[204:207], v[138:139], off offset:16
	s_nop 0
	v_lshl_add_u64 v[138:139], v[138:139], 0, s[42:43]
	s_waitcnt vmcnt(6)
; __device__ __forceinline__ unsigned cvt_pk_bf16(float lo, float hi) { unsigned r; asm volatile("v_cvt_pk_bf16_f32 %0, %1, %2" : "=v"(r) : "v"(lo), "v"(hi)); return r; }
;     __device__ __forceinline__ void operator()(AccT& acc, const Unit& u, int wr, int wc, int fr, int fq) const {
;     ...
;                 for (int bj = 0; bj < 2; ++bj) { f32x4 v0 = acc[ai][bj][m][0], v1 = acc[ai][bj][m][1];
;                     if (rot) { const f32x4 a = v0, b = v1;
;                         v0[0] = a[0] * cs0[0] - a[1] * cs0[1]; v0[1] = a[1] * cs0[0] + a[0] * cs0[1]; v0[2] = a[2] * cs0[2] - a[3] * cs0[3]; v0[3] = a[3] * cs0[2] + a[2] * cs0[3];
;                         v1[0] = b[0] * cs1[0] - b[1] * cs1[1]; v1[1] = b[1] * cs1[0] + b[0] * cs1[1]; v1[2] = b[2] * cs1[2] - b[3] * cs1[3]; v1[3] = b[3] * cs1[2] + b[2] * cs1[3]; }
;                     u32x4 w; w.x = cvt_pk_bf16(v0[0], v0[1]); w.y = cvt_pk_bf16(v0[2], v0[3]); w.z = cvt_pk_bf16(v1[0], v1[1]); w.w = cvt_pk_bf16(v1[2], v1[3]);
;                     *(u32x4*)(rowp + bj * 128) = w; }
	v_mul_f32_e32 v0, v115, v223
	v_mul_f32_e32 v172, v99, v227
	v_mul_f32_e32 v160, v114, v223
	v_mul_f32_e32 v173, v98, v227
	v_mul_f32_e32 v161, v114, v222
	v_mul_f32_e32 v174, v98, v226
	v_mul_f32_e32 v170, v225, v117
	v_mul_f32_e32 v175, v229, v101
	v_mul_f32_e32 v171, v116, v225
	v_mul_f32_e32 v176, v100, v229
	v_fma_f32 v115, v115, v222, v160
	v_fma_f32 v99, v99, v226, v173
	v_sub_f32_e32 v114, v161, v0
	v_sub_f32_e32 v98, v174, v172
	v_fma_f32 v116, v224, v116, -v170
	v_fma_f32 v100, v228, v100, -v175
	v_fma_f32 v117, v117, v224, v171
	v_fma_f32 v101, v101, v228, v176
	v_mul_f32_e32 v0, v83, v223
	v_mul_f32_e32 v172, v67, v227
	v_mul_f32_e32 v160, v82, v223
	v_mul_f32_e32 v173, v66, v227
	v_mul_f32_e32 v161, v82, v222
	v_mul_f32_e32 v174, v66, v226
	v_mul_f32_e32 v170, v225, v85
	v_mul_f32_e32 v175, v229, v69
	v_mul_f32_e32 v171, v84, v225
	v_mul_f32_e32 v176, v68, v229
	v_fma_f32 v83, v83, v222, v160
	v_fma_f32 v67, v67, v226, v173
	v_sub_f32_e32 v82, v161, v0
	v_sub_f32_e32 v66, v174, v172
	v_fma_f32 v84, v224, v84, -v170
	v_fma_f32 v68, v228, v68, -v175
	v_fma_f32 v85, v85, v224, v171
	v_fma_f32 v69, v69, v228, v176
	global_load_dwordx4 v[222:225], v[138:139], off
	global_load_dwordx4 v[226:229], v[138:139], off offset:16
	s_waitcnt vmcnt(6)
	v_mul_f32_e32 v0, v63, v135
	v_mul_f32_e32 v172, v47, v131
	v_mul_f32_e32 v160, v62, v135
	v_mul_f32_e32 v173, v46, v131
	v_mul_f32_e32 v161, v62, v134
	v_mul_f32_e32 v174, v46, v130
	v_mul_f32_e32 v170, v137, v65
	v_mul_f32_e32 v175, v133, v49
	v_mul_f32_e32 v171, v64, v137
	v_mul_f32_e32 v176, v48, v133
	v_fma_f32 v63, v63, v134, v160
	v_fma_f32 v47, v47, v130, v173
	v_sub_f32_e32 v62, v161, v0
	v_sub_f32_e32 v46, v174, v172
	v_fma_f32 v64, v136, v64, -v170
	v_fma_f32 v48, v132, v48, -v175
	v_fma_f32 v65, v65, v136, v171
	v_fma_f32 v49, v49, v132, v176
	v_mul_f32_e32 v0, v31, v135
	v_mul_f32_e32 v172, v15, v131
	v_mul_f32_e32 v160, v30, v135
	v_mul_f32_e32 v173, v14, v131
	v_mul_f32_e32 v161, v30, v134
	v_mul_f32_e32 v174, v14, v130
	v_mul_f32_e32 v170, v137, v33
	v_mul_f32_e32 v175, v133, v17
	v_mul_f32_e32 v171, v32, v137
	v_mul_f32_e32 v176, v16, v133
	v_fma_f32 v31, v31, v134, v160
	v_fma_f32 v15, v15, v130, v173
	v_sub_f32_e32 v30, v161, v0
	v_sub_f32_e32 v14, v174, v172
	v_fma_f32 v32, v136, v32, -v170
	v_fma_f32 v16, v132, v16, -v175
	v_fma_f32 v33, v33, v136, v171
	v_fma_f32 v17, v17, v132, v176
	s_waitcnt vmcnt(4)
	v_mul_f32_e32 v0, v59, v183
	v_mul_f32_e32 v172, v43, v193
	v_mul_f32_e32 v160, v58, v183
	v_mul_f32_e32 v173, v42, v193
	v_mul_f32_e32 v161, v58, v182
	v_mul_f32_e32 v174, v42, v192
	v_mul_f32_e32 v170, v185, v61
	v_mul_f32_e32 v175, v195, v45
	v_mul_f32_e32 v171, v60, v185
	v_mul_f32_e32 v176, v44, v195
	v_fma_f32 v59, v59, v182, v160
	v_fma_f32 v43, v43, v192, v173
	v_sub_f32_e32 v58, v161, v0
	v_sub_f32_e32 v42, v174, v172
	v_fma_f32 v60, v184, v60, -v170
	v_fma_f32 v44, v194, v44, -v175
	v_fma_f32 v61, v61, v184, v171
	v_fma_f32 v45, v45, v194, v176
	v_mul_f32_e32 v0, v27, v183
	v_mul_f32_e32 v172, v11, v193
	v_mul_f32_e32 v160, v26, v183
	v_mul_f32_e32 v173, v10, v193
	v_mul_f32_e32 v161, v26, v182
	v_mul_f32_e32 v174, v10, v192
	v_mul_f32_e32 v170, v185, v29
	v_mul_f32_e32 v175, v195, v13
	v_mul_f32_e32 v171, v28, v185
	v_mul_f32_e32 v176, v12, v195
	v_fma_f32 v27, v27, v182, v160
	v_fma_f32 v11, v11, v192, v173
	v_sub_f32_e32 v26, v161, v0
	v_sub_f32_e32 v10, v174, v172
	v_fma_f32 v28, v184, v28, -v170
	v_fma_f32 v12, v194, v12, -v175
	v_fma_f32 v29, v29, v184, v171
	v_fma_f32 v13, v13, v194, v176
	s_waitcnt vmcnt(2)
	v_mul_f32_e32 v0, v55, v197
	v_mul_f32_e32 v172, v39, v205
	v_mul_f32_e32 v160, v54, v197
	v_mul_f32_e32 v173, v38, v205
	v_mul_f32_e32 v161, v54, v196
	v_mul_f32_e32 v174, v38, v204
	v_mul_f32_e32 v170, v199, v57
	v_mul_f32_e32 v175, v207, v41
	v_mul_f32_e32 v171, v56, v199
	v_mul_f32_e32 v176, v40, v207
	v_fma_f32 v55, v55, v196, v160
	v_fma_f32 v39, v39, v204, v173
	v_sub_f32_e32 v54, v161, v0
	v_sub_f32_e32 v38, v174, v172
	v_fma_f32 v56, v198, v56, -v170
	v_fma_f32 v40, v206, v40, -v175
	v_fma_f32 v57, v57, v198, v171
	v_fma_f32 v41, v41, v206, v176
	v_mul_f32_e32 v0, v23, v197
	v_mul_f32_e32 v172, v7, v205
	v_mul_f32_e32 v160, v22, v197
	v_mul_f32_e32 v173, v6, v205
	v_mul_f32_e32 v161, v22, v196
	v_mul_f32_e32 v174, v6, v204
	v_mul_f32_e32 v170, v199, v25
	v_mul_f32_e32 v175, v207, v9
	v_mul_f32_e32 v171, v24, v199
	v_mul_f32_e32 v176, v8, v207
	v_fma_f32 v23, v23, v196, v160
	v_fma_f32 v7, v7, v204, v173
	v_sub_f32_e32 v22, v161, v0
	v_sub_f32_e32 v6, v174, v172
	v_fma_f32 v24, v198, v24, -v170
	v_fma_f32 v8, v206, v8, -v175
	v_fma_f32 v25, v25, v198, v171
	v_fma_f32 v9, v9, v206, v176
	s_waitcnt vmcnt(0)
; __device__ __forceinline__ unsigned cvt_pk_bf16(float lo, float hi) { unsigned r; asm volatile("v_cvt_pk_bf16_f32 %0, %1, %2" : "=v"(r) : "v"(lo), "v"(hi)); return r; }
;     __device__ __forceinline__ void operator()(AccT& acc, const Unit& u, int wr, int wc, int fr, int fq) const {
;     ...
;                 for (int bj = 0; bj < 2; ++bj) { f32x4 v0 = acc[ai][bj][m][0], v1 = acc[ai][bj][m][1];
;                     if (rot) { const f32x4 a = v0, b = v1;
;                         v0[0] = a[0] * cs0[0] - a[1] * cs0[1]; v0[1] = a[1] * cs0[0] + a[0] * cs0[1]; v0[2] = a[2] * cs0[2] - a[3] * cs0[3]; v0[3] = a[3] * cs0[2] + a[2] * cs0[3];
;                         v1[0] = b[0] * cs1[0] - b[1] * cs1[1]; v1[1] = b[1] * cs1[0] + b[0] * cs1[1]; v1[2] = b[2] * cs1[2] - b[3] * cs1[3]; v1[3] = b[3] * cs1[2] + b[2] * cs1[3]; }
;                     u32x4 w; w.x = cvt_pk_bf16(v0[0], v0[1]); w.y = cvt_pk_bf16(v0[2], v0[3]); w.z = cvt_pk_bf16(v1[0], v1[1]); w.w = cvt_pk_bf16(v1[2], v1[3]);
;                     *(u32x4*)(rowp + bj * 128) = w; }
;                 __builtin_amdgcn_sched_barrier(0); }
	v_mul_f32_e32 v0, v51, v223
	v_mul_f32_e32 v172, v35, v227
	v_mul_f32_e32 v160, v50, v223
	v_mul_f32_e32 v173, v34, v227
	v_mul_f32_e32 v161, v50, v222
	v_mul_f32_e32 v174, v34, v226
	v_mul_f32_e32 v170, v225, v53
	v_mul_f32_e32 v175, v229, v37
	v_mul_f32_e32 v171, v52, v225
	v_mul_f32_e32 v176, v36, v229
	v_fma_f32 v51, v51, v222, v160
	v_fma_f32 v35, v35, v226, v173
	v_sub_f32_e32 v50, v161, v0
	v_sub_f32_e32 v34, v174, v172
	v_fma_f32 v52, v224, v52, -v170
	v_fma_f32 v36, v228, v36, -v175
	v_fma_f32 v53, v53, v224, v171
	v_fma_f32 v37, v37, v228, v176
	v_mul_f32_e32 v0, v19, v223
	v_mul_f32_e32 v172, v3, v227
	v_mul_f32_e32 v160, v18, v223
	v_mul_f32_e32 v173, v2, v227
	v_mul_f32_e32 v161, v18, v222
	v_mul_f32_e32 v174, v2, v226
	v_mul_f32_e32 v170, v225, v21
	v_mul_f32_e32 v175, v229, v5
	v_mul_f32_e32 v171, v20, v225
	v_mul_f32_e32 v176, v4, v229
	v_fma_f32 v19, v19, v222, v160
	v_fma_f32 v3, v3, v226, v173
	v_sub_f32_e32 v18, v161, v0
	v_sub_f32_e32 v2, v174, v172
	v_fma_f32 v20, v224, v20, -v170
	v_fma_f32 v4, v228, v4, -v175
	v_fma_f32 v21, v21, v224, v171
	v_fma_f32 v5, v5, v228, v176
	v_cvt_pk_bf16_f32 v164, v126, v127
	v_cvt_pk_bf16_f32 v165, v128, v129
	v_cvt_pk_bf16_f32 v166, v110, v111
	v_cvt_pk_bf16_f32 v167, v112, v113
	global_store_dwordx4 v[142:143], v[164:167], off
	v_cvt_pk_bf16_f32 v178, v94, v95
	v_cvt_pk_bf16_f32 v179, v96, v97
	v_cvt_pk_bf16_f32 v180, v78, v79
	v_cvt_pk_bf16_f32 v181, v80, v81
	global_store_dwordx4 v[142:143], v[178:181], off offset:256
	v_lshl_add_u64 v[144:145], v[142:143], 0, s[2:3]
	v_cvt_pk_bf16_f32 v164, v122, v123
	v_cvt_pk_bf16_f32 v165, v124, v125
	v_cvt_pk_bf16_f32 v166, v106, v107
	v_cvt_pk_bf16_f32 v167, v108, v109
	global_store_dwordx4 v[144:145], v[164:167], off
	v_cvt_pk_bf16_f32 v178, v90, v91
	v_cvt_pk_bf16_f32 v179, v92, v93
	v_cvt_pk_bf16_f32 v180, v74, v75
	v_cvt_pk_bf16_f32 v181, v76, v77
	global_store_dwordx4 v[144:145], v[178:181], off offset:256
	v_lshl_add_u64 v[142:143], v[144:145], 0, s[2:3]
	v_cvt_pk_bf16_f32 v164, v118, v119
	v_cvt_pk_bf16_f32 v165, v120, v121
	v_cvt_pk_bf16_f32 v166, v102, v103
	v_cvt_pk_bf16_f32 v167, v104, v105
	global_store_dwordx4 v[142:143], v[164:167], off
	v_cvt_pk_bf16_f32 v178, v86, v87
	v_cvt_pk_bf16_f32 v179, v88, v89
	v_cvt_pk_bf16_f32 v180, v70, v71
	v_cvt_pk_bf16_f32 v181, v72, v73
	global_store_dwordx4 v[142:143], v[178:181], off offset:256
	v_lshl_add_u64 v[144:145], v[142:143], 0, s[2:3]
	v_cvt_pk_bf16_f32 v164, v114, v115
	v_cvt_pk_bf16_f32 v165, v116, v117
	v_cvt_pk_bf16_f32 v166, v98, v99
	v_cvt_pk_bf16_f32 v167, v100, v101
	global_store_dwordx4 v[144:145], v[164:167], off
	v_cvt_pk_bf16_f32 v178, v82, v83
	v_cvt_pk_bf16_f32 v179, v84, v85
	v_cvt_pk_bf16_f32 v180, v66, v67
	v_cvt_pk_bf16_f32 v181, v68, v69
	global_store_dwordx4 v[144:145], v[178:181], off offset:256
	v_lshl_add_u64 v[142:143], v[144:145], 0, s[2:3]
	v_lshl_add_u64 v[142:143], v[142:143], 0, s[2:3]
	v_lshl_add_u64 v[142:143], v[142:143], 0, s[2:3]
	v_lshl_add_u64 v[142:143], v[142:143], 0, s[2:3]
	v_lshl_add_u64 v[142:143], v[142:143], 0, s[2:3]
	v_cvt_pk_bf16_f32 v164, v62, v63
	v_cvt_pk_bf16_f32 v165, v64, v65
	v_cvt_pk_bf16_f32 v166, v46, v47
	v_cvt_pk_bf16_f32 v167, v48, v49
	global_store_dwordx4 v[142:143], v[164:167], off
	v_cvt_pk_bf16_f32 v178, v30, v31
	v_cvt_pk_bf16_f32 v179, v32, v33
	v_cvt_pk_bf16_f32 v180, v14, v15
	v_cvt_pk_bf16_f32 v181, v16, v17
	global_store_dwordx4 v[142:143], v[178:181], off offset:256
	v_lshl_add_u64 v[144:145], v[142:143], 0, s[2:3]
	v_cvt_pk_bf16_f32 v164, v58, v59
	v_cvt_pk_bf16_f32 v165, v60, v61
	v_cvt_pk_bf16_f32 v166, v42, v43
	v_cvt_pk_bf16_f32 v167, v44, v45
	global_store_dwordx4 v[144:145], v[164:167], off
	v_cvt_pk_bf16_f32 v178, v26, v27
	v_cvt_pk_bf16_f32 v179, v28, v29
	v_cvt_pk_bf16_f32 v180, v10, v11
	v_cvt_pk_bf16_f32 v181, v12, v13
	global_store_dwordx4 v[144:145], v[178:181], off offset:256
	v_lshl_add_u64 v[142:143], v[144:145], 0, s[2:3]
	v_cvt_pk_bf16_f32 v164, v54, v55
	v_cvt_pk_bf16_f32 v165, v56, v57
	v_cvt_pk_bf16_f32 v166, v38, v39
	v_cvt_pk_bf16_f32 v167, v40, v41
	global_store_dwordx4 v[142:143], v[164:167], off
	v_cvt_pk_bf16_f32 v178, v22, v23
	v_cvt_pk_bf16_f32 v179, v24, v25
	v_cvt_pk_bf16_f32 v180, v6, v7
	v_cvt_pk_bf16_f32 v181, v8, v9
	global_store_dwordx4 v[142:143], v[178:181], off offset:256
	v_lshl_add_u64 v[144:145], v[142:143], 0, s[2:3]
	v_cvt_pk_bf16_f32 v164, v50, v51
	v_cvt_pk_bf16_f32 v165, v52, v53
	v_cvt_pk_bf16_f32 v166, v34, v35
	v_cvt_pk_bf16_f32 v167, v36, v37
	global_store_dwordx4 v[144:145], v[164:167], off
	v_cvt_pk_bf16_f32 v178, v18, v19
	v_cvt_pk_bf16_f32 v179, v20, v21
	v_cvt_pk_bf16_f32 v180, v2, v3
	v_cvt_pk_bf16_f32 v181, v4, v5
	global_store_dwordx4 v[144:145], v[178:181], off offset:256

; __device__ __forceinline__ unsigned cvt_pk_bf16(float lo, float hi) { unsigned r; asm volatile("v_cvt_pk_bf16_f32 %0, %1, %2" : "=v"(r) : "v"(lo), "v"(hi)); return r; }
; __device__ __forceinline__ float sigmoidf_(float x) { return 1.0f / (1.0f + __expf(-x)); }
; __device__ __forceinline__ float dppf_prev(float cur, float below) { return __uint_as_float(dpp_prev(__float_as_uint(cur), __float_as_uint(below))); }
; __device__ __forceinline__ float dppf_next(float cur, float above) { return __uint_as_float(dpp_next(__float_as_uint(cur), __float_as_uint(above))); }
;     __device__ __forceinline__ void operator()(AccT& acc, const Unit& u, int wr, int wc, int fr, int fq) const {
;     ...
;         if (mqk) {
;             const int mc0 = col0 - 2048;
; #pragma unroll
;             for (int ai = 0; ai < 2; ++ai) { const int grp = u.pm * 4 + ai * 2 + wr;
; #pragma unroll
;                 for (int bj = 0; bj < 2; ++bj) { const int mc = mc0 + bj * 128; const float mul = mc < 512 ? 0.08838834764831845f : 1.0f;
; #pragma unroll
;                     for (int n = 0; n < 2; ++n) {
;                         const f32x4 w0 = *(const f32x4*)(cw + mc + 4 * n), w1 = *(const f32x4*)(cw + 1024 + mc + 4 * n), w2 = *(const f32x4*)(cw + 2048 + mc + 4 * n), b = *(const f32x4*)(cb + mc + 4 * n);
; #pragma unroll
;                         for (int m = 0; m < 4; ++m) { const int lr = m * 16 + fr; const f32x4 gc = acc[ai][bj][m][n]; f32x4 o;
; #pragma unroll
;                             for (int j = 0; j < 4; ++j) { const float gp = dppf_prev(gc[j], m > 0 ? acc[ai][bj][m - 1][n][j] : 0.f), gn = dppf_next(gc[j], m < 3 ? acc[ai][bj][m + 1][n][j] : 0.f);
;                                 const float uu = gp * w0[j] + gc[j] * w1[j] + gn * w2[j] + b[j]; o[j] = uu * sigmoidf_(uu) * mul; }
;                             u32x2 w; w.x = cvt_pk_bf16(o[0], o[1]); w.y = cvt_pk_bf16(o[2], o[3]);
;                             *(u32x2*)(O + (size_t)(grp * 64 + lr) * NPROJ + col0 + bj * 128 + 4 * n) = w;
;                             if (m == 0 || m == 3) { if (lr < 2 || lr > 61) { u32x2 wg; wg.x = cvt_pk_bf16(gc[0], gc[1]); wg.y = cvt_pk_bf16(gc[2], gc[3]);
;                                 *(u32x2*)(HQ + (size_t)(grp * 4 + (lr < 2 ? lr : lr - 60)) * 1024 + mc + 4 * n) = wg; } } } } } }
.LBB0_680:
	s_and_b64 vcc, exec, s[2:3]
	s_cbranch_vccz .LBB0_600
	s_movk_i32 s2, 0xa00
	v_ashrrev_i32_e32 v159, 31, v158
	v_cmp_gt_i32_e32 vcc, s2, v158
	v_readlane_b32 s72, v254, 46
	v_readlane_b32 s73, v254, 47
	v_readlane_b32 s74, v254, 48
	v_readlane_b32 s75, v254, 49
	s_lshl_b32 s0, s0, 2
	s_add_i32 s0, s0, s13
	v_cndmask_b32_e32 v0, 1.0, v218, vcc
	v_cmp_gt_u32_e64 s[42:43], 2, v190
	v_cmp_lt_u32_e64 s[44:45], 13, v190
	s_mov_b32 s4, 0xbfb8aa3b
	s_mov_b32 s68, 0x20000
	s_mov_b32 s69, 0
	s_add_u32 s60, s72, 0xffffe000
	s_addc_u32 s61, s73, -1
	s_add_u32 s62, s72, 0xfffff000
	s_addc_u32 s63, s73, -1
	s_add_u32 s64, s72, 0x0
	s_addc_u32 s65, s73, 0
	s_add_u32 s66, s74, 0xffffe000
	s_addc_u32 s67, s75, -1
	v_lshl_add_u64 v[200:201], v[158:159], 2, s[60:61]
	v_lshl_add_u64 v[198:199], v[158:159], 2, s[62:63]
	global_load_dwordx4 v[130:133], v[200:201], off
	global_load_dwordx4 v[134:137], v[198:199], off
	v_lshl_add_u64 v[200:201], v[158:159], 2, s[64:65]
	v_lshl_add_u64 v[198:199], v[158:159], 2, s[66:67]
	global_load_dwordx4 v[138:141], v[200:201], off
	global_load_dwordx4 v[142:145], v[198:199], off
	s_add_u32 s60, s72, 0xffffe010
	s_addc_u32 s61, s73, -1
	s_add_u32 s62, s72, 0xfffff010
	s_addc_u32 s63, s73, -1
	s_add_u32 s64, s72, 0x10
	s_addc_u32 s65, s73, 0
	s_add_u32 s66, s74, 0xffffe010
	s_addc_u32 s67, s75, -1
	v_lshl_add_u64 v[200:201], v[158:159], 2, s[60:61]
	v_lshl_add_u64 v[198:199], v[158:159], 2, s[62:63]
	global_load_dwordx4 v[222:225], v[200:201], off
	global_load_dwordx4 v[226:229], v[198:199], off
	v_lshl_add_u64 v[200:201], v[158:159], 2, s[64:65]
	v_lshl_add_u64 v[198:199], v[158:159], 2, s[66:67]
	global_load_dwordx4 v[230:233], v[200:201], off
	global_load_dwordx4 v[204:207], v[198:199], off
	s_add_i32 s2, s0, 0
	s_lshl_b32 s3, s2, 19
	s_add_u32 s70, s22, s3
	s_addc_u32 s71, s23, 0
	v_lshlrev_b32_e32 v200, 13, v190
	v_mov_b32_e32 v201, 0
	v_lshl_add_u64 v[160:161], v[200:201], 0, s[70:71]
	v_lshl_add_u64 v[160:161], v[158:159], 1, v[160:161]
	v_mov_b32_e32 v170, 0
	v_mov_b32_e32 v171, 0
	v_mov_b32_e32 v172, 0
	v_mov_b32_e32 v173, 0
	v_mov_b32_dpp v174, v122 row_ror:15 row_mask:0xf bank_mask:0xf
	v_mov_b32_dpp v175, v123 row_ror:15 row_mask:0xf bank_mask:0xf
	v_mov_b32_dpp v176, v124 row_ror:15 row_mask:0xf bank_mask:0xf
	v_mov_b32_dpp v177, v125 row_ror:15 row_mask:0xf bank_mask:0xf
	v_mov_b32_dpp v170, v126 row_shr:1 row_mask:0xf bank_mask:0xf
	v_mov_b32_dpp v171, v127 row_shr:1 row_mask:0xf bank_mask:0xf
	v_mov_b32_dpp v172, v128 row_shr:1 row_mask:0xf bank_mask:0xf
	v_mov_b32_dpp v173, v129 row_shr:1 row_mask:0xf bank_mask:0xf
	v_mov_b32_dpp v174, v126 row_shl:1 row_mask:0xf bank_mask:0xf
	v_mov_b32_dpp v175, v127 row_shl:1 row_mask:0xf bank_mask:0xf
	v_mov_b32_dpp v176, v128 row_shl:1 row_mask:0xf bank_mask:0xf
	v_mov_b32_dpp v177, v129 row_shl:1 row_mask:0xf bank_mask:0xf
	s_waitcnt vmcnt(7)
	v_pk_mul_f32 v[170:171], v[130:131], v[170:171]
	v_pk_mul_f32 v[172:173], v[132:133], v[172:173]
	s_waitcnt vmcnt(5)
	v_pk_mul_f32 v[174:175], v[138:139], v[174:175]
	v_pk_mul_f32 v[176:177], v[140:141], v[176:177]
	v_pk_fma_f32 v[164:165], v[126:127], v[134:135], v[170:171]
	v_pk_fma_f32 v[166:167], v[128:129], v[136:137], v[172:173]
	v_pk_add_f32 v[164:165], v[164:165], v[174:175]
	v_pk_add_f32 v[166:167], v[166:167], v[176:177]
	s_waitcnt vmcnt(4)
	v_pk_add_f32 v[164:165], v[142:143], v[164:165]
	v_pk_add_f32 v[166:167], v[144:145], v[166:167]
	v_pk_mul_f32 v[178:179], v[164:165], s[4:5] op_sel_hi:[1,0]
	v_pk_mul_f32 v[184:185], v[166:167], s[4:5] op_sel_hi:[1,0]
	v_exp_f32_e32 v178, v178
	v_exp_f32_e32 v179, v179
	v_exp_f32_e32 v184, v184
	v_exp_f32_e32 v185, v185
	v_pk_add_f32 v[178:179], v[178:179], 1.0 op_sel_hi:[1,0]
	v_pk_add_f32 v[184:185], v[184:185], 1.0 op_sel_hi:[1,0]
	v_rcp_f32_e32 v180, v178
	v_rcp_f32_e32 v181, v179
	v_rcp_f32_e32 v192, v184
	v_rcp_f32_e32 v193, v185
	v_pk_fma_f32 v[182:183], v[178:179], v[180:181], 1.0 op_sel_hi:[1,1,0] neg_lo:[1,0,0] neg_hi:[1,0,0]
	v_pk_fma_f32 v[194:195], v[184:185], v[192:193], 1.0 op_sel_hi:[1,1,0] neg_lo:[1,0,0] neg_hi:[1,0,0]
	v_pk_fma_f32 v[180:181], v[182:183], v[180:181], v[180:181]
	v_pk_fma_f32 v[192:193], v[194:195], v[192:193], v[192:193]
	v_pk_mul_f32 v[164:165], v[164:165], v[180:181]
	v_pk_mul_f32 v[166:167], v[166:167], v[192:193]
	v_pk_mul_f32 v[164:165], v[0:1], v[164:165] op_sel_hi:[0,1]
	v_pk_mul_f32 v[166:167], v[0:1], v[166:167] op_sel_hi:[0,1]
	v_cvt_pk_bf16_f32 v196, v164, v165
	v_cvt_pk_bf16_f32 v197, v166, v167
	global_store_dwordx2 v[160:161], v[196:197], off
	v_lshl_add_u64 v[160:161], v[160:161], 0, s[68:69]
	s_add_i32 s2, s0, 0
	s_lshl_b32 s2, s2, 2
	s_lshl_b32 s2, s2, 11
	s_ashr_i32 s3, s2, 31
	s_add_u32 s70, s48, s2
	s_addc_u32 s71, s49, s3
	v_lshlrev_b32_e32 v200, 11, v190
	v_mov_b32_e32 v201, 0
	v_lshl_add_u64 v[200:201], v[200:201], 0, s[70:71]
	v_lshl_add_u64 v[200:201], v[158:159], 1, v[200:201]
	s_mov_b64 exec, s[42:43]
	v_cvt_pk_bf16_f32 v198, v126, v127
	v_cvt_pk_bf16_f32 v199, v128, v129
	global_store_dwordx2 v[200:201], v[198:199], off offset:-4096
	s_mov_b64 exec, -1
	v_mov_b32_dpp v170, v126 row_ror:1 row_mask:0xf bank_mask:0xf
	v_mov_b32_dpp v171, v127 row_ror:1 row_mask:0xf bank_mask:0xf
	v_mov_b32_dpp v172, v128 row_ror:1 row_mask:0xf bank_mask:0xf
	v_mov_b32_dpp v173, v129 row_ror:1 row_mask:0xf bank_mask:0xf
	v_mov_b32_dpp v174, v118 row_ror:15 row_mask:0xf bank_mask:0xf
	v_mov_b32_dpp v175, v119 row_ror:15 row_mask:0xf bank_mask:0xf
	v_mov_b32_dpp v176, v120 row_ror:15 row_mask:0xf bank_mask:0xf
	v_mov_b32_dpp v177, v121 row_ror:15 row_mask:0xf bank_mask:0xf
	v_mov_b32_dpp v170, v122 row_shr:1 row_mask:0xf bank_mask:0xf
; __device__ __forceinline__ unsigned cvt_pk_bf16(float lo, float hi) { unsigned r; asm volatile("v_cvt_pk_bf16_f32 %0, %1, %2" : "=v"(r) : "v"(lo), "v"(hi)); return r; }
; __device__ __forceinline__ float sigmoidf_(float x) { return 1.0f / (1.0f + __expf(-x)); }
; __device__ __forceinline__ float dppf_prev(float cur, float below) { return __uint_as_float(dpp_prev(__float_as_uint(cur), __float_as_uint(below))); }
; __device__ __forceinline__ float dppf_next(float cur, float above) { return __uint_as_float(dpp_next(__float_as_uint(cur), __float_as_uint(above))); }
;     __device__ __forceinline__ void operator()(AccT& acc, const Unit& u, int wr, int wc, int fr, int fq) const {
;     ...
;             for (int ai = 0; ai < 2; ++ai) { const int grp = u.pm * 4 + ai * 2 + wr;
; #pragma unroll
;                 for (int bj = 0; bj < 2; ++bj) { const int mc = mc0 + bj * 128; const float mul = mc < 512 ? 0.08838834764831845f : 1.0f;
; #pragma unroll
;                     for (int n = 0; n < 2; ++n) {
;                         const f32x4 w0 = *(const f32x4*)(cw + mc + 4 * n), w1 = *(const f32x4*)(cw + 1024 + mc + 4 * n), w2 = *(const f32x4*)(cw + 2048 + mc + 4 * n), b = *(const f32x4*)(cb + mc + 4 * n);
; #pragma unroll
;                         for (int m = 0; m < 4; ++m) { const int lr = m * 16 + fr; const f32x4 gc = acc[ai][bj][m][n]; f32x4 o;
; #pragma unroll
;                             for (int j = 0; j < 4; ++j) { const float gp = dppf_prev(gc[j], m > 0 ? acc[ai][bj][m - 1][n][j] : 0.f), gn = dppf_next(gc[j], m < 3 ? acc[ai][bj][m + 1][n][j] : 0.f);
;                                 const float uu = gp * w0[j] + gc[j] * w1[j] + gn * w2[j] + b[j]; o[j] = uu * sigmoidf_(uu) * mul; }
;                             u32x2 w; w.x = cvt_pk_bf16(o[0], o[1]); w.y = cvt_pk_bf16(o[2], o[3]);
;                             *(u32x2*)(O + (size_t)(grp * 64 + lr) * NPROJ + col0 + bj * 128 + 4 * n) = w;
;                             if (m == 0 || m == 3) { if (lr < 2 || lr > 61) { u32x2 wg; wg.x = cvt_pk_bf16(gc[0], gc[1]); wg.y = cvt_pk_bf16(gc[2], gc[3]);
;                                 *(u32x2*)(HQ + (size_t)(grp * 4 + (lr < 2 ? lr : lr - 60)) * 1024 + mc + 4 * n) = wg; } } } } } }
	v_mov_b32_dpp v171, v123 row_shr:1 row_mask:0xf bank_mask:0xf
	v_mov_b32_dpp v172, v124 row_shr:1 row_mask:0xf bank_mask:0xf
	v_mov_b32_dpp v173, v125 row_shr:1 row_mask:0xf bank_mask:0xf
	v_mov_b32_dpp v174, v122 row_shl:1 row_mask:0xf bank_mask:0xf
	v_mov_b32_dpp v175, v123 row_shl:1 row_mask:0xf bank_mask:0xf
	v_mov_b32_dpp v176, v124 row_shl:1 row_mask:0xf bank_mask:0xf
	v_mov_b32_dpp v177, v125 row_shl:1 row_mask:0xf bank_mask:0xf
	v_pk_mul_f32 v[170:171], v[130:131], v[170:171]
	v_pk_mul_f32 v[172:173], v[132:133], v[172:173]
	v_pk_mul_f32 v[174:175], v[138:139], v[174:175]
	v_pk_mul_f32 v[176:177], v[140:141], v[176:177]
	v_pk_fma_f32 v[164:165], v[122:123], v[134:135], v[170:171]
	v_pk_fma_f32 v[166:167], v[124:125], v[136:137], v[172:173]
	v_pk_add_f32 v[164:165], v[164:165], v[174:175]
	v_pk_add_f32 v[166:167], v[166:167], v[176:177]
	v_pk_add_f32 v[164:165], v[142:143], v[164:165]
	v_pk_add_f32 v[166:167], v[144:145], v[166:167]
	v_pk_mul_f32 v[178:179], v[164:165], s[4:5] op_sel_hi:[1,0]
	v_pk_mul_f32 v[184:185], v[166:167], s[4:5] op_sel_hi:[1,0]
	v_exp_f32_e32 v178, v178
	v_exp_f32_e32 v179, v179
	v_exp_f32_e32 v184, v184
	v_exp_f32_e32 v185, v185
	v_pk_add_f32 v[178:179], v[178:179], 1.0 op_sel_hi:[1,0]
	v_pk_add_f32 v[184:185], v[184:185], 1.0 op_sel_hi:[1,0]
	v_rcp_f32_e32 v180, v178
	v_rcp_f32_e32 v181, v179
	v_rcp_f32_e32 v192, v184
	v_rcp_f32_e32 v193, v185
	v_pk_fma_f32 v[182:183], v[178:179], v[180:181], 1.0 op_sel_hi:[1,1,0] neg_lo:[1,0,0] neg_hi:[1,0,0]
	v_pk_fma_f32 v[194:195], v[184:185], v[192:193], 1.0 op_sel_hi:[1,1,0] neg_lo:[1,0,0] neg_hi:[1,0,0]
	v_pk_fma_f32 v[180:181], v[182:183], v[180:181], v[180:181]
	v_pk_fma_f32 v[192:193], v[194:195], v[192:193], v[192:193]
	v_pk_mul_f32 v[164:165], v[164:165], v[180:181]
	v_pk_mul_f32 v[166:167], v[166:167], v[192:193]
	v_pk_mul_f32 v[164:165], v[0:1], v[164:165] op_sel_hi:[0,1]
	v_pk_mul_f32 v[166:167], v[0:1], v[166:167] op_sel_hi:[0,1]
	v_cvt_pk_bf16_f32 v196, v164, v165
	v_cvt_pk_bf16_f32 v197, v166, v167
	global_store_dwordx2 v[160:161], v[196:197], off
	v_lshl_add_u64 v[160:161], v[160:161], 0, s[68:69]
	v_mov_b32_dpp v170, v122 row_ror:1 row_mask:0xf bank_mask:0xf
	v_mov_b32_dpp v171, v123 row_ror:1 row_mask:0xf bank_mask:0xf
	v_mov_b32_dpp v172, v124 row_ror:1 row_mask:0xf bank_mask:0xf
	v_mov_b32_dpp v173, v125 row_ror:1 row_mask:0xf bank_mask:0xf
	v_mov_b32_dpp v174, v114 row_ror:15 row_mask:0xf bank_mask:0xf
	v_mov_b32_dpp v175, v115 row_ror:15 row_mask:0xf bank_mask:0xf
	v_mov_b32_dpp v176, v116 row_ror:15 row_mask:0xf bank_mask:0xf
	v_mov_b32_dpp v177, v117 row_ror:15 row_mask:0xf bank_mask:0xf
	v_mov_b32_dpp v170, v118 row_shr:1 row_mask:0xf bank_mask:0xf
	v_mov_b32_dpp v171, v119 row_shr:1 row_mask:0xf bank_mask:0xf
	v_mov_b32_dpp v172, v120 row_shr:1 row_mask:0xf bank_mask:0xf
	v_mov_b32_dpp v173, v121 row_shr:1 row_mask:0xf bank_mask:0xf
	v_mov_b32_dpp v174, v118 row_shl:1 row_mask:0xf bank_mask:0xf
	v_mov_b32_dpp v175, v119 row_shl:1 row_mask:0xf bank_mask:0xf
	v_mov_b32_dpp v176, v120 row_shl:1 row_mask:0xf bank_mask:0xf
	v_mov_b32_dpp v177, v121 row_shl:1 row_mask:0xf bank_mask:0xf
	v_pk_mul_f32 v[170:171], v[130:131], v[170:171]
	v_pk_mul_f32 v[172:173], v[132:133], v[172:173]
	v_pk_mul_f32 v[174:175], v[138:139], v[174:175]
	v_pk_mul_f32 v[176:177], v[140:141], v[176:177]
	v_pk_fma_f32 v[164:165], v[118:119], v[134:135], v[170:171]
	v_pk_fma_f32 v[166:167], v[120:121], v[136:137], v[172:173]
	v_pk_add_f32 v[164:165], v[164:165], v[174:175]
	v_pk_add_f32 v[166:167], v[166:167], v[176:177]
	v_pk_add_f32 v[164:165], v[142:143], v[164:165]
	v_pk_add_f32 v[166:167], v[144:145], v[166:167]
	v_pk_mul_f32 v[178:179], v[164:165], s[4:5] op_sel_hi:[1,0]
	v_pk_mul_f32 v[184:185], v[166:167], s[4:5] op_sel_hi:[1,0]
	v_exp_f32_e32 v178, v178
	v_exp_f32_e32 v179, v179
	v_exp_f32_e32 v184, v184
	v_exp_f32_e32 v185, v185
	v_pk_add_f32 v[178:179], v[178:179], 1.0 op_sel_hi:[1,0]
	v_pk_add_f32 v[184:185], v[184:185], 1.0 op_sel_hi:[1,0]
	v_rcp_f32_e32 v180, v178
	v_rcp_f32_e32 v181, v179
	v_rcp_f32_e32 v192, v184
	v_rcp_f32_e32 v193, v185
	v_pk_fma_f32 v[182:183], v[178:179], v[180:181], 1.0 op_sel_hi:[1,1,0] neg_lo:[1,0,0] neg_hi:[1,0,0]
	v_pk_fma_f32 v[194:195], v[184:185], v[192:193], 1.0 op_sel_hi:[1,1,0] neg_lo:[1,0,0] neg_hi:[1,0,0]
	v_pk_fma_f32 v[180:181], v[182:183], v[180:181], v[180:181]
	v_pk_fma_f32 v[192:193], v[194:195], v[192:193], v[192:193]
	v_pk_mul_f32 v[164:165], v[164:165], v[180:181]
	v_pk_mul_f32 v[166:167], v[166:167], v[192:193]
	v_pk_mul_f32 v[164:165], v[0:1], v[164:165] op_sel_hi:[0,1]
	v_pk_mul_f32 v[166:167], v[0:1], v[166:167] op_sel_hi:[0,1]
	v_cvt_pk_bf16_f32 v196, v164, v165
	v_cvt_pk_bf16_f32 v197, v166, v167
	global_store_dwordx2 v[160:161], v[196:197], off
	v_lshl_add_u64 v[160:161], v[160:161], 0, s[68:69]
	v_mov_b32_dpp v170, v118 row_ror:1 row_mask:0xf bank_mask:0xf
	v_mov_b32_dpp v171, v119 row_ror:1 row_mask:0xf bank_mask:0xf
	v_mov_b32_dpp v172, v120 row_ror:1 row_mask:0xf bank_mask:0xf
	v_mov_b32_dpp v173, v121 row_ror:1 row_mask:0xf bank_mask:0xf
	v_mov_b32_e32 v174, 0
	v_mov_b32_e32 v175, 0
	v_mov_b32_e32 v176, 0
	v_mov_b32_e32 v177, 0
	v_mov_b32_dpp v170, v114 row_shr:1 row_mask:0xf bank_mask:0xf
	v_mov_b32_dpp v171, v115 row_shr:1 row_mask:0xf bank_mask:0xf
	v_mov_b32_dpp v172, v116 row_shr:1 row_mask:0xf bank_mask:0xf
	v_mov_b32_dpp v173, v117 row_shr:1 row_mask:0xf bank_mask:0xf
	v_mov_b32_dpp v174, v114 row_shl:1 row_mask:0xf bank_mask:0xf
	v_mov_b32_dpp v175, v115 row_shl:1 row_mask:0xf bank_mask:0xf
	v_mov_b32_dpp v176, v116 row_shl:1 row_mask:0xf bank_mask:0xf
	v_mov_b32_dpp v177, v117 row_shl:1 row_mask:0xf bank_mask:0xf
; __device__ __forceinline__ unsigned cvt_pk_bf16(float lo, float hi) { unsigned r; asm volatile("v_cvt_pk_bf16_f32 %0, %1, %2" : "=v"(r) : "v"(lo), "v"(hi)); return r; }
; __device__ __forceinline__ float sigmoidf_(float x) { return 1.0f / (1.0f + __expf(-x)); }
; __device__ __forceinline__ float dppf_prev(float cur, float below) { return __uint_as_float(dpp_prev(__float_as_uint(cur), __float_as_uint(below))); }
; __device__ __forceinline__ float dppf_next(float cur, float above) { return __uint_as_float(dpp_next(__float_as_uint(cur), __float_as_uint(above))); }
;     __device__ __forceinline__ void operator()(AccT& acc, const Unit& u, int wr, int wc, int fr, int fq) const {
;     ...
;             for (int ai = 0; ai < 2; ++ai) { const int grp = u.pm * 4 + ai * 2 + wr;
; #pragma unroll
;                 for (int bj = 0; bj < 2; ++bj) { const int mc = mc0 + bj * 128; const float mul = mc < 512 ? 0.08838834764831845f : 1.0f;
; #pragma unroll
;                     for (int n = 0; n < 2; ++n) {
;                         const f32x4 w0 = *(const f32x4*)(cw + mc + 4 * n), w1 = *(const f32x4*)(cw + 1024 + mc + 4 * n), w2 = *(const f32x4*)(cw + 2048 + mc + 4 * n), b = *(const f32x4*)(cb + mc + 4 * n);
; #pragma unroll
;                         for (int m = 0; m < 4; ++m) { const int lr = m * 16 + fr; const f32x4 gc = acc[ai][bj][m][n]; f32x4 o;
; #pragma unroll
;                             for (int j = 0; j < 4; ++j) { const float gp = dppf_prev(gc[j], m > 0 ? acc[ai][bj][m - 1][n][j] : 0.f), gn = dppf_next(gc[j], m < 3 ? acc[ai][bj][m + 1][n][j] : 0.f);
;                                 const float uu = gp * w0[j] + gc[j] * w1[j] + gn * w2[j] + b[j]; o[j] = uu * sigmoidf_(uu) * mul; }
;                             u32x2 w; w.x = cvt_pk_bf16(o[0], o[1]); w.y = cvt_pk_bf16(o[2], o[3]);
;                             *(u32x2*)(O + (size_t)(grp * 64 + lr) * NPROJ + col0 + bj * 128 + 4 * n) = w;
;                             if (m == 0 || m == 3) { if (lr < 2 || lr > 61) { u32x2 wg; wg.x = cvt_pk_bf16(gc[0], gc[1]); wg.y = cvt_pk_bf16(gc[2], gc[3]);
;                                 *(u32x2*)(HQ + (size_t)(grp * 4 + (lr < 2 ? lr : lr - 60)) * 1024 + mc + 4 * n) = wg; } } } } } }
	v_pk_mul_f32 v[170:171], v[130:131], v[170:171]
	v_pk_mul_f32 v[172:173], v[132:133], v[172:173]
	v_pk_mul_f32 v[174:175], v[138:139], v[174:175]
	v_pk_mul_f32 v[176:177], v[140:141], v[176:177]
	v_pk_fma_f32 v[164:165], v[114:115], v[134:135], v[170:171]
	v_pk_fma_f32 v[166:167], v[116:117], v[136:137], v[172:173]
	v_pk_add_f32 v[164:165], v[164:165], v[174:175]
	v_pk_add_f32 v[166:167], v[166:167], v[176:177]
	v_pk_add_f32 v[164:165], v[142:143], v[164:165]
	v_pk_add_f32 v[166:167], v[144:145], v[166:167]
	v_pk_mul_f32 v[178:179], v[164:165], s[4:5] op_sel_hi:[1,0]
	v_pk_mul_f32 v[184:185], v[166:167], s[4:5] op_sel_hi:[1,0]
	v_exp_f32_e32 v178, v178
	v_exp_f32_e32 v179, v179
	v_exp_f32_e32 v184, v184
	v_exp_f32_e32 v185, v185
	v_pk_add_f32 v[178:179], v[178:179], 1.0 op_sel_hi:[1,0]
	v_pk_add_f32 v[184:185], v[184:185], 1.0 op_sel_hi:[1,0]
	v_rcp_f32_e32 v180, v178
	v_rcp_f32_e32 v181, v179
	v_rcp_f32_e32 v192, v184
	v_rcp_f32_e32 v193, v185
	v_pk_fma_f32 v[182:183], v[178:179], v[180:181], 1.0 op_sel_hi:[1,1,0] neg_lo:[1,0,0] neg_hi:[1,0,0]
	v_pk_fma_f32 v[194:195], v[184:185], v[192:193], 1.0 op_sel_hi:[1,1,0] neg_lo:[1,0,0] neg_hi:[1,0,0]
	v_pk_fma_f32 v[180:181], v[182:183], v[180:181], v[180:181]
	v_pk_fma_f32 v[192:193], v[194:195], v[192:193], v[192:193]
	v_pk_mul_f32 v[164:165], v[164:165], v[180:181]
	v_pk_mul_f32 v[166:167], v[166:167], v[192:193]
	v_pk_mul_f32 v[164:165], v[0:1], v[164:165] op_sel_hi:[0,1]
	v_pk_mul_f32 v[166:167], v[0:1], v[166:167] op_sel_hi:[0,1]
	v_cvt_pk_bf16_f32 v196, v164, v165
	v_cvt_pk_bf16_f32 v197, v166, v167
	global_store_dwordx2 v[160:161], v[196:197], off
	s_add_i32 s2, s0, 0
	s_lshl_b32 s2, s2, 2
	s_add_i32 s2, s2, -12
	s_lshl_b32 s2, s2, 11
	s_ashr_i32 s3, s2, 31
	s_add_u32 s70, s48, s2
	s_addc_u32 s71, s49, s3
	v_lshlrev_b32_e32 v200, 11, v190
	v_mov_b32_e32 v201, 0
	v_lshl_add_u64 v[200:201], v[200:201], 0, s[70:71]
	v_lshl_add_u64 v[200:201], v[158:159], 1, v[200:201]
	s_mov_b64 exec, s[44:45]
	v_cvt_pk_bf16_f32 v198, v114, v115
	v_cvt_pk_bf16_f32 v199, v116, v117
	global_store_dwordx2 v[200:201], v[198:199], off offset:-4096
	s_mov_b64 exec, -1
	s_add_i32 s2, s0, 2
	s_lshl_b32 s3, s2, 19
	s_add_u32 s70, s22, s3
	s_addc_u32 s71, s23, 0
	v_lshlrev_b32_e32 v200, 13, v190
	v_mov_b32_e32 v201, 0
	v_lshl_add_u64 v[160:161], v[200:201], 0, s[70:71]
	v_lshl_add_u64 v[160:161], v[158:159], 1, v[160:161]
	v_mov_b32_e32 v170, 0
	v_mov_b32_e32 v171, 0
	v_mov_b32_e32 v172, 0
	v_mov_b32_e32 v173, 0
	v_mov_b32_dpp v174, v58 row_ror:15 row_mask:0xf bank_mask:0xf
	v_mov_b32_dpp v175, v59 row_ror:15 row_mask:0xf bank_mask:0xf
	v_mov_b32_dpp v176, v60 row_ror:15 row_mask:0xf bank_mask:0xf
	v_mov_b32_dpp v177, v61 row_ror:15 row_mask:0xf bank_mask:0xf
	v_mov_b32_dpp v170, v62 row_shr:1 row_mask:0xf bank_mask:0xf
	v_mov_b32_dpp v171, v63 row_shr:1 row_mask:0xf bank_mask:0xf
	v_mov_b32_dpp v172, v64 row_shr:1 row_mask:0xf bank_mask:0xf
	v_mov_b32_dpp v173, v65 row_shr:1 row_mask:0xf bank_mask:0xf
	v_mov_b32_dpp v174, v62 row_shl:1 row_mask:0xf bank_mask:0xf
	v_mov_b32_dpp v175, v63 row_shl:1 row_mask:0xf bank_mask:0xf
	v_mov_b32_dpp v176, v64 row_shl:1 row_mask:0xf bank_mask:0xf
	v_mov_b32_dpp v177, v65 row_shl:1 row_mask:0xf bank_mask:0xf
	v_pk_mul_f32 v[170:171], v[130:131], v[170:171]
	v_pk_mul_f32 v[172:173], v[132:133], v[172:173]
	v_pk_mul_f32 v[174:175], v[138:139], v[174:175]
	v_pk_mul_f32 v[176:177], v[140:141], v[176:177]
	v_pk_fma_f32 v[164:165], v[62:63], v[134:135], v[170:171]
	v_pk_fma_f32 v[166:167], v[64:65], v[136:137], v[172:173]
	v_pk_add_f32 v[164:165], v[164:165], v[174:175]
	v_pk_add_f32 v[166:167], v[166:167], v[176:177]
	v_pk_add_f32 v[164:165], v[142:143], v[164:165]
	v_pk_add_f32 v[166:167], v[144:145], v[166:167]
	v_pk_mul_f32 v[178:179], v[164:165], s[4:5] op_sel_hi:[1,0]
	v_pk_mul_f32 v[184:185], v[166:167], s[4:5] op_sel_hi:[1,0]
	v_exp_f32_e32 v178, v178
	v_exp_f32_e32 v179, v179
	v_exp_f32_e32 v184, v184
	v_exp_f32_e32 v185, v185
	v_pk_add_f32 v[178:179], v[178:179], 1.0 op_sel_hi:[1,0]
	v_pk_add_f32 v[184:185], v[184:185], 1.0 op_sel_hi:[1,0]
	v_rcp_f32_e32 v180, v178
	v_rcp_f32_e32 v181, v179
	v_rcp_f32_e32 v192, v184
	v_rcp_f32_e32 v193, v185
	v_pk_fma_f32 v[182:183], v[178:179], v[180:181], 1.0 op_sel_hi:[1,1,0] neg_lo:[1,0,0] neg_hi:[1,0,0]
	v_pk_fma_f32 v[194:195], v[184:185], v[192:193], 1.0 op_sel_hi:[1,1,0] neg_lo:[1,0,0] neg_hi:[1,0,0]
	v_pk_fma_f32 v[180:181], v[182:183], v[180:181], v[180:181]
	v_pk_fma_f32 v[192:193], v[194:195], v[192:193], v[192:193]
	v_pk_mul_f32 v[164:165], v[164:165], v[180:181]
	v_pk_mul_f32 v[166:167], v[166:167], v[192:193]
	v_pk_mul_f32 v[164:165], v[0:1], v[164:165] op_sel_hi:[0,1]
	v_pk_mul_f32 v[166:167], v[0:1], v[166:167] op_sel_hi:[0,1]
	v_cvt_pk_bf16_f32 v196, v164, v165
	v_cvt_pk_bf16_f32 v197, v166, v167
	global_store_dwordx2 v[160:161], v[196:197], off
	v_lshl_add_u64 v[160:161], v[160:161], 0, s[68:69]
	s_add_i32 s2, s0, 2
	s_lshl_b32 s2, s2, 2
	s_lshl_b32 s2, s2, 11
	s_ashr_i32 s3, s2, 31
	s_add_u32 s70, s48, s2
	s_addc_u32 s71, s49, s3
	v_lshlrev_b32_e32 v200, 11, v190
	v_mov_b32_e32 v201, 0
	v_lshl_add_u64 v[200:201], v[200:201], 0, s[70:71]
	v_lshl_add_u64 v[200:201], v[158:159], 1, v[200:201]
	s_mov_b64 exec, s[42:43]
	v_cvt_pk_bf16_f32 v198, v62, v63
	v_cvt_pk_bf16_f32 v199, v64, v65
	global_store_dwordx2 v[200:201], v[198:199], off offset:-4096
	s_mov_b64 exec, -1
	v_mov_b32_dpp v170, v62 row_ror:1 row_mask:0xf bank_mask:0xf
	v_mov_b32_dpp v171, v63 row_ror:1 row_mask:0xf bank_mask:0xf
	v_mov_b32_dpp v172, v64 row_ror:1 row_mask:0xf bank_mask:0xf
	v_mov_b32_dpp v173, v65 row_ror:1 row_mask:0xf bank_mask:0xf
; __device__ __forceinline__ unsigned cvt_pk_bf16(float lo, float hi) { unsigned r; asm volatile("v_cvt_pk_bf16_f32 %0, %1, %2" : "=v"(r) : "v"(lo), "v"(hi)); return r; }
; __device__ __forceinline__ float sigmoidf_(float x) { return 1.0f / (1.0f + __expf(-x)); }
; __device__ __forceinline__ float dppf_prev(float cur, float below) { return __uint_as_float(dpp_prev(__float_as_uint(cur), __float_as_uint(below))); }
; __device__ __forceinline__ float dppf_next(float cur, float above) { return __uint_as_float(dpp_next(__float_as_uint(cur), __float_as_uint(above))); }
;     __device__ __forceinline__ void operator()(AccT& acc, const Unit& u, int wr, int wc, int fr, int fq) const {
;     ...
;             for (int ai = 0; ai < 2; ++ai) { const int grp = u.pm * 4 + ai * 2 + wr;
; #pragma unroll
;                 for (int bj = 0; bj < 2; ++bj) { const int mc = mc0 + bj * 128; const float mul = mc < 512 ? 0.08838834764831845f : 1.0f;
; #pragma unroll
;                     for (int n = 0; n < 2; ++n) {
;                         const f32x4 w0 = *(const f32x4*)(cw + mc + 4 * n), w1 = *(const f32x4*)(cw + 1024 + mc + 4 * n), w2 = *(const f32x4*)(cw + 2048 + mc + 4 * n), b = *(const f32x4*)(cb + mc + 4 * n);
; #pragma unroll
;                         for (int m = 0; m < 4; ++m) { const int lr = m * 16 + fr; const f32x4 gc = acc[ai][bj][m][n]; f32x4 o;
; #pragma unroll
;                             for (int j = 0; j < 4; ++j) { const float gp = dppf_prev(gc[j], m > 0 ? acc[ai][bj][m - 1][n][j] : 0.f), gn = dppf_next(gc[j], m < 3 ? acc[ai][bj][m + 1][n][j] : 0.f);
;                                 const float uu = gp * w0[j] + gc[j] * w1[j] + gn * w2[j] + b[j]; o[j] = uu * sigmoidf_(uu) * mul; }
;                             u32x2 w; w.x = cvt_pk_bf16(o[0], o[1]); w.y = cvt_pk_bf16(o[2], o[3]);
;                             *(u32x2*)(O + (size_t)(grp * 64 + lr) * NPROJ + col0 + bj * 128 + 4 * n) = w;
;                             if (m == 0 || m == 3) { if (lr < 2 || lr > 61) { u32x2 wg; wg.x = cvt_pk_bf16(gc[0], gc[1]); wg.y = cvt_pk_bf16(gc[2], gc[3]);
;                                 *(u32x2*)(HQ + (size_t)(grp * 4 + (lr < 2 ? lr : lr - 60)) * 1024 + mc + 4 * n) = wg; } } } } } }
	v_mov_b32_dpp v174, v54 row_ror:15 row_mask:0xf bank_mask:0xf
	v_mov_b32_dpp v175, v55 row_ror:15 row_mask:0xf bank_mask:0xf
	v_mov_b32_dpp v176, v56 row_ror:15 row_mask:0xf bank_mask:0xf
	v_mov_b32_dpp v177, v57 row_ror:15 row_mask:0xf bank_mask:0xf
	v_mov_b32_dpp v170, v58 row_shr:1 row_mask:0xf bank_mask:0xf
	v_mov_b32_dpp v171, v59 row_shr:1 row_mask:0xf bank_mask:0xf
	v_mov_b32_dpp v172, v60 row_shr:1 row_mask:0xf bank_mask:0xf
	v_mov_b32_dpp v173, v61 row_shr:1 row_mask:0xf bank_mask:0xf
	v_mov_b32_dpp v174, v58 row_shl:1 row_mask:0xf bank_mask:0xf
	v_mov_b32_dpp v175, v59 row_shl:1 row_mask:0xf bank_mask:0xf
	v_mov_b32_dpp v176, v60 row_shl:1 row_mask:0xf bank_mask:0xf
	v_mov_b32_dpp v177, v61 row_shl:1 row_mask:0xf bank_mask:0xf
	v_pk_mul_f32 v[170:171], v[130:131], v[170:171]
	v_pk_mul_f32 v[172:173], v[132:133], v[172:173]
	v_pk_mul_f32 v[174:175], v[138:139], v[174:175]
	v_pk_mul_f32 v[176:177], v[140:141], v[176:177]
	v_pk_fma_f32 v[164:165], v[58:59], v[134:135], v[170:171]
	v_pk_fma_f32 v[166:167], v[60:61], v[136:137], v[172:173]
	v_pk_add_f32 v[164:165], v[164:165], v[174:175]
	v_pk_add_f32 v[166:167], v[166:167], v[176:177]
	v_pk_add_f32 v[164:165], v[142:143], v[164:165]
	v_pk_add_f32 v[166:167], v[144:145], v[166:167]
	v_pk_mul_f32 v[178:179], v[164:165], s[4:5] op_sel_hi:[1,0]
	v_pk_mul_f32 v[184:185], v[166:167], s[4:5] op_sel_hi:[1,0]
	v_exp_f32_e32 v178, v178
	v_exp_f32_e32 v179, v179
	v_exp_f32_e32 v184, v184
	v_exp_f32_e32 v185, v185
	v_pk_add_f32 v[178:179], v[178:179], 1.0 op_sel_hi:[1,0]
	v_pk_add_f32 v[184:185], v[184:185], 1.0 op_sel_hi:[1,0]
	v_rcp_f32_e32 v180, v178
	v_rcp_f32_e32 v181, v179
	v_rcp_f32_e32 v192, v184
	v_rcp_f32_e32 v193, v185
	v_pk_fma_f32 v[182:183], v[178:179], v[180:181], 1.0 op_sel_hi:[1,1,0] neg_lo:[1,0,0] neg_hi:[1,0,0]
	v_pk_fma_f32 v[194:195], v[184:185], v[192:193], 1.0 op_sel_hi:[1,1,0] neg_lo:[1,0,0] neg_hi:[1,0,0]
	v_pk_fma_f32 v[180:181], v[182:183], v[180:181], v[180:181]
	v_pk_fma_f32 v[192:193], v[194:195], v[192:193], v[192:193]
	v_pk_mul_f32 v[164:165], v[164:165], v[180:181]
	v_pk_mul_f32 v[166:167], v[166:167], v[192:193]
	v_pk_mul_f32 v[164:165], v[0:1], v[164:165] op_sel_hi:[0,1]
	v_pk_mul_f32 v[166:167], v[0:1], v[166:167] op_sel_hi:[0,1]
	v_cvt_pk_bf16_f32 v196, v164, v165
	v_cvt_pk_bf16_f32 v197, v166, v167
	global_store_dwordx2 v[160:161], v[196:197], off
	v_lshl_add_u64 v[160:161], v[160:161], 0, s[68:69]
	v_mov_b32_dpp v170, v58 row_ror:1 row_mask:0xf bank_mask:0xf
	v_mov_b32_dpp v171, v59 row_ror:1 row_mask:0xf bank_mask:0xf
	v_mov_b32_dpp v172, v60 row_ror:1 row_mask:0xf bank_mask:0xf
	v_mov_b32_dpp v173, v61 row_ror:1 row_mask:0xf bank_mask:0xf
	v_mov_b32_dpp v174, v50 row_ror:15 row_mask:0xf bank_mask:0xf
	v_mov_b32_dpp v175, v51 row_ror:15 row_mask:0xf bank_mask:0xf
	v_mov_b32_dpp v176, v52 row_ror:15 row_mask:0xf bank_mask:0xf
	v_mov_b32_dpp v177, v53 row_ror:15 row_mask:0xf bank_mask:0xf
	v_mov_b32_dpp v170, v54 row_shr:1 row_mask:0xf bank_mask:0xf
	v_mov_b32_dpp v171, v55 row_shr:1 row_mask:0xf bank_mask:0xf
	v_mov_b32_dpp v172, v56 row_shr:1 row_mask:0xf bank_mask:0xf
	v_mov_b32_dpp v173, v57 row_shr:1 row_mask:0xf bank_mask:0xf
	v_mov_b32_dpp v174, v54 row_shl:1 row_mask:0xf bank_mask:0xf
	v_mov_b32_dpp v175, v55 row_shl:1 row_mask:0xf bank_mask:0xf
	v_mov_b32_dpp v176, v56 row_shl:1 row_mask:0xf bank_mask:0xf
	v_mov_b32_dpp v177, v57 row_shl:1 row_mask:0xf bank_mask:0xf
	v_pk_mul_f32 v[170:171], v[130:131], v[170:171]
	v_pk_mul_f32 v[172:173], v[132:133], v[172:173]
	v_pk_mul_f32 v[174:175], v[138:139], v[174:175]
	v_pk_mul_f32 v[176:177], v[140:141], v[176:177]
	v_pk_fma_f32 v[164:165], v[54:55], v[134:135], v[170:171]
	v_pk_fma_f32 v[166:167], v[56:57], v[136:137], v[172:173]
	v_pk_add_f32 v[164:165], v[164:165], v[174:175]
	v_pk_add_f32 v[166:167], v[166:167], v[176:177]
	v_pk_add_f32 v[164:165], v[142:143], v[164:165]
	v_pk_add_f32 v[166:167], v[144:145], v[166:167]
	v_pk_mul_f32 v[178:179], v[164:165], s[4:5] op_sel_hi:[1,0]
	v_pk_mul_f32 v[184:185], v[166:167], s[4:5] op_sel_hi:[1,0]
	v_exp_f32_e32 v178, v178
	v_exp_f32_e32 v179, v179
	v_exp_f32_e32 v184, v184
	v_exp_f32_e32 v185, v185
	v_pk_add_f32 v[178:179], v[178:179], 1.0 op_sel_hi:[1,0]
	v_pk_add_f32 v[184:185], v[184:185], 1.0 op_sel_hi:[1,0]
	v_rcp_f32_e32 v180, v178
	v_rcp_f32_e32 v181, v179
	v_rcp_f32_e32 v192, v184
	v_rcp_f32_e32 v193, v185
	v_pk_fma_f32 v[182:183], v[178:179], v[180:181], 1.0 op_sel_hi:[1,1,0] neg_lo:[1,0,0] neg_hi:[1,0,0]
	v_pk_fma_f32 v[194:195], v[184:185], v[192:193], 1.0 op_sel_hi:[1,1,0] neg_lo:[1,0,0] neg_hi:[1,0,0]
	v_pk_fma_f32 v[180:181], v[182:183], v[180:181], v[180:181]
	v_pk_fma_f32 v[192:193], v[194:195], v[192:193], v[192:193]
	v_pk_mul_f32 v[164:165], v[164:165], v[180:181]
	v_pk_mul_f32 v[166:167], v[166:167], v[192:193]
	v_pk_mul_f32 v[164:165], v[0:1], v[164:165] op_sel_hi:[0,1]
	v_pk_mul_f32 v[166:167], v[0:1], v[166:167] op_sel_hi:[0,1]
	v_cvt_pk_bf16_f32 v196, v164, v165
	v_cvt_pk_bf16_f32 v197, v166, v167
	global_store_dwordx2 v[160:161], v[196:197], off
	v_lshl_add_u64 v[160:161], v[160:161], 0, s[68:69]
	v_mov_b32_dpp v170, v54 row_ror:1 row_mask:0xf bank_mask:0xf
	v_mov_b32_dpp v171, v55 row_ror:1 row_mask:0xf bank_mask:0xf
	v_mov_b32_dpp v172, v56 row_ror:1 row_mask:0xf bank_mask:0xf
	v_mov_b32_dpp v173, v57 row_ror:1 row_mask:0xf bank_mask:0xf
	v_mov_b32_e32 v174, 0
	v_mov_b32_e32 v175, 0
	v_mov_b32_e32 v176, 0
	v_mov_b32_e32 v177, 0
	v_mov_b32_dpp v170, v50 row_shr:1 row_mask:0xf bank_mask:0xf
	v_mov_b32_dpp v171, v51 row_shr:1 row_mask:0xf bank_mask:0xf
	v_mov_b32_dpp v172, v52 row_shr:1 row_mask:0xf bank_mask:0xf
; __device__ __forceinline__ unsigned cvt_pk_bf16(float lo, float hi) { unsigned r; asm volatile("v_cvt_pk_bf16_f32 %0, %1, %2" : "=v"(r) : "v"(lo), "v"(hi)); return r; }
; __device__ __forceinline__ float sigmoidf_(float x) { return 1.0f / (1.0f + __expf(-x)); }
; __device__ __forceinline__ float dppf_prev(float cur, float below) { return __uint_as_float(dpp_prev(__float_as_uint(cur), __float_as_uint(below))); }
; __device__ __forceinline__ float dppf_next(float cur, float above) { return __uint_as_float(dpp_next(__float_as_uint(cur), __float_as_uint(above))); }
;     __device__ __forceinline__ void operator()(AccT& acc, const Unit& u, int wr, int wc, int fr, int fq) const {
;     ...
;             for (int ai = 0; ai < 2; ++ai) { const int grp = u.pm * 4 + ai * 2 + wr;
; #pragma unroll
;                 for (int bj = 0; bj < 2; ++bj) { const int mc = mc0 + bj * 128; const float mul = mc < 512 ? 0.08838834764831845f : 1.0f;
; #pragma unroll
;                     for (int n = 0; n < 2; ++n) {
;                         const f32x4 w0 = *(const f32x4*)(cw + mc + 4 * n), w1 = *(const f32x4*)(cw + 1024 + mc + 4 * n), w2 = *(const f32x4*)(cw + 2048 + mc + 4 * n), b = *(const f32x4*)(cb + mc + 4 * n);
; #pragma unroll
;                         for (int m = 0; m < 4; ++m) { const int lr = m * 16 + fr; const f32x4 gc = acc[ai][bj][m][n]; f32x4 o;
; #pragma unroll
;                             for (int j = 0; j < 4; ++j) { const float gp = dppf_prev(gc[j], m > 0 ? acc[ai][bj][m - 1][n][j] : 0.f), gn = dppf_next(gc[j], m < 3 ? acc[ai][bj][m + 1][n][j] : 0.f);
;                                 const float uu = gp * w0[j] + gc[j] * w1[j] + gn * w2[j] + b[j]; o[j] = uu * sigmoidf_(uu) * mul; }
;                             u32x2 w; w.x = cvt_pk_bf16(o[0], o[1]); w.y = cvt_pk_bf16(o[2], o[3]);
;                             *(u32x2*)(O + (size_t)(grp * 64 + lr) * NPROJ + col0 + bj * 128 + 4 * n) = w;
;                             if (m == 0 || m == 3) { if (lr < 2 || lr > 61) { u32x2 wg; wg.x = cvt_pk_bf16(gc[0], gc[1]); wg.y = cvt_pk_bf16(gc[2], gc[3]);
;                                 *(u32x2*)(HQ + (size_t)(grp * 4 + (lr < 2 ? lr : lr - 60)) * 1024 + mc + 4 * n) = wg; } } } } } }
	v_mov_b32_dpp v173, v53 row_shr:1 row_mask:0xf bank_mask:0xf
	v_mov_b32_dpp v174, v50 row_shl:1 row_mask:0xf bank_mask:0xf
	v_mov_b32_dpp v175, v51 row_shl:1 row_mask:0xf bank_mask:0xf
	v_mov_b32_dpp v176, v52 row_shl:1 row_mask:0xf bank_mask:0xf
	v_mov_b32_dpp v177, v53 row_shl:1 row_mask:0xf bank_mask:0xf
	v_pk_mul_f32 v[170:171], v[130:131], v[170:171]
	v_pk_mul_f32 v[172:173], v[132:133], v[172:173]
	v_pk_mul_f32 v[174:175], v[138:139], v[174:175]
	v_pk_mul_f32 v[176:177], v[140:141], v[176:177]
	v_pk_fma_f32 v[164:165], v[50:51], v[134:135], v[170:171]
	v_pk_fma_f32 v[166:167], v[52:53], v[136:137], v[172:173]
	v_pk_add_f32 v[164:165], v[164:165], v[174:175]
	v_pk_add_f32 v[166:167], v[166:167], v[176:177]
	v_pk_add_f32 v[164:165], v[142:143], v[164:165]
	v_pk_add_f32 v[166:167], v[144:145], v[166:167]
	v_pk_mul_f32 v[178:179], v[164:165], s[4:5] op_sel_hi:[1,0]
	v_pk_mul_f32 v[184:185], v[166:167], s[4:5] op_sel_hi:[1,0]
	v_exp_f32_e32 v178, v178
	v_exp_f32_e32 v179, v179
	v_exp_f32_e32 v184, v184
	v_exp_f32_e32 v185, v185
	v_pk_add_f32 v[178:179], v[178:179], 1.0 op_sel_hi:[1,0]
	v_pk_add_f32 v[184:185], v[184:185], 1.0 op_sel_hi:[1,0]
	v_rcp_f32_e32 v180, v178
	v_rcp_f32_e32 v181, v179
	v_rcp_f32_e32 v192, v184
	v_rcp_f32_e32 v193, v185
	v_pk_fma_f32 v[182:183], v[178:179], v[180:181], 1.0 op_sel_hi:[1,1,0] neg_lo:[1,0,0] neg_hi:[1,0,0]
	v_pk_fma_f32 v[194:195], v[184:185], v[192:193], 1.0 op_sel_hi:[1,1,0] neg_lo:[1,0,0] neg_hi:[1,0,0]
	v_pk_fma_f32 v[180:181], v[182:183], v[180:181], v[180:181]
	v_pk_fma_f32 v[192:193], v[194:195], v[192:193], v[192:193]
	v_pk_mul_f32 v[164:165], v[164:165], v[180:181]
	v_pk_mul_f32 v[166:167], v[166:167], v[192:193]
	v_pk_mul_f32 v[164:165], v[0:1], v[164:165] op_sel_hi:[0,1]
	v_pk_mul_f32 v[166:167], v[0:1], v[166:167] op_sel_hi:[0,1]
	v_cvt_pk_bf16_f32 v196, v164, v165
	v_cvt_pk_bf16_f32 v197, v166, v167
	global_store_dwordx2 v[160:161], v[196:197], off
	s_add_i32 s2, s0, 2
	s_lshl_b32 s2, s2, 2
	s_add_i32 s2, s2, -12
	s_lshl_b32 s2, s2, 11
	s_ashr_i32 s3, s2, 31
	s_add_u32 s70, s48, s2
	s_addc_u32 s71, s49, s3
	v_lshlrev_b32_e32 v200, 11, v190
	v_mov_b32_e32 v201, 0
	v_lshl_add_u64 v[200:201], v[200:201], 0, s[70:71]
	v_lshl_add_u64 v[200:201], v[158:159], 1, v[200:201]
	s_mov_b64 exec, s[44:45]
	v_cvt_pk_bf16_f32 v198, v50, v51
	v_cvt_pk_bf16_f32 v199, v52, v53
	global_store_dwordx2 v[200:201], v[198:199], off offset:-4096
	s_mov_b64 exec, -1
	s_add_u32 s60, s72, 0xffffe200
	s_addc_u32 s61, s73, -1
	s_add_u32 s62, s72, 0xfffff200
	s_addc_u32 s63, s73, -1
	s_add_u32 s64, s72, 0x200
	s_addc_u32 s65, s73, 0
	s_add_u32 s66, s74, 0xffffe200
	s_addc_u32 s67, s75, -1
	v_lshl_add_u64 v[200:201], v[158:159], 2, s[60:61]
	v_lshl_add_u64 v[198:199], v[158:159], 2, s[62:63]
	global_load_dwordx4 v[130:133], v[200:201], off
	global_load_dwordx4 v[134:137], v[198:199], off
	v_lshl_add_u64 v[200:201], v[158:159], 2, s[64:65]
	v_lshl_add_u64 v[198:199], v[158:159], 2, s[66:67]
	global_load_dwordx4 v[138:141], v[200:201], off
	global_load_dwordx4 v[142:145], v[198:199], off
	s_add_i32 s2, s0, 0
	s_lshl_b32 s3, s2, 19
	s_add_u32 s70, s22, s3
	s_addc_u32 s71, s23, 0
	v_lshlrev_b32_e32 v200, 13, v190
	v_mov_b32_e32 v201, 0
	v_lshl_add_u64 v[160:161], v[200:201], 0, s[70:71]
	v_lshl_add_u64 v[160:161], v[158:159], 1, v[160:161]
	v_mov_b32_e32 v170, 0
	v_mov_b32_e32 v171, 0
	v_mov_b32_e32 v172, 0
	v_mov_b32_e32 v173, 0
	v_mov_b32_dpp v174, v106 row_ror:15 row_mask:0xf bank_mask:0xf
	v_mov_b32_dpp v175, v107 row_ror:15 row_mask:0xf bank_mask:0xf
	v_mov_b32_dpp v176, v108 row_ror:15 row_mask:0xf bank_mask:0xf
	v_mov_b32_dpp v177, v109 row_ror:15 row_mask:0xf bank_mask:0xf
	v_mov_b32_dpp v170, v110 row_shr:1 row_mask:0xf bank_mask:0xf
	v_mov_b32_dpp v171, v111 row_shr:1 row_mask:0xf bank_mask:0xf
	v_mov_b32_dpp v172, v112 row_shr:1 row_mask:0xf bank_mask:0xf
	v_mov_b32_dpp v173, v113 row_shr:1 row_mask:0xf bank_mask:0xf
	v_mov_b32_dpp v174, v110 row_shl:1 row_mask:0xf bank_mask:0xf
	v_mov_b32_dpp v175, v111 row_shl:1 row_mask:0xf bank_mask:0xf
	v_mov_b32_dpp v176, v112 row_shl:1 row_mask:0xf bank_mask:0xf
	v_mov_b32_dpp v177, v113 row_shl:1 row_mask:0xf bank_mask:0xf
	s_waitcnt vmcnt(19)
	v_pk_mul_f32 v[170:171], v[222:223], v[170:171]
	v_pk_mul_f32 v[172:173], v[224:225], v[172:173]
	s_waitcnt vmcnt(17)
	v_pk_mul_f32 v[174:175], v[230:231], v[174:175]
	v_pk_mul_f32 v[176:177], v[232:233], v[176:177]
	v_pk_fma_f32 v[164:165], v[110:111], v[226:227], v[170:171]
	v_pk_fma_f32 v[166:167], v[112:113], v[228:229], v[172:173]
	v_pk_add_f32 v[164:165], v[164:165], v[174:175]
	v_pk_add_f32 v[166:167], v[166:167], v[176:177]
	s_waitcnt vmcnt(16)
; __device__ __forceinline__ unsigned cvt_pk_bf16(float lo, float hi) { unsigned r; asm volatile("v_cvt_pk_bf16_f32 %0, %1, %2" : "=v"(r) : "v"(lo), "v"(hi)); return r; }
; __device__ __forceinline__ float sigmoidf_(float x) { return 1.0f / (1.0f + __expf(-x)); }
; __device__ __forceinline__ float dppf_prev(float cur, float below) { return __uint_as_float(dpp_prev(__float_as_uint(cur), __float_as_uint(below))); }
; __device__ __forceinline__ float dppf_next(float cur, float above) { return __uint_as_float(dpp_next(__float_as_uint(cur), __float_as_uint(above))); }
;     __device__ __forceinline__ void operator()(AccT& acc, const Unit& u, int wr, int wc, int fr, int fq) const {
;     ...
;             for (int ai = 0; ai < 2; ++ai) { const int grp = u.pm * 4 + ai * 2 + wr;
; #pragma unroll
;                 for (int bj = 0; bj < 2; ++bj) { const int mc = mc0 + bj * 128; const float mul = mc < 512 ? 0.08838834764831845f : 1.0f;
; #pragma unroll
;                     for (int n = 0; n < 2; ++n) {
;                         const f32x4 w0 = *(const f32x4*)(cw + mc + 4 * n), w1 = *(const f32x4*)(cw + 1024 + mc + 4 * n), w2 = *(const f32x4*)(cw + 2048 + mc + 4 * n), b = *(const f32x4*)(cb + mc + 4 * n);
; #pragma unroll
;                         for (int m = 0; m < 4; ++m) { const int lr = m * 16 + fr; const f32x4 gc = acc[ai][bj][m][n]; f32x4 o;
; #pragma unroll
;                             for (int j = 0; j < 4; ++j) { const float gp = dppf_prev(gc[j], m > 0 ? acc[ai][bj][m - 1][n][j] : 0.f), gn = dppf_next(gc[j], m < 3 ? acc[ai][bj][m + 1][n][j] : 0.f);
;                                 const float uu = gp * w0[j] + gc[j] * w1[j] + gn * w2[j] + b[j]; o[j] = uu * sigmoidf_(uu) * mul; }
;                             u32x2 w; w.x = cvt_pk_bf16(o[0], o[1]); w.y = cvt_pk_bf16(o[2], o[3]);
;                             *(u32x2*)(O + (size_t)(grp * 64 + lr) * NPROJ + col0 + bj * 128 + 4 * n) = w;
;                             if (m == 0 || m == 3) { if (lr < 2 || lr > 61) { u32x2 wg; wg.x = cvt_pk_bf16(gc[0], gc[1]); wg.y = cvt_pk_bf16(gc[2], gc[3]);
;                                 *(u32x2*)(HQ + (size_t)(grp * 4 + (lr < 2 ? lr : lr - 60)) * 1024 + mc + 4 * n) = wg; } } } } } }
	v_pk_add_f32 v[164:165], v[204:205], v[164:165]
	v_pk_add_f32 v[166:167], v[206:207], v[166:167]
	v_pk_mul_f32 v[178:179], v[164:165], s[4:5] op_sel_hi:[1,0]
	v_pk_mul_f32 v[184:185], v[166:167], s[4:5] op_sel_hi:[1,0]
	v_exp_f32_e32 v178, v178
	v_exp_f32_e32 v179, v179
	v_exp_f32_e32 v184, v184
	v_exp_f32_e32 v185, v185
	v_pk_add_f32 v[178:179], v[178:179], 1.0 op_sel_hi:[1,0]
	v_pk_add_f32 v[184:185], v[184:185], 1.0 op_sel_hi:[1,0]
	v_rcp_f32_e32 v180, v178
	v_rcp_f32_e32 v181, v179
	v_rcp_f32_e32 v192, v184
	v_rcp_f32_e32 v193, v185
	v_pk_fma_f32 v[182:183], v[178:179], v[180:181], 1.0 op_sel_hi:[1,1,0] neg_lo:[1,0,0] neg_hi:[1,0,0]
	v_pk_fma_f32 v[194:195], v[184:185], v[192:193], 1.0 op_sel_hi:[1,1,0] neg_lo:[1,0,0] neg_hi:[1,0,0]
	v_pk_fma_f32 v[180:181], v[182:183], v[180:181], v[180:181]
	v_pk_fma_f32 v[192:193], v[194:195], v[192:193], v[192:193]
	v_pk_mul_f32 v[164:165], v[164:165], v[180:181]
	v_pk_mul_f32 v[166:167], v[166:167], v[192:193]
	v_pk_mul_f32 v[164:165], v[0:1], v[164:165] op_sel_hi:[0,1]
	v_pk_mul_f32 v[166:167], v[0:1], v[166:167] op_sel_hi:[0,1]
	v_cvt_pk_bf16_f32 v196, v164, v165
	v_cvt_pk_bf16_f32 v197, v166, v167
	global_store_dwordx2 v[160:161], v[196:197], off offset:8
	v_lshl_add_u64 v[160:161], v[160:161], 0, s[68:69]
	s_add_i32 s2, s0, 0
	s_lshl_b32 s2, s2, 2
	s_lshl_b32 s2, s2, 11
	s_ashr_i32 s3, s2, 31
	s_add_u32 s70, s48, s2
	s_addc_u32 s71, s49, s3
	v_lshlrev_b32_e32 v200, 11, v190
	v_mov_b32_e32 v201, 0
	v_lshl_add_u64 v[200:201], v[200:201], 0, s[70:71]
	v_lshl_add_u64 v[200:201], v[158:159], 1, v[200:201]
	s_mov_b64 exec, s[42:43]
	v_cvt_pk_bf16_f32 v198, v110, v111
	v_cvt_pk_bf16_f32 v199, v112, v113
	global_store_dwordx2 v[200:201], v[198:199], off offset:-4088
	s_mov_b64 exec, -1
	v_mov_b32_dpp v170, v110 row_ror:1 row_mask:0xf bank_mask:0xf
	v_mov_b32_dpp v171, v111 row_ror:1 row_mask:0xf bank_mask:0xf
	v_mov_b32_dpp v172, v112 row_ror:1 row_mask:0xf bank_mask:0xf
	v_mov_b32_dpp v173, v113 row_ror:1 row_mask:0xf bank_mask:0xf
	v_mov_b32_dpp v174, v102 row_ror:15 row_mask:0xf bank_mask:0xf
	v_mov_b32_dpp v175, v103 row_ror:15 row_mask:0xf bank_mask:0xf
	v_mov_b32_dpp v176, v104 row_ror:15 row_mask:0xf bank_mask:0xf
	v_mov_b32_dpp v177, v105 row_ror:15 row_mask:0xf bank_mask:0xf
	v_mov_b32_dpp v170, v106 row_shr:1 row_mask:0xf bank_mask:0xf
	v_mov_b32_dpp v171, v107 row_shr:1 row_mask:0xf bank_mask:0xf
	v_mov_b32_dpp v172, v108 row_shr:1 row_mask:0xf bank_mask:0xf
	v_mov_b32_dpp v173, v109 row_shr:1 row_mask:0xf bank_mask:0xf
	v_mov_b32_dpp v174, v106 row_shl:1 row_mask:0xf bank_mask:0xf
	v_mov_b32_dpp v175, v107 row_shl:1 row_mask:0xf bank_mask:0xf
	v_mov_b32_dpp v176, v108 row_shl:1 row_mask:0xf bank_mask:0xf
	v_mov_b32_dpp v177, v109 row_shl:1 row_mask:0xf bank_mask:0xf
	v_pk_mul_f32 v[170:171], v[222:223], v[170:171]
	v_pk_mul_f32 v[172:173], v[224:225], v[172:173]
	v_pk_mul_f32 v[174:175], v[230:231], v[174:175]
	v_pk_mul_f32 v[176:177], v[232:233], v[176:177]
	v_pk_fma_f32 v[164:165], v[106:107], v[226:227], v[170:171]
	v_pk_fma_f32 v[166:167], v[108:109], v[228:229], v[172:173]
	v_pk_add_f32 v[164:165], v[164:165], v[174:175]
	v_pk_add_f32 v[166:167], v[166:167], v[176:177]
	v_pk_add_f32 v[164:165], v[204:205], v[164:165]
	v_pk_add_f32 v[166:167], v[206:207], v[166:167]
	v_pk_mul_f32 v[178:179], v[164:165], s[4:5] op_sel_hi:[1,0]
	v_pk_mul_f32 v[184:185], v[166:167], s[4:5] op_sel_hi:[1,0]
	v_exp_f32_e32 v178, v178
	v_exp_f32_e32 v179, v179
	v_exp_f32_e32 v184, v184
	v_exp_f32_e32 v185, v185
	v_pk_add_f32 v[178:179], v[178:179], 1.0 op_sel_hi:[1,0]
	v_pk_add_f32 v[184:185], v[184:185], 1.0 op_sel_hi:[1,0]
	v_rcp_f32_e32 v180, v178
	v_rcp_f32_e32 v181, v179
	v_rcp_f32_e32 v192, v184
	v_rcp_f32_e32 v193, v185
	v_pk_fma_f32 v[182:183], v[178:179], v[180:181], 1.0 op_sel_hi:[1,1,0] neg_lo:[1,0,0] neg_hi:[1,0,0]
	v_pk_fma_f32 v[194:195], v[184:185], v[192:193], 1.0 op_sel_hi:[1,1,0] neg_lo:[1,0,0] neg_hi:[1,0,0]
	v_pk_fma_f32 v[180:181], v[182:183], v[180:181], v[180:181]
	v_pk_fma_f32 v[192:193], v[194:195], v[192:193], v[192:193]
	v_pk_mul_f32 v[164:165], v[164:165], v[180:181]
	v_pk_mul_f32 v[166:167], v[166:167], v[192:193]
	v_pk_mul_f32 v[164:165], v[0:1], v[164:165] op_sel_hi:[0,1]
	v_pk_mul_f32 v[166:167], v[0:1], v[166:167] op_sel_hi:[0,1]
	v_cvt_pk_bf16_f32 v196, v164, v165
	v_cvt_pk_bf16_f32 v197, v166, v167
	global_store_dwordx2 v[160:161], v[196:197], off offset:8
	v_lshl_add_u64 v[160:161], v[160:161], 0, s[68:69]
	v_mov_b32_dpp v170, v106 row_ror:1 row_mask:0xf bank_mask:0xf
	v_mov_b32_dpp v171, v107 row_ror:1 row_mask:0xf bank_mask:0xf
	v_mov_b32_dpp v172, v108 row_ror:1 row_mask:0xf bank_mask:0xf
	v_mov_b32_dpp v173, v109 row_ror:1 row_mask:0xf bank_mask:0xf
	v_mov_b32_dpp v174, v98 row_ror:15 row_mask:0xf bank_mask:0xf
	v_mov_b32_dpp v175, v99 row_ror:15 row_mask:0xf bank_mask:0xf
	v_mov_b32_dpp v176, v100 row_ror:15 row_mask:0xf bank_mask:0xf
	v_mov_b32_dpp v177, v101 row_ror:15 row_mask:0xf bank_mask:0xf
	v_mov_b32_dpp v170, v102 row_shr:1 row_mask:0xf bank_mask:0xf
	v_mov_b32_dpp v171, v103 row_shr:1 row_mask:0xf bank_mask:0xf
	v_mov_b32_dpp v172, v104 row_shr:1 row_mask:0xf bank_mask:0xf
	v_mov_b32_dpp v173, v105 row_shr:1 row_mask:0xf bank_mask:0xf
	v_mov_b32_dpp v174, v102 row_shl:1 row_mask:0xf bank_mask:0xf
	v_mov_b32_dpp v175, v103 row_shl:1 row_mask:0xf bank_mask:0xf
	v_mov_b32_dpp v176, v104 row_shl:1 row_mask:0xf bank_mask:0xf
	v_mov_b32_dpp v177, v105 row_shl:1 row_mask:0xf bank_mask:0xf
	v_pk_mul_f32 v[170:171], v[222:223], v[170:171]
	v_pk_mul_f32 v[172:173], v[224:225], v[172:173]
	v_pk_mul_f32 v[174:175], v[230:231], v[174:175]
	v_pk_mul_f32 v[176:177], v[232:233], v[176:177]
; __device__ __forceinline__ unsigned cvt_pk_bf16(float lo, float hi) { unsigned r; asm volatile("v_cvt_pk_bf16_f32 %0, %1, %2" : "=v"(r) : "v"(lo), "v"(hi)); return r; }
; __device__ __forceinline__ float sigmoidf_(float x) { return 1.0f / (1.0f + __expf(-x)); }
; __device__ __forceinline__ float dppf_prev(float cur, float below) { return __uint_as_float(dpp_prev(__float_as_uint(cur), __float_as_uint(below))); }
; __device__ __forceinline__ float dppf_next(float cur, float above) { return __uint_as_float(dpp_next(__float_as_uint(cur), __float_as_uint(above))); }
;     __device__ __forceinline__ void operator()(AccT& acc, const Unit& u, int wr, int wc, int fr, int fq) const {
;     ...
;             for (int ai = 0; ai < 2; ++ai) { const int grp = u.pm * 4 + ai * 2 + wr;
; #pragma unroll
;                 for (int bj = 0; bj < 2; ++bj) { const int mc = mc0 + bj * 128; const float mul = mc < 512 ? 0.08838834764831845f : 1.0f;
; #pragma unroll
;                     for (int n = 0; n < 2; ++n) {
;                         const f32x4 w0 = *(const f32x4*)(cw + mc + 4 * n), w1 = *(const f32x4*)(cw + 1024 + mc + 4 * n), w2 = *(const f32x4*)(cw + 2048 + mc + 4 * n), b = *(const f32x4*)(cb + mc + 4 * n);
; #pragma unroll
;                         for (int m = 0; m < 4; ++m) { const int lr = m * 16 + fr; const f32x4 gc = acc[ai][bj][m][n]; f32x4 o;
; #pragma unroll
;                             for (int j = 0; j < 4; ++j) { const float gp = dppf_prev(gc[j], m > 0 ? acc[ai][bj][m - 1][n][j] : 0.f), gn = dppf_next(gc[j], m < 3 ? acc[ai][bj][m + 1][n][j] : 0.f);
;                                 const float uu = gp * w0[j] + gc[j] * w1[j] + gn * w2[j] + b[j]; o[j] = uu * sigmoidf_(uu) * mul; }
;                             u32x2 w; w.x = cvt_pk_bf16(o[0], o[1]); w.y = cvt_pk_bf16(o[2], o[3]);
;                             *(u32x2*)(O + (size_t)(grp * 64 + lr) * NPROJ + col0 + bj * 128 + 4 * n) = w;
;                             if (m == 0 || m == 3) { if (lr < 2 || lr > 61) { u32x2 wg; wg.x = cvt_pk_bf16(gc[0], gc[1]); wg.y = cvt_pk_bf16(gc[2], gc[3]);
;                                 *(u32x2*)(HQ + (size_t)(grp * 4 + (lr < 2 ? lr : lr - 60)) * 1024 + mc + 4 * n) = wg; } } } } } }
	v_pk_fma_f32 v[164:165], v[102:103], v[226:227], v[170:171]
	v_pk_fma_f32 v[166:167], v[104:105], v[228:229], v[172:173]
	v_pk_add_f32 v[164:165], v[164:165], v[174:175]
	v_pk_add_f32 v[166:167], v[166:167], v[176:177]
	v_pk_add_f32 v[164:165], v[204:205], v[164:165]
	v_pk_add_f32 v[166:167], v[206:207], v[166:167]
	v_pk_mul_f32 v[178:179], v[164:165], s[4:5] op_sel_hi:[1,0]
	v_pk_mul_f32 v[184:185], v[166:167], s[4:5] op_sel_hi:[1,0]
	v_exp_f32_e32 v178, v178
	v_exp_f32_e32 v179, v179
	v_exp_f32_e32 v184, v184
	v_exp_f32_e32 v185, v185
	v_pk_add_f32 v[178:179], v[178:179], 1.0 op_sel_hi:[1,0]
	v_pk_add_f32 v[184:185], v[184:185], 1.0 op_sel_hi:[1,0]
	v_rcp_f32_e32 v180, v178
	v_rcp_f32_e32 v181, v179
	v_rcp_f32_e32 v192, v184
	v_rcp_f32_e32 v193, v185
	v_pk_fma_f32 v[182:183], v[178:179], v[180:181], 1.0 op_sel_hi:[1,1,0] neg_lo:[1,0,0] neg_hi:[1,0,0]
	v_pk_fma_f32 v[194:195], v[184:185], v[192:193], 1.0 op_sel_hi:[1,1,0] neg_lo:[1,0,0] neg_hi:[1,0,0]
	v_pk_fma_f32 v[180:181], v[182:183], v[180:181], v[180:181]
	v_pk_fma_f32 v[192:193], v[194:195], v[192:193], v[192:193]
	v_pk_mul_f32 v[164:165], v[164:165], v[180:181]
	v_pk_mul_f32 v[166:167], v[166:167], v[192:193]
	v_pk_mul_f32 v[164:165], v[0:1], v[164:165] op_sel_hi:[0,1]
	v_pk_mul_f32 v[166:167], v[0:1], v[166:167] op_sel_hi:[0,1]
	v_cvt_pk_bf16_f32 v196, v164, v165
	v_cvt_pk_bf16_f32 v197, v166, v167
	global_store_dwordx2 v[160:161], v[196:197], off offset:8
	v_lshl_add_u64 v[160:161], v[160:161], 0, s[68:69]
	v_mov_b32_dpp v170, v102 row_ror:1 row_mask:0xf bank_mask:0xf
	v_mov_b32_dpp v171, v103 row_ror:1 row_mask:0xf bank_mask:0xf
	v_mov_b32_dpp v172, v104 row_ror:1 row_mask:0xf bank_mask:0xf
	v_mov_b32_dpp v173, v105 row_ror:1 row_mask:0xf bank_mask:0xf
	v_mov_b32_e32 v174, 0
	v_mov_b32_e32 v175, 0
	v_mov_b32_e32 v176, 0
	v_mov_b32_e32 v177, 0
	v_mov_b32_dpp v170, v98 row_shr:1 row_mask:0xf bank_mask:0xf
	v_mov_b32_dpp v171, v99 row_shr:1 row_mask:0xf bank_mask:0xf
	v_mov_b32_dpp v172, v100 row_shr:1 row_mask:0xf bank_mask:0xf
	v_mov_b32_dpp v173, v101 row_shr:1 row_mask:0xf bank_mask:0xf
	v_mov_b32_dpp v174, v98 row_shl:1 row_mask:0xf bank_mask:0xf
	v_mov_b32_dpp v175, v99 row_shl:1 row_mask:0xf bank_mask:0xf
	v_mov_b32_dpp v176, v100 row_shl:1 row_mask:0xf bank_mask:0xf
	v_mov_b32_dpp v177, v101 row_shl:1 row_mask:0xf bank_mask:0xf
	v_pk_mul_f32 v[170:171], v[222:223], v[170:171]
	v_pk_mul_f32 v[172:173], v[224:225], v[172:173]
	v_pk_mul_f32 v[174:175], v[230:231], v[174:175]
	v_pk_mul_f32 v[176:177], v[232:233], v[176:177]
	v_pk_fma_f32 v[164:165], v[98:99], v[226:227], v[170:171]
	v_pk_fma_f32 v[166:167], v[100:101], v[228:229], v[172:173]
	v_pk_add_f32 v[164:165], v[164:165], v[174:175]
	v_pk_add_f32 v[166:167], v[166:167], v[176:177]
	v_pk_add_f32 v[164:165], v[204:205], v[164:165]
	v_pk_add_f32 v[166:167], v[206:207], v[166:167]
	v_pk_mul_f32 v[178:179], v[164:165], s[4:5] op_sel_hi:[1,0]
	v_pk_mul_f32 v[184:185], v[166:167], s[4:5] op_sel_hi:[1,0]
	v_exp_f32_e32 v178, v178
	v_exp_f32_e32 v179, v179
	v_exp_f32_e32 v184, v184
	v_exp_f32_e32 v185, v185
	v_pk_add_f32 v[178:179], v[178:179], 1.0 op_sel_hi:[1,0]
	v_pk_add_f32 v[184:185], v[184:185], 1.0 op_sel_hi:[1,0]
	v_rcp_f32_e32 v180, v178
	v_rcp_f32_e32 v181, v179
	v_rcp_f32_e32 v192, v184
	v_rcp_f32_e32 v193, v185
	v_pk_fma_f32 v[182:183], v[178:179], v[180:181], 1.0 op_sel_hi:[1,1,0] neg_lo:[1,0,0] neg_hi:[1,0,0]
	v_pk_fma_f32 v[194:195], v[184:185], v[192:193], 1.0 op_sel_hi:[1,1,0] neg_lo:[1,0,0] neg_hi:[1,0,0]
	v_pk_fma_f32 v[180:181], v[182:183], v[180:181], v[180:181]
	v_pk_fma_f32 v[192:193], v[194:195], v[192:193], v[192:193]
	v_pk_mul_f32 v[164:165], v[164:165], v[180:181]
	v_pk_mul_f32 v[166:167], v[166:167], v[192:193]
	v_pk_mul_f32 v[164:165], v[0:1], v[164:165] op_sel_hi:[0,1]
	v_pk_mul_f32 v[166:167], v[0:1], v[166:167] op_sel_hi:[0,1]
	v_cvt_pk_bf16_f32 v196, v164, v165
	v_cvt_pk_bf16_f32 v197, v166, v167
	global_store_dwordx2 v[160:161], v[196:197], off offset:8
	s_add_i32 s2, s0, 0
	s_lshl_b32 s2, s2, 2
	s_add_i32 s2, s2, -12
	s_lshl_b32 s2, s2, 11
	s_ashr_i32 s3, s2, 31
	s_add_u32 s70, s48, s2
	s_addc_u32 s71, s49, s3
	v_lshlrev_b32_e32 v200, 11, v190
	v_mov_b32_e32 v201, 0
	v_lshl_add_u64 v[200:201], v[200:201], 0, s[70:71]
	v_lshl_add_u64 v[200:201], v[158:159], 1, v[200:201]
	s_mov_b64 exec, s[44:45]
	v_cvt_pk_bf16_f32 v198, v98, v99
	v_cvt_pk_bf16_f32 v199, v100, v101
	global_store_dwordx2 v[200:201], v[198:199], off offset:-4088
	s_mov_b64 exec, -1
	s_add_i32 s2, s0, 2
	s_lshl_b32 s3, s2, 19
	s_add_u32 s70, s22, s3
	s_addc_u32 s71, s23, 0
	v_lshlrev_b32_e32 v200, 13, v190
	v_mov_b32_e32 v201, 0
	v_lshl_add_u64 v[160:161], v[200:201], 0, s[70:71]
	v_lshl_add_u64 v[160:161], v[158:159], 1, v[160:161]
	v_mov_b32_e32 v170, 0
	v_mov_b32_e32 v171, 0
	v_mov_b32_e32 v172, 0
	v_mov_b32_e32 v173, 0
	v_mov_b32_dpp v174, v42 row_ror:15 row_mask:0xf bank_mask:0xf
	v_mov_b32_dpp v175, v43 row_ror:15 row_mask:0xf bank_mask:0xf
	v_mov_b32_dpp v176, v44 row_ror:15 row_mask:0xf bank_mask:0xf
	v_mov_b32_dpp v177, v45 row_ror:15 row_mask:0xf bank_mask:0xf
	v_mov_b32_dpp v170, v46 row_shr:1 row_mask:0xf bank_mask:0xf
	v_mov_b32_dpp v171, v47 row_shr:1 row_mask:0xf bank_mask:0xf
	v_mov_b32_dpp v172, v48 row_shr:1 row_mask:0xf bank_mask:0xf
	v_mov_b32_dpp v173, v49 row_shr:1 row_mask:0xf bank_mask:0xf
	v_mov_b32_dpp v174, v46 row_shl:1 row_mask:0xf bank_mask:0xf
	v_mov_b32_dpp v175, v47 row_shl:1 row_mask:0xf bank_mask:0xf
	v_mov_b32_dpp v176, v48 row_shl:1 row_mask:0xf bank_mask:0xf
	v_mov_b32_dpp v177, v49 row_shl:1 row_mask:0xf bank_mask:0xf
	v_pk_mul_f32 v[170:171], v[222:223], v[170:171]
; __device__ __forceinline__ unsigned cvt_pk_bf16(float lo, float hi) { unsigned r; asm volatile("v_cvt_pk_bf16_f32 %0, %1, %2" : "=v"(r) : "v"(lo), "v"(hi)); return r; }
; __device__ __forceinline__ float sigmoidf_(float x) { return 1.0f / (1.0f + __expf(-x)); }
; __device__ __forceinline__ float dppf_prev(float cur, float below) { return __uint_as_float(dpp_prev(__float_as_uint(cur), __float_as_uint(below))); }
; __device__ __forceinline__ float dppf_next(float cur, float above) { return __uint_as_float(dpp_next(__float_as_uint(cur), __float_as_uint(above))); }
;     __device__ __forceinline__ void operator()(AccT& acc, const Unit& u, int wr, int wc, int fr, int fq) const {
;     ...
;             for (int ai = 0; ai < 2; ++ai) { const int grp = u.pm * 4 + ai * 2 + wr;
; #pragma unroll
;                 for (int bj = 0; bj < 2; ++bj) { const int mc = mc0 + bj * 128; const float mul = mc < 512 ? 0.08838834764831845f : 1.0f;
; #pragma unroll
;                     for (int n = 0; n < 2; ++n) {
;                         const f32x4 w0 = *(const f32x4*)(cw + mc + 4 * n), w1 = *(const f32x4*)(cw + 1024 + mc + 4 * n), w2 = *(const f32x4*)(cw + 2048 + mc + 4 * n), b = *(const f32x4*)(cb + mc + 4 * n);
; #pragma unroll
;                         for (int m = 0; m < 4; ++m) { const int lr = m * 16 + fr; const f32x4 gc = acc[ai][bj][m][n]; f32x4 o;
; #pragma unroll
;                             for (int j = 0; j < 4; ++j) { const float gp = dppf_prev(gc[j], m > 0 ? acc[ai][bj][m - 1][n][j] : 0.f), gn = dppf_next(gc[j], m < 3 ? acc[ai][bj][m + 1][n][j] : 0.f);
;                                 const float uu = gp * w0[j] + gc[j] * w1[j] + gn * w2[j] + b[j]; o[j] = uu * sigmoidf_(uu) * mul; }
;                             u32x2 w; w.x = cvt_pk_bf16(o[0], o[1]); w.y = cvt_pk_bf16(o[2], o[3]);
;                             *(u32x2*)(O + (size_t)(grp * 64 + lr) * NPROJ + col0 + bj * 128 + 4 * n) = w;
;                             if (m == 0 || m == 3) { if (lr < 2 || lr > 61) { u32x2 wg; wg.x = cvt_pk_bf16(gc[0], gc[1]); wg.y = cvt_pk_bf16(gc[2], gc[3]);
;                                 *(u32x2*)(HQ + (size_t)(grp * 4 + (lr < 2 ? lr : lr - 60)) * 1024 + mc + 4 * n) = wg; } } } } } }
	v_pk_mul_f32 v[172:173], v[224:225], v[172:173]
	v_pk_mul_f32 v[174:175], v[230:231], v[174:175]
	v_pk_mul_f32 v[176:177], v[232:233], v[176:177]
	v_pk_fma_f32 v[164:165], v[46:47], v[226:227], v[170:171]
	v_pk_fma_f32 v[166:167], v[48:49], v[228:229], v[172:173]
	v_pk_add_f32 v[164:165], v[164:165], v[174:175]
	v_pk_add_f32 v[166:167], v[166:167], v[176:177]
	v_pk_add_f32 v[164:165], v[204:205], v[164:165]
	v_pk_add_f32 v[166:167], v[206:207], v[166:167]
	v_pk_mul_f32 v[178:179], v[164:165], s[4:5] op_sel_hi:[1,0]
	v_pk_mul_f32 v[184:185], v[166:167], s[4:5] op_sel_hi:[1,0]
	v_exp_f32_e32 v178, v178
	v_exp_f32_e32 v179, v179
	v_exp_f32_e32 v184, v184
	v_exp_f32_e32 v185, v185
	v_pk_add_f32 v[178:179], v[178:179], 1.0 op_sel_hi:[1,0]
	v_pk_add_f32 v[184:185], v[184:185], 1.0 op_sel_hi:[1,0]
	v_rcp_f32_e32 v180, v178
	v_rcp_f32_e32 v181, v179
	v_rcp_f32_e32 v192, v184
	v_rcp_f32_e32 v193, v185
	v_pk_fma_f32 v[182:183], v[178:179], v[180:181], 1.0 op_sel_hi:[1,1,0] neg_lo:[1,0,0] neg_hi:[1,0,0]
	v_pk_fma_f32 v[194:195], v[184:185], v[192:193], 1.0 op_sel_hi:[1,1,0] neg_lo:[1,0,0] neg_hi:[1,0,0]
	v_pk_fma_f32 v[180:181], v[182:183], v[180:181], v[180:181]
	v_pk_fma_f32 v[192:193], v[194:195], v[192:193], v[192:193]
	v_pk_mul_f32 v[164:165], v[164:165], v[180:181]
	v_pk_mul_f32 v[166:167], v[166:167], v[192:193]
	v_pk_mul_f32 v[164:165], v[0:1], v[164:165] op_sel_hi:[0,1]
	v_pk_mul_f32 v[166:167], v[0:1], v[166:167] op_sel_hi:[0,1]
	v_cvt_pk_bf16_f32 v196, v164, v165
	v_cvt_pk_bf16_f32 v197, v166, v167
	global_store_dwordx2 v[160:161], v[196:197], off offset:8
	v_lshl_add_u64 v[160:161], v[160:161], 0, s[68:69]
	s_add_i32 s2, s0, 2
	s_lshl_b32 s2, s2, 2
	s_lshl_b32 s2, s2, 11
	s_ashr_i32 s3, s2, 31
	s_add_u32 s70, s48, s2
	s_addc_u32 s71, s49, s3
	v_lshlrev_b32_e32 v200, 11, v190
	v_mov_b32_e32 v201, 0
	v_lshl_add_u64 v[200:201], v[200:201], 0, s[70:71]
	v_lshl_add_u64 v[200:201], v[158:159], 1, v[200:201]
	s_mov_b64 exec, s[42:43]
	v_cvt_pk_bf16_f32 v198, v46, v47
	v_cvt_pk_bf16_f32 v199, v48, v49
	global_store_dwordx2 v[200:201], v[198:199], off offset:-4088
	s_mov_b64 exec, -1
	v_mov_b32_dpp v170, v46 row_ror:1 row_mask:0xf bank_mask:0xf
	v_mov_b32_dpp v171, v47 row_ror:1 row_mask:0xf bank_mask:0xf
	v_mov_b32_dpp v172, v48 row_ror:1 row_mask:0xf bank_mask:0xf
	v_mov_b32_dpp v173, v49 row_ror:1 row_mask:0xf bank_mask:0xf
	v_mov_b32_dpp v174, v38 row_ror:15 row_mask:0xf bank_mask:0xf
	v_mov_b32_dpp v175, v39 row_ror:15 row_mask:0xf bank_mask:0xf
	v_mov_b32_dpp v176, v40 row_ror:15 row_mask:0xf bank_mask:0xf
	v_mov_b32_dpp v177, v41 row_ror:15 row_mask:0xf bank_mask:0xf
	v_mov_b32_dpp v170, v42 row_shr:1 row_mask:0xf bank_mask:0xf
	v_mov_b32_dpp v171, v43 row_shr:1 row_mask:0xf bank_mask:0xf
	v_mov_b32_dpp v172, v44 row_shr:1 row_mask:0xf bank_mask:0xf
	v_mov_b32_dpp v173, v45 row_shr:1 row_mask:0xf bank_mask:0xf
	v_mov_b32_dpp v174, v42 row_shl:1 row_mask:0xf bank_mask:0xf
	v_mov_b32_dpp v175, v43 row_shl:1 row_mask:0xf bank_mask:0xf
	v_mov_b32_dpp v176, v44 row_shl:1 row_mask:0xf bank_mask:0xf
	v_mov_b32_dpp v177, v45 row_shl:1 row_mask:0xf bank_mask:0xf
	v_pk_mul_f32 v[170:171], v[222:223], v[170:171]
	v_pk_mul_f32 v[172:173], v[224:225], v[172:173]
	v_pk_mul_f32 v[174:175], v[230:231], v[174:175]
	v_pk_mul_f32 v[176:177], v[232:233], v[176:177]
	v_pk_fma_f32 v[164:165], v[42:43], v[226:227], v[170:171]
	v_pk_fma_f32 v[166:167], v[44:45], v[228:229], v[172:173]
	v_pk_add_f32 v[164:165], v[164:165], v[174:175]
	v_pk_add_f32 v[166:167], v[166:167], v[176:177]
	v_pk_add_f32 v[164:165], v[204:205], v[164:165]
	v_pk_add_f32 v[166:167], v[206:207], v[166:167]
	v_pk_mul_f32 v[178:179], v[164:165], s[4:5] op_sel_hi:[1,0]
	v_pk_mul_f32 v[184:185], v[166:167], s[4:5] op_sel_hi:[1,0]
	v_exp_f32_e32 v178, v178
	v_exp_f32_e32 v179, v179
	v_exp_f32_e32 v184, v184
	v_exp_f32_e32 v185, v185
	v_pk_add_f32 v[178:179], v[178:179], 1.0 op_sel_hi:[1,0]
	v_pk_add_f32 v[184:185], v[184:185], 1.0 op_sel_hi:[1,0]
	v_rcp_f32_e32 v180, v178
	v_rcp_f32_e32 v181, v179
	v_rcp_f32_e32 v192, v184
	v_rcp_f32_e32 v193, v185
	v_pk_fma_f32 v[182:183], v[178:179], v[180:181], 1.0 op_sel_hi:[1,1,0] neg_lo:[1,0,0] neg_hi:[1,0,0]
	v_pk_fma_f32 v[194:195], v[184:185], v[192:193], 1.0 op_sel_hi:[1,1,0] neg_lo:[1,0,0] neg_hi:[1,0,0]
	v_pk_fma_f32 v[180:181], v[182:183], v[180:181], v[180:181]
	v_pk_fma_f32 v[192:193], v[194:195], v[192:193], v[192:193]
	v_pk_mul_f32 v[164:165], v[164:165], v[180:181]
	v_pk_mul_f32 v[166:167], v[166:167], v[192:193]
	v_pk_mul_f32 v[164:165], v[0:1], v[164:165] op_sel_hi:[0,1]
	v_pk_mul_f32 v[166:167], v[0:1], v[166:167] op_sel_hi:[0,1]
	v_cvt_pk_bf16_f32 v196, v164, v165
	v_cvt_pk_bf16_f32 v197, v166, v167
	global_store_dwordx2 v[160:161], v[196:197], off offset:8
	v_lshl_add_u64 v[160:161], v[160:161], 0, s[68:69]
	v_mov_b32_dpp v170, v42 row_ror:1 row_mask:0xf bank_mask:0xf
	v_mov_b32_dpp v171, v43 row_ror:1 row_mask:0xf bank_mask:0xf
	v_mov_b32_dpp v172, v44 row_ror:1 row_mask:0xf bank_mask:0xf
	v_mov_b32_dpp v173, v45 row_ror:1 row_mask:0xf bank_mask:0xf
	v_mov_b32_dpp v174, v34 row_ror:15 row_mask:0xf bank_mask:0xf
	v_mov_b32_dpp v175, v35 row_ror:15 row_mask:0xf bank_mask:0xf
	v_mov_b32_dpp v176, v36 row_ror:15 row_mask:0xf bank_mask:0xf
	v_mov_b32_dpp v177, v37 row_ror:15 row_mask:0xf bank_mask:0xf
	v_mov_b32_dpp v170, v38 row_shr:1 row_mask:0xf bank_mask:0xf
	v_mov_b32_dpp v171, v39 row_shr:1 row_mask:0xf bank_mask:0xf
	v_mov_b32_dpp v172, v40 row_shr:1 row_mask:0xf bank_mask:0xf
	v_mov_b32_dpp v173, v41 row_shr:1 row_mask:0xf bank_mask:0xf
	v_mov_b32_dpp v174, v38 row_shl:1 row_mask:0xf bank_mask:0xf
	v_mov_b32_dpp v175, v39 row_shl:1 row_mask:0xf bank_mask:0xf
; __device__ __forceinline__ unsigned cvt_pk_bf16(float lo, float hi) { unsigned r; asm volatile("v_cvt_pk_bf16_f32 %0, %1, %2" : "=v"(r) : "v"(lo), "v"(hi)); return r; }
; __device__ __forceinline__ float sigmoidf_(float x) { return 1.0f / (1.0f + __expf(-x)); }
; __device__ __forceinline__ float dppf_prev(float cur, float below) { return __uint_as_float(dpp_prev(__float_as_uint(cur), __float_as_uint(below))); }
; __device__ __forceinline__ float dppf_next(float cur, float above) { return __uint_as_float(dpp_next(__float_as_uint(cur), __float_as_uint(above))); }
;     __device__ __forceinline__ void operator()(AccT& acc, const Unit& u, int wr, int wc, int fr, int fq) const {
;     ...
;             for (int ai = 0; ai < 2; ++ai) { const int grp = u.pm * 4 + ai * 2 + wr;
; #pragma unroll
;                 for (int bj = 0; bj < 2; ++bj) { const int mc = mc0 + bj * 128; const float mul = mc < 512 ? 0.08838834764831845f : 1.0f;
; #pragma unroll
;                     for (int n = 0; n < 2; ++n) {
;                         const f32x4 w0 = *(const f32x4*)(cw + mc + 4 * n), w1 = *(const f32x4*)(cw + 1024 + mc + 4 * n), w2 = *(const f32x4*)(cw + 2048 + mc + 4 * n), b = *(const f32x4*)(cb + mc + 4 * n);
; #pragma unroll
;                         for (int m = 0; m < 4; ++m) { const int lr = m * 16 + fr; const f32x4 gc = acc[ai][bj][m][n]; f32x4 o;
; #pragma unroll
;                             for (int j = 0; j < 4; ++j) { const float gp = dppf_prev(gc[j], m > 0 ? acc[ai][bj][m - 1][n][j] : 0.f), gn = dppf_next(gc[j], m < 3 ? acc[ai][bj][m + 1][n][j] : 0.f);
;                                 const float uu = gp * w0[j] + gc[j] * w1[j] + gn * w2[j] + b[j]; o[j] = uu * sigmoidf_(uu) * mul; }
;                             u32x2 w; w.x = cvt_pk_bf16(o[0], o[1]); w.y = cvt_pk_bf16(o[2], o[3]);
;                             *(u32x2*)(O + (size_t)(grp * 64 + lr) * NPROJ + col0 + bj * 128 + 4 * n) = w;
;                             if (m == 0 || m == 3) { if (lr < 2 || lr > 61) { u32x2 wg; wg.x = cvt_pk_bf16(gc[0], gc[1]); wg.y = cvt_pk_bf16(gc[2], gc[3]);
;                                 *(u32x2*)(HQ + (size_t)(grp * 4 + (lr < 2 ? lr : lr - 60)) * 1024 + mc + 4 * n) = wg; } } } } } }
	v_mov_b32_dpp v176, v40 row_shl:1 row_mask:0xf bank_mask:0xf
	v_mov_b32_dpp v177, v41 row_shl:1 row_mask:0xf bank_mask:0xf
	v_pk_mul_f32 v[170:171], v[222:223], v[170:171]
	v_pk_mul_f32 v[172:173], v[224:225], v[172:173]
	v_pk_mul_f32 v[174:175], v[230:231], v[174:175]
	v_pk_mul_f32 v[176:177], v[232:233], v[176:177]
	v_pk_fma_f32 v[164:165], v[38:39], v[226:227], v[170:171]
	v_pk_fma_f32 v[166:167], v[40:41], v[228:229], v[172:173]
	v_pk_add_f32 v[164:165], v[164:165], v[174:175]
	v_pk_add_f32 v[166:167], v[166:167], v[176:177]
	v_pk_add_f32 v[164:165], v[204:205], v[164:165]
	v_pk_add_f32 v[166:167], v[206:207], v[166:167]
	v_pk_mul_f32 v[178:179], v[164:165], s[4:5] op_sel_hi:[1,0]
	v_pk_mul_f32 v[184:185], v[166:167], s[4:5] op_sel_hi:[1,0]
	v_exp_f32_e32 v178, v178
	v_exp_f32_e32 v179, v179
	v_exp_f32_e32 v184, v184
	v_exp_f32_e32 v185, v185
	v_pk_add_f32 v[178:179], v[178:179], 1.0 op_sel_hi:[1,0]
	v_pk_add_f32 v[184:185], v[184:185], 1.0 op_sel_hi:[1,0]
	v_rcp_f32_e32 v180, v178
	v_rcp_f32_e32 v181, v179
	v_rcp_f32_e32 v192, v184
	v_rcp_f32_e32 v193, v185
	v_pk_fma_f32 v[182:183], v[178:179], v[180:181], 1.0 op_sel_hi:[1,1,0] neg_lo:[1,0,0] neg_hi:[1,0,0]
	v_pk_fma_f32 v[194:195], v[184:185], v[192:193], 1.0 op_sel_hi:[1,1,0] neg_lo:[1,0,0] neg_hi:[1,0,0]
	v_pk_fma_f32 v[180:181], v[182:183], v[180:181], v[180:181]
	v_pk_fma_f32 v[192:193], v[194:195], v[192:193], v[192:193]
	v_pk_mul_f32 v[164:165], v[164:165], v[180:181]
	v_pk_mul_f32 v[166:167], v[166:167], v[192:193]
	v_pk_mul_f32 v[164:165], v[0:1], v[164:165] op_sel_hi:[0,1]
	v_pk_mul_f32 v[166:167], v[0:1], v[166:167] op_sel_hi:[0,1]
	v_cvt_pk_bf16_f32 v196, v164, v165
	v_cvt_pk_bf16_f32 v197, v166, v167
	global_store_dwordx2 v[160:161], v[196:197], off offset:8
	v_lshl_add_u64 v[160:161], v[160:161], 0, s[68:69]
	v_mov_b32_dpp v170, v38 row_ror:1 row_mask:0xf bank_mask:0xf
	v_mov_b32_dpp v171, v39 row_ror:1 row_mask:0xf bank_mask:0xf
	v_mov_b32_dpp v172, v40 row_ror:1 row_mask:0xf bank_mask:0xf
	v_mov_b32_dpp v173, v41 row_ror:1 row_mask:0xf bank_mask:0xf
	v_mov_b32_e32 v174, 0
	v_mov_b32_e32 v175, 0
	v_mov_b32_e32 v176, 0
	v_mov_b32_e32 v177, 0
	v_mov_b32_dpp v170, v34 row_shr:1 row_mask:0xf bank_mask:0xf
	v_mov_b32_dpp v171, v35 row_shr:1 row_mask:0xf bank_mask:0xf
	v_mov_b32_dpp v172, v36 row_shr:1 row_mask:0xf bank_mask:0xf
	v_mov_b32_dpp v173, v37 row_shr:1 row_mask:0xf bank_mask:0xf
	v_mov_b32_dpp v174, v34 row_shl:1 row_mask:0xf bank_mask:0xf
	v_mov_b32_dpp v175, v35 row_shl:1 row_mask:0xf bank_mask:0xf
	v_mov_b32_dpp v176, v36 row_shl:1 row_mask:0xf bank_mask:0xf
	v_mov_b32_dpp v177, v37 row_shl:1 row_mask:0xf bank_mask:0xf
	v_pk_mul_f32 v[170:171], v[222:223], v[170:171]
	v_pk_mul_f32 v[172:173], v[224:225], v[172:173]
	v_pk_mul_f32 v[174:175], v[230:231], v[174:175]
	v_pk_mul_f32 v[176:177], v[232:233], v[176:177]
	v_pk_fma_f32 v[164:165], v[34:35], v[226:227], v[170:171]
	v_pk_fma_f32 v[166:167], v[36:37], v[228:229], v[172:173]
	v_pk_add_f32 v[164:165], v[164:165], v[174:175]
	v_pk_add_f32 v[166:167], v[166:167], v[176:177]
	v_pk_add_f32 v[164:165], v[204:205], v[164:165]
	v_pk_add_f32 v[166:167], v[206:207], v[166:167]
	v_pk_mul_f32 v[178:179], v[164:165], s[4:5] op_sel_hi:[1,0]
	v_pk_mul_f32 v[184:185], v[166:167], s[4:5] op_sel_hi:[1,0]
	v_exp_f32_e32 v178, v178
	v_exp_f32_e32 v179, v179
	v_exp_f32_e32 v184, v184
	v_exp_f32_e32 v185, v185
	v_pk_add_f32 v[178:179], v[178:179], 1.0 op_sel_hi:[1,0]
	v_pk_add_f32 v[184:185], v[184:185], 1.0 op_sel_hi:[1,0]
	v_rcp_f32_e32 v180, v178
	v_rcp_f32_e32 v181, v179
	v_rcp_f32_e32 v192, v184
	v_rcp_f32_e32 v193, v185
	v_pk_fma_f32 v[182:183], v[178:179], v[180:181], 1.0 op_sel_hi:[1,1,0] neg_lo:[1,0,0] neg_hi:[1,0,0]
	v_pk_fma_f32 v[194:195], v[184:185], v[192:193], 1.0 op_sel_hi:[1,1,0] neg_lo:[1,0,0] neg_hi:[1,0,0]
	v_pk_fma_f32 v[180:181], v[182:183], v[180:181], v[180:181]
	v_pk_fma_f32 v[192:193], v[194:195], v[192:193], v[192:193]
	v_pk_mul_f32 v[164:165], v[164:165], v[180:181]
	v_pk_mul_f32 v[166:167], v[166:167], v[192:193]
	v_pk_mul_f32 v[164:165], v[0:1], v[164:165] op_sel_hi:[0,1]
	v_pk_mul_f32 v[166:167], v[0:1], v[166:167] op_sel_hi:[0,1]
	v_cvt_pk_bf16_f32 v196, v164, v165
	v_cvt_pk_bf16_f32 v197, v166, v167
	global_store_dwordx2 v[160:161], v[196:197], off offset:8
	s_add_i32 s2, s0, 2
	s_lshl_b32 s2, s2, 2
	s_add_i32 s2, s2, -12
	s_lshl_b32 s2, s2, 11
	s_ashr_i32 s3, s2, 31
	s_add_u32 s70, s48, s2
	s_addc_u32 s71, s49, s3
	v_lshlrev_b32_e32 v200, 11, v190
	v_mov_b32_e32 v201, 0
	v_lshl_add_u64 v[200:201], v[200:201], 0, s[70:71]
	v_lshl_add_u64 v[200:201], v[158:159], 1, v[200:201]
	s_mov_b64 exec, s[44:45]
	v_cvt_pk_bf16_f32 v198, v34, v35
	v_cvt_pk_bf16_f32 v199, v36, v37
	global_store_dwordx2 v[200:201], v[198:199], off offset:-4088
	s_mov_b64 exec, -1
	s_add_u32 s60, s72, 0xffffe210
	s_addc_u32 s61, s73, -1
	s_add_u32 s62, s72, 0xfffff210
	s_addc_u32 s63, s73, -1
	s_add_u32 s64, s72, 0x210
	s_addc_u32 s65, s73, 0
	s_add_u32 s66, s74, 0xffffe210
	s_addc_u32 s67, s75, -1
	v_lshl_add_u64 v[200:201], v[158:159], 2, s[60:61]
	v_lshl_add_u64 v[198:199], v[158:159], 2, s[62:63]
	global_load_dwordx4 v[222:225], v[200:201], off
	global_load_dwordx4 v[226:229], v[198:199], off
	v_lshl_add_u64 v[200:201], v[158:159], 2, s[64:65]
	v_lshl_add_u64 v[198:199], v[158:159], 2, s[66:67]
	global_load_dwordx4 v[230:233], v[200:201], off
	global_load_dwordx4 v[204:207], v[198:199], off
	s_add_i32 s2, s0, 0
	s_lshl_b32 s3, s2, 19
	s_add_u32 s70, s22, s3
	s_addc_u32 s71, s23, 0
	v_lshlrev_b32_e32 v200, 13, v190
	v_mov_b32_e32 v201, 0
	v_lshl_add_u64 v[160:161], v[200:201], 0, s[70:71]
	v_lshl_add_u64 v[160:161], v[158:159], 1, v[160:161]
	v_mov_b32_e32 v170, 0
	v_mov_b32_e32 v171, 0
	v_mov_b32_e32 v172, 0
	v_mov_b32_e32 v173, 0
	v_mov_b32_dpp v174, v90 row_ror:15 row_mask:0xf bank_mask:0xf
	v_mov_b32_dpp v175, v91 row_ror:15 row_mask:0xf bank_mask:0xf
	v_mov_b32_dpp v176, v92 row_ror:15 row_mask:0xf bank_mask:0xf
	v_mov_b32_dpp v177, v93 row_ror:15 row_mask:0xf bank_mask:0xf
	v_mov_b32_dpp v170, v94 row_shr:1 row_mask:0xf bank_mask:0xf
	v_mov_b32_dpp v171, v95 row_shr:1 row_mask:0xf bank_mask:0xf
	v_mov_b32_dpp v172, v96 row_shr:1 row_mask:0xf bank_mask:0xf
	v_mov_b32_dpp v173, v97 row_shr:1 row_mask:0xf bank_mask:0xf
	v_mov_b32_dpp v174, v94 row_shl:1 row_mask:0xf bank_mask:0xf
	v_mov_b32_dpp v175, v95 row_shl:1 row_mask:0xf bank_mask:0xf
	v_mov_b32_dpp v176, v96 row_shl:1 row_mask:0xf bank_mask:0xf
	v_mov_b32_dpp v177, v97 row_shl:1 row_mask:0xf bank_mask:0xf
	s_waitcnt vmcnt(19)
; __device__ __forceinline__ unsigned cvt_pk_bf16(float lo, float hi) { unsigned r; asm volatile("v_cvt_pk_bf16_f32 %0, %1, %2" : "=v"(r) : "v"(lo), "v"(hi)); return r; }
; __device__ __forceinline__ float sigmoidf_(float x) { return 1.0f / (1.0f + __expf(-x)); }
; __device__ __forceinline__ float dppf_prev(float cur, float below) { return __uint_as_float(dpp_prev(__float_as_uint(cur), __float_as_uint(below))); }
; __device__ __forceinline__ float dppf_next(float cur, float above) { return __uint_as_float(dpp_next(__float_as_uint(cur), __float_as_uint(above))); }
;     __device__ __forceinline__ void operator()(AccT& acc, const Unit& u, int wr, int wc, int fr, int fq) const {
;     ...
;             for (int ai = 0; ai < 2; ++ai) { const int grp = u.pm * 4 + ai * 2 + wr;
; #pragma unroll
;                 for (int bj = 0; bj < 2; ++bj) { const int mc = mc0 + bj * 128; const float mul = mc < 512 ? 0.08838834764831845f : 1.0f;
; #pragma unroll
;                     for (int n = 0; n < 2; ++n) {
;                         const f32x4 w0 = *(const f32x4*)(cw + mc + 4 * n), w1 = *(const f32x4*)(cw + 1024 + mc + 4 * n), w2 = *(const f32x4*)(cw + 2048 + mc + 4 * n), b = *(const f32x4*)(cb + mc + 4 * n);
; #pragma unroll
;                         for (int m = 0; m < 4; ++m) { const int lr = m * 16 + fr; const f32x4 gc = acc[ai][bj][m][n]; f32x4 o;
; #pragma unroll
;                             for (int j = 0; j < 4; ++j) { const float gp = dppf_prev(gc[j], m > 0 ? acc[ai][bj][m - 1][n][j] : 0.f), gn = dppf_next(gc[j], m < 3 ? acc[ai][bj][m + 1][n][j] : 0.f);
;                                 const float uu = gp * w0[j] + gc[j] * w1[j] + gn * w2[j] + b[j]; o[j] = uu * sigmoidf_(uu) * mul; }
;                             u32x2 w; w.x = cvt_pk_bf16(o[0], o[1]); w.y = cvt_pk_bf16(o[2], o[3]);
;                             *(u32x2*)(O + (size_t)(grp * 64 + lr) * NPROJ + col0 + bj * 128 + 4 * n) = w;
;                             if (m == 0 || m == 3) { if (lr < 2 || lr > 61) { u32x2 wg; wg.x = cvt_pk_bf16(gc[0], gc[1]); wg.y = cvt_pk_bf16(gc[2], gc[3]);
;                                 *(u32x2*)(HQ + (size_t)(grp * 4 + (lr < 2 ? lr : lr - 60)) * 1024 + mc + 4 * n) = wg; } } } } } }
	v_pk_mul_f32 v[170:171], v[130:131], v[170:171]
	v_pk_mul_f32 v[172:173], v[132:133], v[172:173]
	s_waitcnt vmcnt(17)
	v_pk_mul_f32 v[174:175], v[138:139], v[174:175]
	v_pk_mul_f32 v[176:177], v[140:141], v[176:177]
	v_pk_fma_f32 v[164:165], v[94:95], v[134:135], v[170:171]
	v_pk_fma_f32 v[166:167], v[96:97], v[136:137], v[172:173]
	v_pk_add_f32 v[164:165], v[164:165], v[174:175]
	v_pk_add_f32 v[166:167], v[166:167], v[176:177]
	s_waitcnt vmcnt(16)
	v_pk_add_f32 v[164:165], v[142:143], v[164:165]
	v_pk_add_f32 v[166:167], v[144:145], v[166:167]
	v_pk_mul_f32 v[178:179], v[164:165], s[4:5] op_sel_hi:[1,0]
	v_pk_mul_f32 v[184:185], v[166:167], s[4:5] op_sel_hi:[1,0]
	v_exp_f32_e32 v178, v178
	v_exp_f32_e32 v179, v179
	v_exp_f32_e32 v184, v184
	v_exp_f32_e32 v185, v185
	v_pk_add_f32 v[178:179], v[178:179], 1.0 op_sel_hi:[1,0]
	v_pk_add_f32 v[184:185], v[184:185], 1.0 op_sel_hi:[1,0]
	v_rcp_f32_e32 v180, v178
	v_rcp_f32_e32 v181, v179
	v_rcp_f32_e32 v192, v184
	v_rcp_f32_e32 v193, v185
	v_pk_fma_f32 v[182:183], v[178:179], v[180:181], 1.0 op_sel_hi:[1,1,0] neg_lo:[1,0,0] neg_hi:[1,0,0]
	v_pk_fma_f32 v[194:195], v[184:185], v[192:193], 1.0 op_sel_hi:[1,1,0] neg_lo:[1,0,0] neg_hi:[1,0,0]
	v_pk_fma_f32 v[180:181], v[182:183], v[180:181], v[180:181]
	v_pk_fma_f32 v[192:193], v[194:195], v[192:193], v[192:193]
	v_pk_mul_f32 v[164:165], v[164:165], v[180:181]
	v_pk_mul_f32 v[166:167], v[166:167], v[192:193]
	v_pk_mul_f32 v[164:165], v[0:1], v[164:165] op_sel_hi:[0,1]
	v_pk_mul_f32 v[166:167], v[0:1], v[166:167] op_sel_hi:[0,1]
	v_cvt_pk_bf16_f32 v196, v164, v165
	v_cvt_pk_bf16_f32 v197, v166, v167
	global_store_dwordx2 v[160:161], v[196:197], off offset:256
	v_lshl_add_u64 v[160:161], v[160:161], 0, s[68:69]
	s_add_i32 s2, s0, 0
	s_lshl_b32 s2, s2, 2
	s_lshl_b32 s2, s2, 11
	s_ashr_i32 s3, s2, 31
	s_add_u32 s70, s48, s2
	s_addc_u32 s71, s49, s3
	v_lshlrev_b32_e32 v200, 11, v190
	v_mov_b32_e32 v201, 0
	v_lshl_add_u64 v[200:201], v[200:201], 0, s[70:71]
	v_lshl_add_u64 v[200:201], v[158:159], 1, v[200:201]
	s_mov_b64 exec, s[42:43]
	v_cvt_pk_bf16_f32 v198, v94, v95
	v_cvt_pk_bf16_f32 v199, v96, v97
	global_store_dwordx2 v[200:201], v[198:199], off offset:-3840
	s_mov_b64 exec, -1
	v_mov_b32_dpp v170, v94 row_ror:1 row_mask:0xf bank_mask:0xf
	v_mov_b32_dpp v171, v95 row_ror:1 row_mask:0xf bank_mask:0xf
	v_mov_b32_dpp v172, v96 row_ror:1 row_mask:0xf bank_mask:0xf
	v_mov_b32_dpp v173, v97 row_ror:1 row_mask:0xf bank_mask:0xf
	v_mov_b32_dpp v174, v86 row_ror:15 row_mask:0xf bank_mask:0xf
	v_mov_b32_dpp v175, v87 row_ror:15 row_mask:0xf bank_mask:0xf
	v_mov_b32_dpp v176, v88 row_ror:15 row_mask:0xf bank_mask:0xf
	v_mov_b32_dpp v177, v89 row_ror:15 row_mask:0xf bank_mask:0xf
	v_mov_b32_dpp v170, v90 row_shr:1 row_mask:0xf bank_mask:0xf
	v_mov_b32_dpp v171, v91 row_shr:1 row_mask:0xf bank_mask:0xf
	v_mov_b32_dpp v172, v92 row_shr:1 row_mask:0xf bank_mask:0xf
	v_mov_b32_dpp v173, v93 row_shr:1 row_mask:0xf bank_mask:0xf
	v_mov_b32_dpp v174, v90 row_shl:1 row_mask:0xf bank_mask:0xf
	v_mov_b32_dpp v175, v91 row_shl:1 row_mask:0xf bank_mask:0xf
	v_mov_b32_dpp v176, v92 row_shl:1 row_mask:0xf bank_mask:0xf
	v_mov_b32_dpp v177, v93 row_shl:1 row_mask:0xf bank_mask:0xf
	v_pk_mul_f32 v[170:171], v[130:131], v[170:171]
	v_pk_mul_f32 v[172:173], v[132:133], v[172:173]
	v_pk_mul_f32 v[174:175], v[138:139], v[174:175]
	v_pk_mul_f32 v[176:177], v[140:141], v[176:177]
	v_pk_fma_f32 v[164:165], v[90:91], v[134:135], v[170:171]
	v_pk_fma_f32 v[166:167], v[92:93], v[136:137], v[172:173]
	v_pk_add_f32 v[164:165], v[164:165], v[174:175]
	v_pk_add_f32 v[166:167], v[166:167], v[176:177]
	v_pk_add_f32 v[164:165], v[142:143], v[164:165]
	v_pk_add_f32 v[166:167], v[144:145], v[166:167]
	v_pk_mul_f32 v[178:179], v[164:165], s[4:5] op_sel_hi:[1,0]
	v_pk_mul_f32 v[184:185], v[166:167], s[4:5] op_sel_hi:[1,0]
	v_exp_f32_e32 v178, v178
	v_exp_f32_e32 v179, v179
	v_exp_f32_e32 v184, v184
	v_exp_f32_e32 v185, v185
	v_pk_add_f32 v[178:179], v[178:179], 1.0 op_sel_hi:[1,0]
	v_pk_add_f32 v[184:185], v[184:185], 1.0 op_sel_hi:[1,0]
	v_rcp_f32_e32 v180, v178
	v_rcp_f32_e32 v181, v179
	v_rcp_f32_e32 v192, v184
	v_rcp_f32_e32 v193, v185
	v_pk_fma_f32 v[182:183], v[178:179], v[180:181], 1.0 op_sel_hi:[1,1,0] neg_lo:[1,0,0] neg_hi:[1,0,0]
	v_pk_fma_f32 v[194:195], v[184:185], v[192:193], 1.0 op_sel_hi:[1,1,0] neg_lo:[1,0,0] neg_hi:[1,0,0]
	v_pk_fma_f32 v[180:181], v[182:183], v[180:181], v[180:181]
	v_pk_fma_f32 v[192:193], v[194:195], v[192:193], v[192:193]
	v_pk_mul_f32 v[164:165], v[164:165], v[180:181]
	v_pk_mul_f32 v[166:167], v[166:167], v[192:193]
	v_pk_mul_f32 v[164:165], v[0:1], v[164:165] op_sel_hi:[0,1]
	v_pk_mul_f32 v[166:167], v[0:1], v[166:167] op_sel_hi:[0,1]
	v_cvt_pk_bf16_f32 v196, v164, v165
	v_cvt_pk_bf16_f32 v197, v166, v167
	global_store_dwordx2 v[160:161], v[196:197], off offset:256
	v_lshl_add_u64 v[160:161], v[160:161], 0, s[68:69]
	v_mov_b32_dpp v170, v90 row_ror:1 row_mask:0xf bank_mask:0xf
	v_mov_b32_dpp v171, v91 row_ror:1 row_mask:0xf bank_mask:0xf
	v_mov_b32_dpp v172, v92 row_ror:1 row_mask:0xf bank_mask:0xf
	v_mov_b32_dpp v173, v93 row_ror:1 row_mask:0xf bank_mask:0xf
	v_mov_b32_dpp v174, v82 row_ror:15 row_mask:0xf bank_mask:0xf
	v_mov_b32_dpp v175, v83 row_ror:15 row_mask:0xf bank_mask:0xf
	v_mov_b32_dpp v176, v84 row_ror:15 row_mask:0xf bank_mask:0xf
	v_mov_b32_dpp v177, v85 row_ror:15 row_mask:0xf bank_mask:0xf
	v_mov_b32_dpp v170, v86 row_shr:1 row_mask:0xf bank_mask:0xf
	v_mov_b32_dpp v171, v87 row_shr:1 row_mask:0xf bank_mask:0xf
	v_mov_b32_dpp v172, v88 row_shr:1 row_mask:0xf bank_mask:0xf
	v_mov_b32_dpp v173, v89 row_shr:1 row_mask:0xf bank_mask:0xf
; __device__ __forceinline__ unsigned cvt_pk_bf16(float lo, float hi) { unsigned r; asm volatile("v_cvt_pk_bf16_f32 %0, %1, %2" : "=v"(r) : "v"(lo), "v"(hi)); return r; }
; __device__ __forceinline__ float sigmoidf_(float x) { return 1.0f / (1.0f + __expf(-x)); }
; __device__ __forceinline__ float dppf_prev(float cur, float below) { return __uint_as_float(dpp_prev(__float_as_uint(cur), __float_as_uint(below))); }
; __device__ __forceinline__ float dppf_next(float cur, float above) { return __uint_as_float(dpp_next(__float_as_uint(cur), __float_as_uint(above))); }
;     __device__ __forceinline__ void operator()(AccT& acc, const Unit& u, int wr, int wc, int fr, int fq) const {
;     ...
;             for (int ai = 0; ai < 2; ++ai) { const int grp = u.pm * 4 + ai * 2 + wr;
; #pragma unroll
;                 for (int bj = 0; bj < 2; ++bj) { const int mc = mc0 + bj * 128; const float mul = mc < 512 ? 0.08838834764831845f : 1.0f;
; #pragma unroll
;                     for (int n = 0; n < 2; ++n) {
;                         const f32x4 w0 = *(const f32x4*)(cw + mc + 4 * n), w1 = *(const f32x4*)(cw + 1024 + mc + 4 * n), w2 = *(const f32x4*)(cw + 2048 + mc + 4 * n), b = *(const f32x4*)(cb + mc + 4 * n);
; #pragma unroll
;                         for (int m = 0; m < 4; ++m) { const int lr = m * 16 + fr; const f32x4 gc = acc[ai][bj][m][n]; f32x4 o;
; #pragma unroll
;                             for (int j = 0; j < 4; ++j) { const float gp = dppf_prev(gc[j], m > 0 ? acc[ai][bj][m - 1][n][j] : 0.f), gn = dppf_next(gc[j], m < 3 ? acc[ai][bj][m + 1][n][j] : 0.f);
;                                 const float uu = gp * w0[j] + gc[j] * w1[j] + gn * w2[j] + b[j]; o[j] = uu * sigmoidf_(uu) * mul; }
;                             u32x2 w; w.x = cvt_pk_bf16(o[0], o[1]); w.y = cvt_pk_bf16(o[2], o[3]);
;                             *(u32x2*)(O + (size_t)(grp * 64 + lr) * NPROJ + col0 + bj * 128 + 4 * n) = w;
;                             if (m == 0 || m == 3) { if (lr < 2 || lr > 61) { u32x2 wg; wg.x = cvt_pk_bf16(gc[0], gc[1]); wg.y = cvt_pk_bf16(gc[2], gc[3]);
;                                 *(u32x2*)(HQ + (size_t)(grp * 4 + (lr < 2 ? lr : lr - 60)) * 1024 + mc + 4 * n) = wg; } } } } } }
	v_mov_b32_dpp v174, v86 row_shl:1 row_mask:0xf bank_mask:0xf
	v_mov_b32_dpp v175, v87 row_shl:1 row_mask:0xf bank_mask:0xf
	v_mov_b32_dpp v176, v88 row_shl:1 row_mask:0xf bank_mask:0xf
	v_mov_b32_dpp v177, v89 row_shl:1 row_mask:0xf bank_mask:0xf
	v_pk_mul_f32 v[170:171], v[130:131], v[170:171]
	v_pk_mul_f32 v[172:173], v[132:133], v[172:173]
	v_pk_mul_f32 v[174:175], v[138:139], v[174:175]
	v_pk_mul_f32 v[176:177], v[140:141], v[176:177]
	v_pk_fma_f32 v[164:165], v[86:87], v[134:135], v[170:171]
	v_pk_fma_f32 v[166:167], v[88:89], v[136:137], v[172:173]
	v_pk_add_f32 v[164:165], v[164:165], v[174:175]
	v_pk_add_f32 v[166:167], v[166:167], v[176:177]
	v_pk_add_f32 v[164:165], v[142:143], v[164:165]
	v_pk_add_f32 v[166:167], v[144:145], v[166:167]
	v_pk_mul_f32 v[178:179], v[164:165], s[4:5] op_sel_hi:[1,0]
	v_pk_mul_f32 v[184:185], v[166:167], s[4:5] op_sel_hi:[1,0]
	v_exp_f32_e32 v178, v178
	v_exp_f32_e32 v179, v179
	v_exp_f32_e32 v184, v184
	v_exp_f32_e32 v185, v185
	v_pk_add_f32 v[178:179], v[178:179], 1.0 op_sel_hi:[1,0]
	v_pk_add_f32 v[184:185], v[184:185], 1.0 op_sel_hi:[1,0]
	v_rcp_f32_e32 v180, v178
	v_rcp_f32_e32 v181, v179
	v_rcp_f32_e32 v192, v184
	v_rcp_f32_e32 v193, v185
	v_pk_fma_f32 v[182:183], v[178:179], v[180:181], 1.0 op_sel_hi:[1,1,0] neg_lo:[1,0,0] neg_hi:[1,0,0]
	v_pk_fma_f32 v[194:195], v[184:185], v[192:193], 1.0 op_sel_hi:[1,1,0] neg_lo:[1,0,0] neg_hi:[1,0,0]
	v_pk_fma_f32 v[180:181], v[182:183], v[180:181], v[180:181]
	v_pk_fma_f32 v[192:193], v[194:195], v[192:193], v[192:193]
	v_pk_mul_f32 v[164:165], v[164:165], v[180:181]
	v_pk_mul_f32 v[166:167], v[166:167], v[192:193]
	v_pk_mul_f32 v[164:165], v[0:1], v[164:165] op_sel_hi:[0,1]
	v_pk_mul_f32 v[166:167], v[0:1], v[166:167] op_sel_hi:[0,1]
	v_cvt_pk_bf16_f32 v196, v164, v165
	v_cvt_pk_bf16_f32 v197, v166, v167
	global_store_dwordx2 v[160:161], v[196:197], off offset:256
	v_lshl_add_u64 v[160:161], v[160:161], 0, s[68:69]
	v_mov_b32_dpp v170, v86 row_ror:1 row_mask:0xf bank_mask:0xf
	v_mov_b32_dpp v171, v87 row_ror:1 row_mask:0xf bank_mask:0xf
	v_mov_b32_dpp v172, v88 row_ror:1 row_mask:0xf bank_mask:0xf
	v_mov_b32_dpp v173, v89 row_ror:1 row_mask:0xf bank_mask:0xf
	v_mov_b32_e32 v174, 0
	v_mov_b32_e32 v175, 0
	v_mov_b32_e32 v176, 0
	v_mov_b32_e32 v177, 0
	v_mov_b32_dpp v170, v82 row_shr:1 row_mask:0xf bank_mask:0xf
	v_mov_b32_dpp v171, v83 row_shr:1 row_mask:0xf bank_mask:0xf
	v_mov_b32_dpp v172, v84 row_shr:1 row_mask:0xf bank_mask:0xf
	v_mov_b32_dpp v173, v85 row_shr:1 row_mask:0xf bank_mask:0xf
	v_mov_b32_dpp v174, v82 row_shl:1 row_mask:0xf bank_mask:0xf
	v_mov_b32_dpp v175, v83 row_shl:1 row_mask:0xf bank_mask:0xf
	v_mov_b32_dpp v176, v84 row_shl:1 row_mask:0xf bank_mask:0xf
	v_mov_b32_dpp v177, v85 row_shl:1 row_mask:0xf bank_mask:0xf
	v_pk_mul_f32 v[170:171], v[130:131], v[170:171]
	v_pk_mul_f32 v[172:173], v[132:133], v[172:173]
	v_pk_mul_f32 v[174:175], v[138:139], v[174:175]
	v_pk_mul_f32 v[176:177], v[140:141], v[176:177]
	v_pk_fma_f32 v[164:165], v[82:83], v[134:135], v[170:171]
	v_pk_fma_f32 v[166:167], v[84:85], v[136:137], v[172:173]
	v_pk_add_f32 v[164:165], v[164:165], v[174:175]
	v_pk_add_f32 v[166:167], v[166:167], v[176:177]
	v_pk_add_f32 v[164:165], v[142:143], v[164:165]
	v_pk_add_f32 v[166:167], v[144:145], v[166:167]
	v_pk_mul_f32 v[178:179], v[164:165], s[4:5] op_sel_hi:[1,0]
	v_pk_mul_f32 v[184:185], v[166:167], s[4:5] op_sel_hi:[1,0]
	v_exp_f32_e32 v178, v178
	v_exp_f32_e32 v179, v179
	v_exp_f32_e32 v184, v184
	v_exp_f32_e32 v185, v185
	v_pk_add_f32 v[178:179], v[178:179], 1.0 op_sel_hi:[1,0]
	v_pk_add_f32 v[184:185], v[184:185], 1.0 op_sel_hi:[1,0]
	v_rcp_f32_e32 v180, v178
	v_rcp_f32_e32 v181, v179
	v_rcp_f32_e32 v192, v184
	v_rcp_f32_e32 v193, v185
	v_pk_fma_f32 v[182:183], v[178:179], v[180:181], 1.0 op_sel_hi:[1,1,0] neg_lo:[1,0,0] neg_hi:[1,0,0]
	v_pk_fma_f32 v[194:195], v[184:185], v[192:193], 1.0 op_sel_hi:[1,1,0] neg_lo:[1,0,0] neg_hi:[1,0,0]
	v_pk_fma_f32 v[180:181], v[182:183], v[180:181], v[180:181]
	v_pk_fma_f32 v[192:193], v[194:195], v[192:193], v[192:193]
	v_pk_mul_f32 v[164:165], v[164:165], v[180:181]
	v_pk_mul_f32 v[166:167], v[166:167], v[192:193]
	v_pk_mul_f32 v[164:165], v[0:1], v[164:165] op_sel_hi:[0,1]
	v_pk_mul_f32 v[166:167], v[0:1], v[166:167] op_sel_hi:[0,1]
	v_cvt_pk_bf16_f32 v196, v164, v165
	v_cvt_pk_bf16_f32 v197, v166, v167
	global_store_dwordx2 v[160:161], v[196:197], off offset:256
	s_add_i32 s2, s0, 0
	s_lshl_b32 s2, s2, 2
	s_add_i32 s2, s2, -12
	s_lshl_b32 s2, s2, 11
	s_ashr_i32 s3, s2, 31
	s_add_u32 s70, s48, s2
	s_addc_u32 s71, s49, s3
	v_lshlrev_b32_e32 v200, 11, v190
	v_mov_b32_e32 v201, 0
	v_lshl_add_u64 v[200:201], v[200:201], 0, s[70:71]
	v_lshl_add_u64 v[200:201], v[158:159], 1, v[200:201]
	s_mov_b64 exec, s[44:45]
	v_cvt_pk_bf16_f32 v198, v82, v83
	v_cvt_pk_bf16_f32 v199, v84, v85
	global_store_dwordx2 v[200:201], v[198:199], off offset:-3840
	s_mov_b64 exec, -1
	s_add_i32 s2, s0, 2
	s_lshl_b32 s3, s2, 19
	s_add_u32 s70, s22, s3
	s_addc_u32 s71, s23, 0
	v_lshlrev_b32_e32 v200, 13, v190
	v_mov_b32_e32 v201, 0
	v_lshl_add_u64 v[160:161], v[200:201], 0, s[70:71]
	v_lshl_add_u64 v[160:161], v[158:159], 1, v[160:161]
	v_mov_b32_e32 v170, 0
	v_mov_b32_e32 v171, 0
	v_mov_b32_e32 v172, 0
	v_mov_b32_e32 v173, 0
	v_mov_b32_dpp v174, v26 row_ror:15 row_mask:0xf bank_mask:0xf
	v_mov_b32_dpp v175, v27 row_ror:15 row_mask:0xf bank_mask:0xf
	v_mov_b32_dpp v176, v28 row_ror:15 row_mask:0xf bank_mask:0xf
	v_mov_b32_dpp v177, v29 row_ror:15 row_mask:0xf bank_mask:0xf
	v_mov_b32_dpp v170, v30 row_shr:1 row_mask:0xf bank_mask:0xf
	v_mov_b32_dpp v171, v31 row_shr:1 row_mask:0xf bank_mask:0xf
; __device__ __forceinline__ unsigned cvt_pk_bf16(float lo, float hi) { unsigned r; asm volatile("v_cvt_pk_bf16_f32 %0, %1, %2" : "=v"(r) : "v"(lo), "v"(hi)); return r; }
; __device__ __forceinline__ float sigmoidf_(float x) { return 1.0f / (1.0f + __expf(-x)); }
; __device__ __forceinline__ float dppf_prev(float cur, float below) { return __uint_as_float(dpp_prev(__float_as_uint(cur), __float_as_uint(below))); }
; __device__ __forceinline__ float dppf_next(float cur, float above) { return __uint_as_float(dpp_next(__float_as_uint(cur), __float_as_uint(above))); }
;     __device__ __forceinline__ void operator()(AccT& acc, const Unit& u, int wr, int wc, int fr, int fq) const {
;     ...
;             for (int ai = 0; ai < 2; ++ai) { const int grp = u.pm * 4 + ai * 2 + wr;
; #pragma unroll
;                 for (int bj = 0; bj < 2; ++bj) { const int mc = mc0 + bj * 128; const float mul = mc < 512 ? 0.08838834764831845f : 1.0f;
; #pragma unroll
;                     for (int n = 0; n < 2; ++n) {
;                         const f32x4 w0 = *(const f32x4*)(cw + mc + 4 * n), w1 = *(const f32x4*)(cw + 1024 + mc + 4 * n), w2 = *(const f32x4*)(cw + 2048 + mc + 4 * n), b = *(const f32x4*)(cb + mc + 4 * n);
; #pragma unroll
;                         for (int m = 0; m < 4; ++m) { const int lr = m * 16 + fr; const f32x4 gc = acc[ai][bj][m][n]; f32x4 o;
; #pragma unroll
;                             for (int j = 0; j < 4; ++j) { const float gp = dppf_prev(gc[j], m > 0 ? acc[ai][bj][m - 1][n][j] : 0.f), gn = dppf_next(gc[j], m < 3 ? acc[ai][bj][m + 1][n][j] : 0.f);
;                                 const float uu = gp * w0[j] + gc[j] * w1[j] + gn * w2[j] + b[j]; o[j] = uu * sigmoidf_(uu) * mul; }
;                             u32x2 w; w.x = cvt_pk_bf16(o[0], o[1]); w.y = cvt_pk_bf16(o[2], o[3]);
;                             *(u32x2*)(O + (size_t)(grp * 64 + lr) * NPROJ + col0 + bj * 128 + 4 * n) = w;
;                             if (m == 0 || m == 3) { if (lr < 2 || lr > 61) { u32x2 wg; wg.x = cvt_pk_bf16(gc[0], gc[1]); wg.y = cvt_pk_bf16(gc[2], gc[3]);
;                                 *(u32x2*)(HQ + (size_t)(grp * 4 + (lr < 2 ? lr : lr - 60)) * 1024 + mc + 4 * n) = wg; } } } } } }
	v_mov_b32_dpp v172, v32 row_shr:1 row_mask:0xf bank_mask:0xf
	v_mov_b32_dpp v173, v33 row_shr:1 row_mask:0xf bank_mask:0xf
	v_mov_b32_dpp v174, v30 row_shl:1 row_mask:0xf bank_mask:0xf
	v_mov_b32_dpp v175, v31 row_shl:1 row_mask:0xf bank_mask:0xf
	v_mov_b32_dpp v176, v32 row_shl:1 row_mask:0xf bank_mask:0xf
	v_mov_b32_dpp v177, v33 row_shl:1 row_mask:0xf bank_mask:0xf
	v_pk_mul_f32 v[170:171], v[130:131], v[170:171]
	v_pk_mul_f32 v[172:173], v[132:133], v[172:173]
	v_pk_mul_f32 v[174:175], v[138:139], v[174:175]
	v_pk_mul_f32 v[176:177], v[140:141], v[176:177]
	v_pk_fma_f32 v[164:165], v[30:31], v[134:135], v[170:171]
	v_pk_fma_f32 v[166:167], v[32:33], v[136:137], v[172:173]
	v_pk_add_f32 v[164:165], v[164:165], v[174:175]
	v_pk_add_f32 v[166:167], v[166:167], v[176:177]
	v_pk_add_f32 v[164:165], v[142:143], v[164:165]
	v_pk_add_f32 v[166:167], v[144:145], v[166:167]
	v_pk_mul_f32 v[178:179], v[164:165], s[4:5] op_sel_hi:[1,0]
	v_pk_mul_f32 v[184:185], v[166:167], s[4:5] op_sel_hi:[1,0]
	v_exp_f32_e32 v178, v178
	v_exp_f32_e32 v179, v179
	v_exp_f32_e32 v184, v184
	v_exp_f32_e32 v185, v185
	v_pk_add_f32 v[178:179], v[178:179], 1.0 op_sel_hi:[1,0]
	v_pk_add_f32 v[184:185], v[184:185], 1.0 op_sel_hi:[1,0]
	v_rcp_f32_e32 v180, v178
	v_rcp_f32_e32 v181, v179
	v_rcp_f32_e32 v192, v184
	v_rcp_f32_e32 v193, v185
	v_pk_fma_f32 v[182:183], v[178:179], v[180:181], 1.0 op_sel_hi:[1,1,0] neg_lo:[1,0,0] neg_hi:[1,0,0]
	v_pk_fma_f32 v[194:195], v[184:185], v[192:193], 1.0 op_sel_hi:[1,1,0] neg_lo:[1,0,0] neg_hi:[1,0,0]
	v_pk_fma_f32 v[180:181], v[182:183], v[180:181], v[180:181]
	v_pk_fma_f32 v[192:193], v[194:195], v[192:193], v[192:193]
	v_pk_mul_f32 v[164:165], v[164:165], v[180:181]
	v_pk_mul_f32 v[166:167], v[166:167], v[192:193]
	v_pk_mul_f32 v[164:165], v[0:1], v[164:165] op_sel_hi:[0,1]
	v_pk_mul_f32 v[166:167], v[0:1], v[166:167] op_sel_hi:[0,1]
	v_cvt_pk_bf16_f32 v196, v164, v165
	v_cvt_pk_bf16_f32 v197, v166, v167
	global_store_dwordx2 v[160:161], v[196:197], off offset:256
	v_lshl_add_u64 v[160:161], v[160:161], 0, s[68:69]
	s_add_i32 s2, s0, 2
	s_lshl_b32 s2, s2, 2
	s_lshl_b32 s2, s2, 11
	s_ashr_i32 s3, s2, 31
	s_add_u32 s70, s48, s2
	s_addc_u32 s71, s49, s3
	v_lshlrev_b32_e32 v200, 11, v190
	v_mov_b32_e32 v201, 0
	v_lshl_add_u64 v[200:201], v[200:201], 0, s[70:71]
	v_lshl_add_u64 v[200:201], v[158:159], 1, v[200:201]
	s_mov_b64 exec, s[42:43]
	v_cvt_pk_bf16_f32 v198, v30, v31
	v_cvt_pk_bf16_f32 v199, v32, v33
	global_store_dwordx2 v[200:201], v[198:199], off offset:-3840
	s_mov_b64 exec, -1
	v_mov_b32_dpp v170, v30 row_ror:1 row_mask:0xf bank_mask:0xf
	v_mov_b32_dpp v171, v31 row_ror:1 row_mask:0xf bank_mask:0xf
	v_mov_b32_dpp v172, v32 row_ror:1 row_mask:0xf bank_mask:0xf
	v_mov_b32_dpp v173, v33 row_ror:1 row_mask:0xf bank_mask:0xf
	v_mov_b32_dpp v174, v22 row_ror:15 row_mask:0xf bank_mask:0xf
	v_mov_b32_dpp v175, v23 row_ror:15 row_mask:0xf bank_mask:0xf
	v_mov_b32_dpp v176, v24 row_ror:15 row_mask:0xf bank_mask:0xf
	v_mov_b32_dpp v177, v25 row_ror:15 row_mask:0xf bank_mask:0xf
	v_mov_b32_dpp v170, v26 row_shr:1 row_mask:0xf bank_mask:0xf
	v_mov_b32_dpp v171, v27 row_shr:1 row_mask:0xf bank_mask:0xf
	v_mov_b32_dpp v172, v28 row_shr:1 row_mask:0xf bank_mask:0xf
	v_mov_b32_dpp v173, v29 row_shr:1 row_mask:0xf bank_mask:0xf
	v_mov_b32_dpp v174, v26 row_shl:1 row_mask:0xf bank_mask:0xf
	v_mov_b32_dpp v175, v27 row_shl:1 row_mask:0xf bank_mask:0xf
	v_mov_b32_dpp v176, v28 row_shl:1 row_mask:0xf bank_mask:0xf
	v_mov_b32_dpp v177, v29 row_shl:1 row_mask:0xf bank_mask:0xf
	v_pk_mul_f32 v[170:171], v[130:131], v[170:171]
	v_pk_mul_f32 v[172:173], v[132:133], v[172:173]
	v_pk_mul_f32 v[174:175], v[138:139], v[174:175]
	v_pk_mul_f32 v[176:177], v[140:141], v[176:177]
	v_pk_fma_f32 v[164:165], v[26:27], v[134:135], v[170:171]
	v_pk_fma_f32 v[166:167], v[28:29], v[136:137], v[172:173]
	v_pk_add_f32 v[164:165], v[164:165], v[174:175]
	v_pk_add_f32 v[166:167], v[166:167], v[176:177]
	v_pk_add_f32 v[164:165], v[142:143], v[164:165]
	v_pk_add_f32 v[166:167], v[144:145], v[166:167]
	v_pk_mul_f32 v[178:179], v[164:165], s[4:5] op_sel_hi:[1,0]
	v_pk_mul_f32 v[184:185], v[166:167], s[4:5] op_sel_hi:[1,0]
	v_exp_f32_e32 v178, v178
	v_exp_f32_e32 v179, v179
	v_exp_f32_e32 v184, v184
	v_exp_f32_e32 v185, v185
	v_pk_add_f32 v[178:179], v[178:179], 1.0 op_sel_hi:[1,0]
	v_pk_add_f32 v[184:185], v[184:185], 1.0 op_sel_hi:[1,0]
	v_rcp_f32_e32 v180, v178
	v_rcp_f32_e32 v181, v179
	v_rcp_f32_e32 v192, v184
	v_rcp_f32_e32 v193, v185
	v_pk_fma_f32 v[182:183], v[178:179], v[180:181], 1.0 op_sel_hi:[1,1,0] neg_lo:[1,0,0] neg_hi:[1,0,0]
	v_pk_fma_f32 v[194:195], v[184:185], v[192:193], 1.0 op_sel_hi:[1,1,0] neg_lo:[1,0,0] neg_hi:[1,0,0]
	v_pk_fma_f32 v[180:181], v[182:183], v[180:181], v[180:181]
	v_pk_fma_f32 v[192:193], v[194:195], v[192:193], v[192:193]
	v_pk_mul_f32 v[164:165], v[164:165], v[180:181]
	v_pk_mul_f32 v[166:167], v[166:167], v[192:193]
	v_pk_mul_f32 v[164:165], v[0:1], v[164:165] op_sel_hi:[0,1]
	v_pk_mul_f32 v[166:167], v[0:1], v[166:167] op_sel_hi:[0,1]
	v_cvt_pk_bf16_f32 v196, v164, v165
	v_cvt_pk_bf16_f32 v197, v166, v167
	global_store_dwordx2 v[160:161], v[196:197], off offset:256
	v_lshl_add_u64 v[160:161], v[160:161], 0, s[68:69]
	v_mov_b32_dpp v170, v26 row_ror:1 row_mask:0xf bank_mask:0xf
	v_mov_b32_dpp v171, v27 row_ror:1 row_mask:0xf bank_mask:0xf
	v_mov_b32_dpp v172, v28 row_ror:1 row_mask:0xf bank_mask:0xf
	v_mov_b32_dpp v173, v29 row_ror:1 row_mask:0xf bank_mask:0xf
	v_mov_b32_dpp v174, v18 row_ror:15 row_mask:0xf bank_mask:0xf
	v_mov_b32_dpp v175, v19 row_ror:15 row_mask:0xf bank_mask:0xf
	v_mov_b32_dpp v176, v20 row_ror:15 row_mask:0xf bank_mask:0xf
; __device__ __forceinline__ unsigned cvt_pk_bf16(float lo, float hi) { unsigned r; asm volatile("v_cvt_pk_bf16_f32 %0, %1, %2" : "=v"(r) : "v"(lo), "v"(hi)); return r; }
; __device__ __forceinline__ float sigmoidf_(float x) { return 1.0f / (1.0f + __expf(-x)); }
; __device__ __forceinline__ float dppf_prev(float cur, float below) { return __uint_as_float(dpp_prev(__float_as_uint(cur), __float_as_uint(below))); }
; __device__ __forceinline__ float dppf_next(float cur, float above) { return __uint_as_float(dpp_next(__float_as_uint(cur), __float_as_uint(above))); }
;     __device__ __forceinline__ void operator()(AccT& acc, const Unit& u, int wr, int wc, int fr, int fq) const {
;     ...
;             for (int ai = 0; ai < 2; ++ai) { const int grp = u.pm * 4 + ai * 2 + wr;
; #pragma unroll
;                 for (int bj = 0; bj < 2; ++bj) { const int mc = mc0 + bj * 128; const float mul = mc < 512 ? 0.08838834764831845f : 1.0f;
; #pragma unroll
;                     for (int n = 0; n < 2; ++n) {
;                         const f32x4 w0 = *(const f32x4*)(cw + mc + 4 * n), w1 = *(const f32x4*)(cw + 1024 + mc + 4 * n), w2 = *(const f32x4*)(cw + 2048 + mc + 4 * n), b = *(const f32x4*)(cb + mc + 4 * n);
; #pragma unroll
;                         for (int m = 0; m < 4; ++m) { const int lr = m * 16 + fr; const f32x4 gc = acc[ai][bj][m][n]; f32x4 o;
; #pragma unroll
;                             for (int j = 0; j < 4; ++j) { const float gp = dppf_prev(gc[j], m > 0 ? acc[ai][bj][m - 1][n][j] : 0.f), gn = dppf_next(gc[j], m < 3 ? acc[ai][bj][m + 1][n][j] : 0.f);
;                                 const float uu = gp * w0[j] + gc[j] * w1[j] + gn * w2[j] + b[j]; o[j] = uu * sigmoidf_(uu) * mul; }
;                             u32x2 w; w.x = cvt_pk_bf16(o[0], o[1]); w.y = cvt_pk_bf16(o[2], o[3]);
;                             *(u32x2*)(O + (size_t)(grp * 64 + lr) * NPROJ + col0 + bj * 128 + 4 * n) = w;
;                             if (m == 0 || m == 3) { if (lr < 2 || lr > 61) { u32x2 wg; wg.x = cvt_pk_bf16(gc[0], gc[1]); wg.y = cvt_pk_bf16(gc[2], gc[3]);
;                                 *(u32x2*)(HQ + (size_t)(grp * 4 + (lr < 2 ? lr : lr - 60)) * 1024 + mc + 4 * n) = wg; } } } } } }
	v_mov_b32_dpp v177, v21 row_ror:15 row_mask:0xf bank_mask:0xf
	v_mov_b32_dpp v170, v22 row_shr:1 row_mask:0xf bank_mask:0xf
	v_mov_b32_dpp v171, v23 row_shr:1 row_mask:0xf bank_mask:0xf
	v_mov_b32_dpp v172, v24 row_shr:1 row_mask:0xf bank_mask:0xf
	v_mov_b32_dpp v173, v25 row_shr:1 row_mask:0xf bank_mask:0xf
	v_mov_b32_dpp v174, v22 row_shl:1 row_mask:0xf bank_mask:0xf
	v_mov_b32_dpp v175, v23 row_shl:1 row_mask:0xf bank_mask:0xf
	v_mov_b32_dpp v176, v24 row_shl:1 row_mask:0xf bank_mask:0xf
	v_mov_b32_dpp v177, v25 row_shl:1 row_mask:0xf bank_mask:0xf
	v_pk_mul_f32 v[170:171], v[130:131], v[170:171]
	v_pk_mul_f32 v[172:173], v[132:133], v[172:173]
	v_pk_mul_f32 v[174:175], v[138:139], v[174:175]
	v_pk_mul_f32 v[176:177], v[140:141], v[176:177]
	v_pk_fma_f32 v[164:165], v[22:23], v[134:135], v[170:171]
	v_pk_fma_f32 v[166:167], v[24:25], v[136:137], v[172:173]
	v_pk_add_f32 v[164:165], v[164:165], v[174:175]
	v_pk_add_f32 v[166:167], v[166:167], v[176:177]
	v_pk_add_f32 v[164:165], v[142:143], v[164:165]
	v_pk_add_f32 v[166:167], v[144:145], v[166:167]
	v_pk_mul_f32 v[178:179], v[164:165], s[4:5] op_sel_hi:[1,0]
	v_pk_mul_f32 v[184:185], v[166:167], s[4:5] op_sel_hi:[1,0]
	v_exp_f32_e32 v178, v178
	v_exp_f32_e32 v179, v179
	v_exp_f32_e32 v184, v184
	v_exp_f32_e32 v185, v185
	v_pk_add_f32 v[178:179], v[178:179], 1.0 op_sel_hi:[1,0]
	v_pk_add_f32 v[184:185], v[184:185], 1.0 op_sel_hi:[1,0]
	v_rcp_f32_e32 v180, v178
	v_rcp_f32_e32 v181, v179
	v_rcp_f32_e32 v192, v184
	v_rcp_f32_e32 v193, v185
	v_pk_fma_f32 v[182:183], v[178:179], v[180:181], 1.0 op_sel_hi:[1,1,0] neg_lo:[1,0,0] neg_hi:[1,0,0]
	v_pk_fma_f32 v[194:195], v[184:185], v[192:193], 1.0 op_sel_hi:[1,1,0] neg_lo:[1,0,0] neg_hi:[1,0,0]
	v_pk_fma_f32 v[180:181], v[182:183], v[180:181], v[180:181]
	v_pk_fma_f32 v[192:193], v[194:195], v[192:193], v[192:193]
	v_pk_mul_f32 v[164:165], v[164:165], v[180:181]
	v_pk_mul_f32 v[166:167], v[166:167], v[192:193]
	v_pk_mul_f32 v[164:165], v[0:1], v[164:165] op_sel_hi:[0,1]
	v_pk_mul_f32 v[166:167], v[0:1], v[166:167] op_sel_hi:[0,1]
	v_cvt_pk_bf16_f32 v196, v164, v165
	v_cvt_pk_bf16_f32 v197, v166, v167
	global_store_dwordx2 v[160:161], v[196:197], off offset:256
	v_lshl_add_u64 v[160:161], v[160:161], 0, s[68:69]
	v_mov_b32_dpp v170, v22 row_ror:1 row_mask:0xf bank_mask:0xf
	v_mov_b32_dpp v171, v23 row_ror:1 row_mask:0xf bank_mask:0xf
	v_mov_b32_dpp v172, v24 row_ror:1 row_mask:0xf bank_mask:0xf
	v_mov_b32_dpp v173, v25 row_ror:1 row_mask:0xf bank_mask:0xf
	v_mov_b32_e32 v174, 0
	v_mov_b32_e32 v175, 0
	v_mov_b32_e32 v176, 0
	v_mov_b32_e32 v177, 0
	v_mov_b32_dpp v170, v18 row_shr:1 row_mask:0xf bank_mask:0xf
	v_mov_b32_dpp v171, v19 row_shr:1 row_mask:0xf bank_mask:0xf
	v_mov_b32_dpp v172, v20 row_shr:1 row_mask:0xf bank_mask:0xf
	v_mov_b32_dpp v173, v21 row_shr:1 row_mask:0xf bank_mask:0xf
	v_mov_b32_dpp v174, v18 row_shl:1 row_mask:0xf bank_mask:0xf
	v_mov_b32_dpp v175, v19 row_shl:1 row_mask:0xf bank_mask:0xf
	v_mov_b32_dpp v176, v20 row_shl:1 row_mask:0xf bank_mask:0xf
	v_mov_b32_dpp v177, v21 row_shl:1 row_mask:0xf bank_mask:0xf
	v_pk_mul_f32 v[170:171], v[130:131], v[170:171]
	v_pk_mul_f32 v[172:173], v[132:133], v[172:173]
	v_pk_mul_f32 v[174:175], v[138:139], v[174:175]
	v_pk_mul_f32 v[176:177], v[140:141], v[176:177]
	v_pk_fma_f32 v[164:165], v[18:19], v[134:135], v[170:171]
	v_pk_fma_f32 v[166:167], v[20:21], v[136:137], v[172:173]
	v_pk_add_f32 v[164:165], v[164:165], v[174:175]
	v_pk_add_f32 v[166:167], v[166:167], v[176:177]
	v_pk_add_f32 v[164:165], v[142:143], v[164:165]
	v_pk_add_f32 v[166:167], v[144:145], v[166:167]
	v_pk_mul_f32 v[178:179], v[164:165], s[4:5] op_sel_hi:[1,0]
	v_pk_mul_f32 v[184:185], v[166:167], s[4:5] op_sel_hi:[1,0]
	v_exp_f32_e32 v178, v178
	v_exp_f32_e32 v179, v179
	v_exp_f32_e32 v184, v184
	v_exp_f32_e32 v185, v185
	v_pk_add_f32 v[178:179], v[178:179], 1.0 op_sel_hi:[1,0]
	v_pk_add_f32 v[184:185], v[184:185], 1.0 op_sel_hi:[1,0]
	v_rcp_f32_e32 v180, v178
	v_rcp_f32_e32 v181, v179
	v_rcp_f32_e32 v192, v184
	v_rcp_f32_e32 v193, v185
	v_pk_fma_f32 v[182:183], v[178:179], v[180:181], 1.0 op_sel_hi:[1,1,0] neg_lo:[1,0,0] neg_hi:[1,0,0]
	v_pk_fma_f32 v[194:195], v[184:185], v[192:193], 1.0 op_sel_hi:[1,1,0] neg_lo:[1,0,0] neg_hi:[1,0,0]
	v_pk_fma_f32 v[180:181], v[182:183], v[180:181], v[180:181]
	v_pk_fma_f32 v[192:193], v[194:195], v[192:193], v[192:193]
	v_pk_mul_f32 v[164:165], v[164:165], v[180:181]
	v_pk_mul_f32 v[166:167], v[166:167], v[192:193]
	v_pk_mul_f32 v[164:165], v[0:1], v[164:165] op_sel_hi:[0,1]
	v_pk_mul_f32 v[166:167], v[0:1], v[166:167] op_sel_hi:[0,1]
	v_cvt_pk_bf16_f32 v196, v164, v165
	v_cvt_pk_bf16_f32 v197, v166, v167
	global_store_dwordx2 v[160:161], v[196:197], off offset:256
	s_add_i32 s2, s0, 2
	s_lshl_b32 s2, s2, 2
	s_add_i32 s2, s2, -12
	s_lshl_b32 s2, s2, 11
	s_ashr_i32 s3, s2, 31
	s_add_u32 s70, s48, s2
	s_addc_u32 s71, s49, s3
	v_lshlrev_b32_e32 v200, 11, v190
	v_mov_b32_e32 v201, 0
	v_lshl_add_u64 v[200:201], v[200:201], 0, s[70:71]
	v_lshl_add_u64 v[200:201], v[158:159], 1, v[200:201]
	s_mov_b64 exec, s[44:45]
	v_cvt_pk_bf16_f32 v198, v18, v19
	v_cvt_pk_bf16_f32 v199, v20, v21
	global_store_dwordx2 v[200:201], v[198:199], off offset:-3840
	s_mov_b64 exec, -1
	s_add_i32 s2, s0, 0
	s_lshl_b32 s3, s2, 19
	s_add_u32 s70, s22, s3
	s_addc_u32 s71, s23, 0
	v_lshlrev_b32_e32 v200, 13, v190
	v_mov_b32_e32 v201, 0
	v_lshl_add_u64 v[160:161], v[200:201], 0, s[70:71]
	v_lshl_add_u64 v[160:161], v[158:159], 1, v[160:161]
	v_mov_b32_e32 v170, 0
	v_mov_b32_e32 v171, 0
	v_mov_b32_e32 v172, 0
	v_mov_b32_e32 v173, 0
	v_mov_b32_dpp v174, v74 row_ror:15 row_mask:0xf bank_mask:0xf
	v_mov_b32_dpp v175, v75 row_ror:15 row_mask:0xf bank_mask:0xf
	v_mov_b32_dpp v176, v76 row_ror:15 row_mask:0xf bank_mask:0xf
	v_mov_b32_dpp v177, v77 row_ror:15 row_mask:0xf bank_mask:0xf
	v_mov_b32_dpp v170, v78 row_shr:1 row_mask:0xf bank_mask:0xf
	v_mov_b32_dpp v171, v79 row_shr:1 row_mask:0xf bank_mask:0xf
	v_mov_b32_dpp v172, v80 row_shr:1 row_mask:0xf bank_mask:0xf
	v_mov_b32_dpp v173, v81 row_shr:1 row_mask:0xf bank_mask:0xf
	v_mov_b32_dpp v174, v78 row_shl:1 row_mask:0xf bank_mask:0xf
	v_mov_b32_dpp v175, v79 row_shl:1 row_mask:0xf bank_mask:0xf
	v_mov_b32_dpp v176, v80 row_shl:1 row_mask:0xf bank_mask:0xf
	v_mov_b32_dpp v177, v81 row_shl:1 row_mask:0xf bank_mask:0xf
	s_waitcnt vmcnt(15)
; __device__ __forceinline__ unsigned cvt_pk_bf16(float lo, float hi) { unsigned r; asm volatile("v_cvt_pk_bf16_f32 %0, %1, %2" : "=v"(r) : "v"(lo), "v"(hi)); return r; }
; __device__ __forceinline__ float sigmoidf_(float x) { return 1.0f / (1.0f + __expf(-x)); }
; __device__ __forceinline__ float dppf_prev(float cur, float below) { return __uint_as_float(dpp_prev(__float_as_uint(cur), __float_as_uint(below))); }
; __device__ __forceinline__ float dppf_next(float cur, float above) { return __uint_as_float(dpp_next(__float_as_uint(cur), __float_as_uint(above))); }
;     __device__ __forceinline__ void operator()(AccT& acc, const Unit& u, int wr, int wc, int fr, int fq) const {
;     ...
;             for (int ai = 0; ai < 2; ++ai) { const int grp = u.pm * 4 + ai * 2 + wr;
; #pragma unroll
;                 for (int bj = 0; bj < 2; ++bj) { const int mc = mc0 + bj * 128; const float mul = mc < 512 ? 0.08838834764831845f : 1.0f;
; #pragma unroll
;                     for (int n = 0; n < 2; ++n) {
;                         const f32x4 w0 = *(const f32x4*)(cw + mc + 4 * n), w1 = *(const f32x4*)(cw + 1024 + mc + 4 * n), w2 = *(const f32x4*)(cw + 2048 + mc + 4 * n), b = *(const f32x4*)(cb + mc + 4 * n);
; #pragma unroll
;                         for (int m = 0; m < 4; ++m) { const int lr = m * 16 + fr; const f32x4 gc = acc[ai][bj][m][n]; f32x4 o;
; #pragma unroll
;                             for (int j = 0; j < 4; ++j) { const float gp = dppf_prev(gc[j], m > 0 ? acc[ai][bj][m - 1][n][j] : 0.f), gn = dppf_next(gc[j], m < 3 ? acc[ai][bj][m + 1][n][j] : 0.f);
;                                 const float uu = gp * w0[j] + gc[j] * w1[j] + gn * w2[j] + b[j]; o[j] = uu * sigmoidf_(uu) * mul; }
;                             u32x2 w; w.x = cvt_pk_bf16(o[0], o[1]); w.y = cvt_pk_bf16(o[2], o[3]);
;                             *(u32x2*)(O + (size_t)(grp * 64 + lr) * NPROJ + col0 + bj * 128 + 4 * n) = w;
;                             if (m == 0 || m == 3) { if (lr < 2 || lr > 61) { u32x2 wg; wg.x = cvt_pk_bf16(gc[0], gc[1]); wg.y = cvt_pk_bf16(gc[2], gc[3]);
;                                 *(u32x2*)(HQ + (size_t)(grp * 4 + (lr < 2 ? lr : lr - 60)) * 1024 + mc + 4 * n) = wg; } } } } } }
	v_pk_mul_f32 v[170:171], v[222:223], v[170:171]
	v_pk_mul_f32 v[172:173], v[224:225], v[172:173]
	s_waitcnt vmcnt(13)
	v_pk_mul_f32 v[174:175], v[230:231], v[174:175]
	v_pk_mul_f32 v[176:177], v[232:233], v[176:177]
	v_pk_fma_f32 v[164:165], v[78:79], v[226:227], v[170:171]
	v_pk_fma_f32 v[166:167], v[80:81], v[228:229], v[172:173]
	v_pk_add_f32 v[164:165], v[164:165], v[174:175]
	v_pk_add_f32 v[166:167], v[166:167], v[176:177]
	s_waitcnt vmcnt(12)
	v_pk_add_f32 v[164:165], v[204:205], v[164:165]
	v_pk_add_f32 v[166:167], v[206:207], v[166:167]
	v_pk_mul_f32 v[178:179], v[164:165], s[4:5] op_sel_hi:[1,0]
	v_pk_mul_f32 v[184:185], v[166:167], s[4:5] op_sel_hi:[1,0]
	v_exp_f32_e32 v178, v178
	v_exp_f32_e32 v179, v179
	v_exp_f32_e32 v184, v184
	v_exp_f32_e32 v185, v185
	v_pk_add_f32 v[178:179], v[178:179], 1.0 op_sel_hi:[1,0]
	v_pk_add_f32 v[184:185], v[184:185], 1.0 op_sel_hi:[1,0]
	v_rcp_f32_e32 v180, v178
	v_rcp_f32_e32 v181, v179
	v_rcp_f32_e32 v192, v184
	v_rcp_f32_e32 v193, v185
	v_pk_fma_f32 v[182:183], v[178:179], v[180:181], 1.0 op_sel_hi:[1,1,0] neg_lo:[1,0,0] neg_hi:[1,0,0]
	v_pk_fma_f32 v[194:195], v[184:185], v[192:193], 1.0 op_sel_hi:[1,1,0] neg_lo:[1,0,0] neg_hi:[1,0,0]
	v_pk_fma_f32 v[180:181], v[182:183], v[180:181], v[180:181]
	v_pk_fma_f32 v[192:193], v[194:195], v[192:193], v[192:193]
	v_pk_mul_f32 v[164:165], v[164:165], v[180:181]
	v_pk_mul_f32 v[166:167], v[166:167], v[192:193]
	v_pk_mul_f32 v[164:165], v[0:1], v[164:165] op_sel_hi:[0,1]
	v_pk_mul_f32 v[166:167], v[0:1], v[166:167] op_sel_hi:[0,1]
	v_cvt_pk_bf16_f32 v196, v164, v165
	v_cvt_pk_bf16_f32 v197, v166, v167
	global_store_dwordx2 v[160:161], v[196:197], off offset:264
	v_lshl_add_u64 v[160:161], v[160:161], 0, s[68:69]
	s_add_i32 s2, s0, 0
	s_lshl_b32 s2, s2, 2
	s_lshl_b32 s2, s2, 11
	s_ashr_i32 s3, s2, 31
	s_add_u32 s70, s48, s2
	s_addc_u32 s71, s49, s3
	v_lshlrev_b32_e32 v200, 11, v190
	v_mov_b32_e32 v201, 0
	v_lshl_add_u64 v[200:201], v[200:201], 0, s[70:71]
	v_lshl_add_u64 v[200:201], v[158:159], 1, v[200:201]
	s_mov_b64 exec, s[42:43]
	v_cvt_pk_bf16_f32 v198, v78, v79
	v_cvt_pk_bf16_f32 v199, v80, v81
	global_store_dwordx2 v[200:201], v[198:199], off offset:-3832
	s_mov_b64 exec, -1
	v_mov_b32_dpp v170, v78 row_ror:1 row_mask:0xf bank_mask:0xf
	v_mov_b32_dpp v171, v79 row_ror:1 row_mask:0xf bank_mask:0xf
	v_mov_b32_dpp v172, v80 row_ror:1 row_mask:0xf bank_mask:0xf
	v_mov_b32_dpp v173, v81 row_ror:1 row_mask:0xf bank_mask:0xf
	v_mov_b32_dpp v174, v70 row_ror:15 row_mask:0xf bank_mask:0xf
	v_mov_b32_dpp v175, v71 row_ror:15 row_mask:0xf bank_mask:0xf
	v_mov_b32_dpp v176, v72 row_ror:15 row_mask:0xf bank_mask:0xf
	v_mov_b32_dpp v177, v73 row_ror:15 row_mask:0xf bank_mask:0xf
	v_mov_b32_dpp v170, v74 row_shr:1 row_mask:0xf bank_mask:0xf
	v_mov_b32_dpp v171, v75 row_shr:1 row_mask:0xf bank_mask:0xf
	v_mov_b32_dpp v172, v76 row_shr:1 row_mask:0xf bank_mask:0xf
	v_mov_b32_dpp v173, v77 row_shr:1 row_mask:0xf bank_mask:0xf
	v_mov_b32_dpp v174, v74 row_shl:1 row_mask:0xf bank_mask:0xf
	v_mov_b32_dpp v175, v75 row_shl:1 row_mask:0xf bank_mask:0xf
	v_mov_b32_dpp v176, v76 row_shl:1 row_mask:0xf bank_mask:0xf
	v_mov_b32_dpp v177, v77 row_shl:1 row_mask:0xf bank_mask:0xf
	v_pk_mul_f32 v[170:171], v[222:223], v[170:171]
	v_pk_mul_f32 v[172:173], v[224:225], v[172:173]
	v_pk_mul_f32 v[174:175], v[230:231], v[174:175]
	v_pk_mul_f32 v[176:177], v[232:233], v[176:177]
	v_pk_fma_f32 v[164:165], v[74:75], v[226:227], v[170:171]
	v_pk_fma_f32 v[166:167], v[76:77], v[228:229], v[172:173]
	v_pk_add_f32 v[164:165], v[164:165], v[174:175]
	v_pk_add_f32 v[166:167], v[166:167], v[176:177]
	v_pk_add_f32 v[164:165], v[204:205], v[164:165]
	v_pk_add_f32 v[166:167], v[206:207], v[166:167]
	v_pk_mul_f32 v[178:179], v[164:165], s[4:5] op_sel_hi:[1,0]
	v_pk_mul_f32 v[184:185], v[166:167], s[4:5] op_sel_hi:[1,0]
	v_exp_f32_e32 v178, v178
	v_exp_f32_e32 v179, v179
	v_exp_f32_e32 v184, v184
	v_exp_f32_e32 v185, v185
	v_pk_add_f32 v[178:179], v[178:179], 1.0 op_sel_hi:[1,0]
	v_pk_add_f32 v[184:185], v[184:185], 1.0 op_sel_hi:[1,0]
	v_rcp_f32_e32 v180, v178
	v_rcp_f32_e32 v181, v179
	v_rcp_f32_e32 v192, v184
	v_rcp_f32_e32 v193, v185
	v_pk_fma_f32 v[182:183], v[178:179], v[180:181], 1.0 op_sel_hi:[1,1,0] neg_lo:[1,0,0] neg_hi:[1,0,0]
	v_pk_fma_f32 v[194:195], v[184:185], v[192:193], 1.0 op_sel_hi:[1,1,0] neg_lo:[1,0,0] neg_hi:[1,0,0]
	v_pk_fma_f32 v[180:181], v[182:183], v[180:181], v[180:181]
	v_pk_fma_f32 v[192:193], v[194:195], v[192:193], v[192:193]
	v_pk_mul_f32 v[164:165], v[164:165], v[180:181]
	v_pk_mul_f32 v[166:167], v[166:167], v[192:193]
	v_pk_mul_f32 v[164:165], v[0:1], v[164:165] op_sel_hi:[0,1]
	v_pk_mul_f32 v[166:167], v[0:1], v[166:167] op_sel_hi:[0,1]
	v_cvt_pk_bf16_f32 v196, v164, v165
	v_cvt_pk_bf16_f32 v197, v166, v167
	global_store_dwordx2 v[160:161], v[196:197], off offset:264
	v_lshl_add_u64 v[160:161], v[160:161], 0, s[68:69]
	v_mov_b32_dpp v170, v74 row_ror:1 row_mask:0xf bank_mask:0xf
	v_mov_b32_dpp v171, v75 row_ror:1 row_mask:0xf bank_mask:0xf
	v_mov_b32_dpp v172, v76 row_ror:1 row_mask:0xf bank_mask:0xf
	v_mov_b32_dpp v173, v77 row_ror:1 row_mask:0xf bank_mask:0xf
	v_mov_b32_dpp v174, v66 row_ror:15 row_mask:0xf bank_mask:0xf
	v_mov_b32_dpp v175, v67 row_ror:15 row_mask:0xf bank_mask:0xf
	v_mov_b32_dpp v176, v68 row_ror:15 row_mask:0xf bank_mask:0xf
	v_mov_b32_dpp v177, v69 row_ror:15 row_mask:0xf bank_mask:0xf
	v_mov_b32_dpp v170, v70 row_shr:1 row_mask:0xf bank_mask:0xf
	v_mov_b32_dpp v171, v71 row_shr:1 row_mask:0xf bank_mask:0xf
	v_mov_b32_dpp v172, v72 row_shr:1 row_mask:0xf bank_mask:0xf
	v_mov_b32_dpp v173, v73 row_shr:1 row_mask:0xf bank_mask:0xf
; __device__ __forceinline__ unsigned cvt_pk_bf16(float lo, float hi) { unsigned r; asm volatile("v_cvt_pk_bf16_f32 %0, %1, %2" : "=v"(r) : "v"(lo), "v"(hi)); return r; }
; __device__ __forceinline__ float sigmoidf_(float x) { return 1.0f / (1.0f + __expf(-x)); }
; __device__ __forceinline__ float dppf_prev(float cur, float below) { return __uint_as_float(dpp_prev(__float_as_uint(cur), __float_as_uint(below))); }
; __device__ __forceinline__ float dppf_next(float cur, float above) { return __uint_as_float(dpp_next(__float_as_uint(cur), __float_as_uint(above))); }
;     __device__ __forceinline__ void operator()(AccT& acc, const Unit& u, int wr, int wc, int fr, int fq) const {
;     ...
;             for (int ai = 0; ai < 2; ++ai) { const int grp = u.pm * 4 + ai * 2 + wr;
; #pragma unroll
;                 for (int bj = 0; bj < 2; ++bj) { const int mc = mc0 + bj * 128; const float mul = mc < 512 ? 0.08838834764831845f : 1.0f;
; #pragma unroll
;                     for (int n = 0; n < 2; ++n) {
;                         const f32x4 w0 = *(const f32x4*)(cw + mc + 4 * n), w1 = *(const f32x4*)(cw + 1024 + mc + 4 * n), w2 = *(const f32x4*)(cw + 2048 + mc + 4 * n), b = *(const f32x4*)(cb + mc + 4 * n);
; #pragma unroll
;                         for (int m = 0; m < 4; ++m) { const int lr = m * 16 + fr; const f32x4 gc = acc[ai][bj][m][n]; f32x4 o;
; #pragma unroll
;                             for (int j = 0; j < 4; ++j) { const float gp = dppf_prev(gc[j], m > 0 ? acc[ai][bj][m - 1][n][j] : 0.f), gn = dppf_next(gc[j], m < 3 ? acc[ai][bj][m + 1][n][j] : 0.f);
;                                 const float uu = gp * w0[j] + gc[j] * w1[j] + gn * w2[j] + b[j]; o[j] = uu * sigmoidf_(uu) * mul; }
;                             u32x2 w; w.x = cvt_pk_bf16(o[0], o[1]); w.y = cvt_pk_bf16(o[2], o[3]);
;                             *(u32x2*)(O + (size_t)(grp * 64 + lr) * NPROJ + col0 + bj * 128 + 4 * n) = w;
;                             if (m == 0 || m == 3) { if (lr < 2 || lr > 61) { u32x2 wg; wg.x = cvt_pk_bf16(gc[0], gc[1]); wg.y = cvt_pk_bf16(gc[2], gc[3]);
;                                 *(u32x2*)(HQ + (size_t)(grp * 4 + (lr < 2 ? lr : lr - 60)) * 1024 + mc + 4 * n) = wg; } } } } } }
	v_mov_b32_dpp v174, v70 row_shl:1 row_mask:0xf bank_mask:0xf
	v_mov_b32_dpp v175, v71 row_shl:1 row_mask:0xf bank_mask:0xf
	v_mov_b32_dpp v176, v72 row_shl:1 row_mask:0xf bank_mask:0xf
	v_mov_b32_dpp v177, v73 row_shl:1 row_mask:0xf bank_mask:0xf
	v_pk_mul_f32 v[170:171], v[222:223], v[170:171]
	v_pk_mul_f32 v[172:173], v[224:225], v[172:173]
	v_pk_mul_f32 v[174:175], v[230:231], v[174:175]
	v_pk_mul_f32 v[176:177], v[232:233], v[176:177]
	v_pk_fma_f32 v[164:165], v[70:71], v[226:227], v[170:171]
	v_pk_fma_f32 v[166:167], v[72:73], v[228:229], v[172:173]
	v_pk_add_f32 v[164:165], v[164:165], v[174:175]
	v_pk_add_f32 v[166:167], v[166:167], v[176:177]
	v_pk_add_f32 v[164:165], v[204:205], v[164:165]
	v_pk_add_f32 v[166:167], v[206:207], v[166:167]
	v_pk_mul_f32 v[178:179], v[164:165], s[4:5] op_sel_hi:[1,0]
	v_pk_mul_f32 v[184:185], v[166:167], s[4:5] op_sel_hi:[1,0]
	v_exp_f32_e32 v178, v178
	v_exp_f32_e32 v179, v179
	v_exp_f32_e32 v184, v184
	v_exp_f32_e32 v185, v185
	v_pk_add_f32 v[178:179], v[178:179], 1.0 op_sel_hi:[1,0]
	v_pk_add_f32 v[184:185], v[184:185], 1.0 op_sel_hi:[1,0]
	v_rcp_f32_e32 v180, v178
	v_rcp_f32_e32 v181, v179
	v_rcp_f32_e32 v192, v184
	v_rcp_f32_e32 v193, v185
	v_pk_fma_f32 v[182:183], v[178:179], v[180:181], 1.0 op_sel_hi:[1,1,0] neg_lo:[1,0,0] neg_hi:[1,0,0]
	v_pk_fma_f32 v[194:195], v[184:185], v[192:193], 1.0 op_sel_hi:[1,1,0] neg_lo:[1,0,0] neg_hi:[1,0,0]
	v_pk_fma_f32 v[180:181], v[182:183], v[180:181], v[180:181]
	v_pk_fma_f32 v[192:193], v[194:195], v[192:193], v[192:193]
	v_pk_mul_f32 v[164:165], v[164:165], v[180:181]
	v_pk_mul_f32 v[166:167], v[166:167], v[192:193]
	v_pk_mul_f32 v[164:165], v[0:1], v[164:165] op_sel_hi:[0,1]
	v_pk_mul_f32 v[166:167], v[0:1], v[166:167] op_sel_hi:[0,1]
	v_cvt_pk_bf16_f32 v196, v164, v165
	v_cvt_pk_bf16_f32 v197, v166, v167
	global_store_dwordx2 v[160:161], v[196:197], off offset:264
	v_lshl_add_u64 v[160:161], v[160:161], 0, s[68:69]
	v_mov_b32_dpp v170, v70 row_ror:1 row_mask:0xf bank_mask:0xf
	v_mov_b32_dpp v171, v71 row_ror:1 row_mask:0xf bank_mask:0xf
	v_mov_b32_dpp v172, v72 row_ror:1 row_mask:0xf bank_mask:0xf
	v_mov_b32_dpp v173, v73 row_ror:1 row_mask:0xf bank_mask:0xf
	v_mov_b32_e32 v174, 0
	v_mov_b32_e32 v175, 0
	v_mov_b32_e32 v176, 0
	v_mov_b32_e32 v177, 0
	v_mov_b32_dpp v170, v66 row_shr:1 row_mask:0xf bank_mask:0xf
	v_mov_b32_dpp v171, v67 row_shr:1 row_mask:0xf bank_mask:0xf
	v_mov_b32_dpp v172, v68 row_shr:1 row_mask:0xf bank_mask:0xf
	v_mov_b32_dpp v173, v69 row_shr:1 row_mask:0xf bank_mask:0xf
	v_mov_b32_dpp v174, v66 row_shl:1 row_mask:0xf bank_mask:0xf
	v_mov_b32_dpp v175, v67 row_shl:1 row_mask:0xf bank_mask:0xf
	v_mov_b32_dpp v176, v68 row_shl:1 row_mask:0xf bank_mask:0xf
	v_mov_b32_dpp v177, v69 row_shl:1 row_mask:0xf bank_mask:0xf
	v_pk_mul_f32 v[170:171], v[222:223], v[170:171]
	v_pk_mul_f32 v[172:173], v[224:225], v[172:173]
	v_pk_mul_f32 v[174:175], v[230:231], v[174:175]
	v_pk_mul_f32 v[176:177], v[232:233], v[176:177]
	v_pk_fma_f32 v[164:165], v[66:67], v[226:227], v[170:171]
	v_pk_fma_f32 v[166:167], v[68:69], v[228:229], v[172:173]
	v_pk_add_f32 v[164:165], v[164:165], v[174:175]
	v_pk_add_f32 v[166:167], v[166:167], v[176:177]
	v_pk_add_f32 v[164:165], v[204:205], v[164:165]
	v_pk_add_f32 v[166:167], v[206:207], v[166:167]
	v_pk_mul_f32 v[178:179], v[164:165], s[4:5] op_sel_hi:[1,0]
	v_pk_mul_f32 v[184:185], v[166:167], s[4:5] op_sel_hi:[1,0]
	v_exp_f32_e32 v178, v178
	v_exp_f32_e32 v179, v179
	v_exp_f32_e32 v184, v184
	v_exp_f32_e32 v185, v185
	v_pk_add_f32 v[178:179], v[178:179], 1.0 op_sel_hi:[1,0]
	v_pk_add_f32 v[184:185], v[184:185], 1.0 op_sel_hi:[1,0]
	v_rcp_f32_e32 v180, v178
	v_rcp_f32_e32 v181, v179
	v_rcp_f32_e32 v192, v184
	v_rcp_f32_e32 v193, v185
	v_pk_fma_f32 v[182:183], v[178:179], v[180:181], 1.0 op_sel_hi:[1,1,0] neg_lo:[1,0,0] neg_hi:[1,0,0]
	v_pk_fma_f32 v[194:195], v[184:185], v[192:193], 1.0 op_sel_hi:[1,1,0] neg_lo:[1,0,0] neg_hi:[1,0,0]
	v_pk_fma_f32 v[180:181], v[182:183], v[180:181], v[180:181]
	v_pk_fma_f32 v[192:193], v[194:195], v[192:193], v[192:193]
	v_pk_mul_f32 v[164:165], v[164:165], v[180:181]
	v_pk_mul_f32 v[166:167], v[166:167], v[192:193]
	v_pk_mul_f32 v[164:165], v[0:1], v[164:165] op_sel_hi:[0,1]
	v_pk_mul_f32 v[166:167], v[0:1], v[166:167] op_sel_hi:[0,1]
	v_cvt_pk_bf16_f32 v196, v164, v165
	v_cvt_pk_bf16_f32 v197, v166, v167
	global_store_dwordx2 v[160:161], v[196:197], off offset:264
	s_add_i32 s2, s0, 0
	s_lshl_b32 s2, s2, 2
	s_add_i32 s2, s2, -12
	s_lshl_b32 s2, s2, 11
	s_ashr_i32 s3, s2, 31
	s_add_u32 s70, s48, s2
	s_addc_u32 s71, s49, s3
	v_lshlrev_b32_e32 v200, 11, v190
	v_mov_b32_e32 v201, 0
	v_lshl_add_u64 v[200:201], v[200:201], 0, s[70:71]
	v_lshl_add_u64 v[200:201], v[158:159], 1, v[200:201]
	s_mov_b64 exec, s[44:45]
	v_cvt_pk_bf16_f32 v198, v66, v67
	v_cvt_pk_bf16_f32 v199, v68, v69
	global_store_dwordx2 v[200:201], v[198:199], off offset:-3832
	s_mov_b64 exec, -1
	s_add_i32 s2, s0, 2
	s_lshl_b32 s3, s2, 19
	s_add_u32 s70, s22, s3
	s_addc_u32 s71, s23, 0
	v_lshlrev_b32_e32 v200, 13, v190
	v_mov_b32_e32 v201, 0
	v_lshl_add_u64 v[160:161], v[200:201], 0, s[70:71]
	v_lshl_add_u64 v[160:161], v[158:159], 1, v[160:161]
	v_mov_b32_e32 v170, 0
	v_mov_b32_e32 v171, 0
	v_mov_b32_e32 v172, 0
	v_mov_b32_e32 v173, 0
	v_mov_b32_dpp v174, v10 row_ror:15 row_mask:0xf bank_mask:0xf
	v_mov_b32_dpp v175, v11 row_ror:15 row_mask:0xf bank_mask:0xf
	v_mov_b32_dpp v176, v12 row_ror:15 row_mask:0xf bank_mask:0xf
	v_mov_b32_dpp v177, v13 row_ror:15 row_mask:0xf bank_mask:0xf
	v_mov_b32_dpp v170, v14 row_shr:1 row_mask:0xf bank_mask:0xf
	v_mov_b32_dpp v171, v15 row_shr:1 row_mask:0xf bank_mask:0xf
; __device__ __forceinline__ unsigned cvt_pk_bf16(float lo, float hi) { unsigned r; asm volatile("v_cvt_pk_bf16_f32 %0, %1, %2" : "=v"(r) : "v"(lo), "v"(hi)); return r; }
; __device__ __forceinline__ float sigmoidf_(float x) { return 1.0f / (1.0f + __expf(-x)); }
; __device__ __forceinline__ float dppf_prev(float cur, float below) { return __uint_as_float(dpp_prev(__float_as_uint(cur), __float_as_uint(below))); }
; __device__ __forceinline__ float dppf_next(float cur, float above) { return __uint_as_float(dpp_next(__float_as_uint(cur), __float_as_uint(above))); }
;     __device__ __forceinline__ void operator()(AccT& acc, const Unit& u, int wr, int wc, int fr, int fq) const {
;     ...
;             for (int ai = 0; ai < 2; ++ai) { const int grp = u.pm * 4 + ai * 2 + wr;
; #pragma unroll
;                 for (int bj = 0; bj < 2; ++bj) { const int mc = mc0 + bj * 128; const float mul = mc < 512 ? 0.08838834764831845f : 1.0f;
; #pragma unroll
;                     for (int n = 0; n < 2; ++n) {
;                         const f32x4 w0 = *(const f32x4*)(cw + mc + 4 * n), w1 = *(const f32x4*)(cw + 1024 + mc + 4 * n), w2 = *(const f32x4*)(cw + 2048 + mc + 4 * n), b = *(const f32x4*)(cb + mc + 4 * n);
; #pragma unroll
;                         for (int m = 0; m < 4; ++m) { const int lr = m * 16 + fr; const f32x4 gc = acc[ai][bj][m][n]; f32x4 o;
; #pragma unroll
;                             for (int j = 0; j < 4; ++j) { const float gp = dppf_prev(gc[j], m > 0 ? acc[ai][bj][m - 1][n][j] : 0.f), gn = dppf_next(gc[j], m < 3 ? acc[ai][bj][m + 1][n][j] : 0.f);
;                                 const float uu = gp * w0[j] + gc[j] * w1[j] + gn * w2[j] + b[j]; o[j] = uu * sigmoidf_(uu) * mul; }
;                             u32x2 w; w.x = cvt_pk_bf16(o[0], o[1]); w.y = cvt_pk_bf16(o[2], o[3]);
;                             *(u32x2*)(O + (size_t)(grp * 64 + lr) * NPROJ + col0 + bj * 128 + 4 * n) = w;
;                             if (m == 0 || m == 3) { if (lr < 2 || lr > 61) { u32x2 wg; wg.x = cvt_pk_bf16(gc[0], gc[1]); wg.y = cvt_pk_bf16(gc[2], gc[3]);
;                                 *(u32x2*)(HQ + (size_t)(grp * 4 + (lr < 2 ? lr : lr - 60)) * 1024 + mc + 4 * n) = wg; } } } } } }
	v_mov_b32_dpp v172, v16 row_shr:1 row_mask:0xf bank_mask:0xf
	v_mov_b32_dpp v173, v17 row_shr:1 row_mask:0xf bank_mask:0xf
	v_mov_b32_dpp v174, v14 row_shl:1 row_mask:0xf bank_mask:0xf
	v_mov_b32_dpp v175, v15 row_shl:1 row_mask:0xf bank_mask:0xf
	v_mov_b32_dpp v176, v16 row_shl:1 row_mask:0xf bank_mask:0xf
	v_mov_b32_dpp v177, v17 row_shl:1 row_mask:0xf bank_mask:0xf
	v_pk_mul_f32 v[170:171], v[222:223], v[170:171]
	v_pk_mul_f32 v[172:173], v[224:225], v[172:173]
	v_pk_mul_f32 v[174:175], v[230:231], v[174:175]
	v_pk_mul_f32 v[176:177], v[232:233], v[176:177]
	v_pk_fma_f32 v[164:165], v[14:15], v[226:227], v[170:171]
	v_pk_fma_f32 v[166:167], v[16:17], v[228:229], v[172:173]
	v_pk_add_f32 v[164:165], v[164:165], v[174:175]
	v_pk_add_f32 v[166:167], v[166:167], v[176:177]
	v_pk_add_f32 v[164:165], v[204:205], v[164:165]
	v_pk_add_f32 v[166:167], v[206:207], v[166:167]
	v_pk_mul_f32 v[178:179], v[164:165], s[4:5] op_sel_hi:[1,0]
	v_pk_mul_f32 v[184:185], v[166:167], s[4:5] op_sel_hi:[1,0]
	v_exp_f32_e32 v178, v178
	v_exp_f32_e32 v179, v179
	v_exp_f32_e32 v184, v184
	v_exp_f32_e32 v185, v185
	v_pk_add_f32 v[178:179], v[178:179], 1.0 op_sel_hi:[1,0]
	v_pk_add_f32 v[184:185], v[184:185], 1.0 op_sel_hi:[1,0]
	v_rcp_f32_e32 v180, v178
	v_rcp_f32_e32 v181, v179
	v_rcp_f32_e32 v192, v184
	v_rcp_f32_e32 v193, v185
	v_pk_fma_f32 v[182:183], v[178:179], v[180:181], 1.0 op_sel_hi:[1,1,0] neg_lo:[1,0,0] neg_hi:[1,0,0]
	v_pk_fma_f32 v[194:195], v[184:185], v[192:193], 1.0 op_sel_hi:[1,1,0] neg_lo:[1,0,0] neg_hi:[1,0,0]
	v_pk_fma_f32 v[180:181], v[182:183], v[180:181], v[180:181]
	v_pk_fma_f32 v[192:193], v[194:195], v[192:193], v[192:193]
	v_pk_mul_f32 v[164:165], v[164:165], v[180:181]
	v_pk_mul_f32 v[166:167], v[166:167], v[192:193]
	v_pk_mul_f32 v[164:165], v[0:1], v[164:165] op_sel_hi:[0,1]
	v_pk_mul_f32 v[166:167], v[0:1], v[166:167] op_sel_hi:[0,1]
	v_cvt_pk_bf16_f32 v196, v164, v165
	v_cvt_pk_bf16_f32 v197, v166, v167
	global_store_dwordx2 v[160:161], v[196:197], off offset:264
	v_lshl_add_u64 v[160:161], v[160:161], 0, s[68:69]
	s_add_i32 s2, s0, 2
	s_lshl_b32 s2, s2, 2
	s_lshl_b32 s2, s2, 11
	s_ashr_i32 s3, s2, 31
	s_add_u32 s70, s48, s2
	s_addc_u32 s71, s49, s3
	v_lshlrev_b32_e32 v200, 11, v190
	v_mov_b32_e32 v201, 0
	v_lshl_add_u64 v[200:201], v[200:201], 0, s[70:71]
	v_lshl_add_u64 v[200:201], v[158:159], 1, v[200:201]
	s_mov_b64 exec, s[42:43]
	v_cvt_pk_bf16_f32 v198, v14, v15
	v_cvt_pk_bf16_f32 v199, v16, v17
	global_store_dwordx2 v[200:201], v[198:199], off offset:-3832
	s_mov_b64 exec, -1
	v_mov_b32_dpp v170, v14 row_ror:1 row_mask:0xf bank_mask:0xf
	v_mov_b32_dpp v171, v15 row_ror:1 row_mask:0xf bank_mask:0xf
	v_mov_b32_dpp v172, v16 row_ror:1 row_mask:0xf bank_mask:0xf
	v_mov_b32_dpp v173, v17 row_ror:1 row_mask:0xf bank_mask:0xf
	v_mov_b32_dpp v174, v6 row_ror:15 row_mask:0xf bank_mask:0xf
	v_mov_b32_dpp v175, v7 row_ror:15 row_mask:0xf bank_mask:0xf
	v_mov_b32_dpp v176, v8 row_ror:15 row_mask:0xf bank_mask:0xf
	v_mov_b32_dpp v177, v9 row_ror:15 row_mask:0xf bank_mask:0xf
	v_mov_b32_dpp v170, v10 row_shr:1 row_mask:0xf bank_mask:0xf
	v_mov_b32_dpp v171, v11 row_shr:1 row_mask:0xf bank_mask:0xf
	v_mov_b32_dpp v172, v12 row_shr:1 row_mask:0xf bank_mask:0xf
	v_mov_b32_dpp v173, v13 row_shr:1 row_mask:0xf bank_mask:0xf
	v_mov_b32_dpp v174, v10 row_shl:1 row_mask:0xf bank_mask:0xf
	v_mov_b32_dpp v175, v11 row_shl:1 row_mask:0xf bank_mask:0xf
	v_mov_b32_dpp v176, v12 row_shl:1 row_mask:0xf bank_mask:0xf
	v_mov_b32_dpp v177, v13 row_shl:1 row_mask:0xf bank_mask:0xf
	v_pk_mul_f32 v[170:171], v[222:223], v[170:171]
	v_pk_mul_f32 v[172:173], v[224:225], v[172:173]
	v_pk_mul_f32 v[174:175], v[230:231], v[174:175]
	v_pk_mul_f32 v[176:177], v[232:233], v[176:177]
	v_pk_fma_f32 v[164:165], v[10:11], v[226:227], v[170:171]
	v_pk_fma_f32 v[166:167], v[12:13], v[228:229], v[172:173]
	v_pk_add_f32 v[164:165], v[164:165], v[174:175]
	v_pk_add_f32 v[166:167], v[166:167], v[176:177]
	v_pk_add_f32 v[164:165], v[204:205], v[164:165]
	v_pk_add_f32 v[166:167], v[206:207], v[166:167]
	v_pk_mul_f32 v[178:179], v[164:165], s[4:5] op_sel_hi:[1,0]
	v_pk_mul_f32 v[184:185], v[166:167], s[4:5] op_sel_hi:[1,0]
	v_exp_f32_e32 v178, v178
	v_exp_f32_e32 v179, v179
	v_exp_f32_e32 v184, v184
	v_exp_f32_e32 v185, v185
	v_pk_add_f32 v[178:179], v[178:179], 1.0 op_sel_hi:[1,0]
	v_pk_add_f32 v[184:185], v[184:185], 1.0 op_sel_hi:[1,0]
	v_rcp_f32_e32 v180, v178
	v_rcp_f32_e32 v181, v179
	v_rcp_f32_e32 v192, v184
	v_rcp_f32_e32 v193, v185
	v_pk_fma_f32 v[182:183], v[178:179], v[180:181], 1.0 op_sel_hi:[1,1,0] neg_lo:[1,0,0] neg_hi:[1,0,0]
	v_pk_fma_f32 v[194:195], v[184:185], v[192:193], 1.0 op_sel_hi:[1,1,0] neg_lo:[1,0,0] neg_hi:[1,0,0]
	v_pk_fma_f32 v[180:181], v[182:183], v[180:181], v[180:181]
	v_pk_fma_f32 v[192:193], v[194:195], v[192:193], v[192:193]
	v_pk_mul_f32 v[164:165], v[164:165], v[180:181]
	v_pk_mul_f32 v[166:167], v[166:167], v[192:193]
	v_pk_mul_f32 v[164:165], v[0:1], v[164:165] op_sel_hi:[0,1]
	v_pk_mul_f32 v[166:167], v[0:1], v[166:167] op_sel_hi:[0,1]
	v_cvt_pk_bf16_f32 v196, v164, v165
	v_cvt_pk_bf16_f32 v197, v166, v167
	global_store_dwordx2 v[160:161], v[196:197], off offset:264
	v_lshl_add_u64 v[160:161], v[160:161], 0, s[68:69]
	v_mov_b32_dpp v170, v10 row_ror:1 row_mask:0xf bank_mask:0xf
	v_mov_b32_dpp v171, v11 row_ror:1 row_mask:0xf bank_mask:0xf
	v_mov_b32_dpp v172, v12 row_ror:1 row_mask:0xf bank_mask:0xf
; __device__ __forceinline__ unsigned cvt_pk_bf16(float lo, float hi) { unsigned r; asm volatile("v_cvt_pk_bf16_f32 %0, %1, %2" : "=v"(r) : "v"(lo), "v"(hi)); return r; }
; __device__ __forceinline__ float sigmoidf_(float x) { return 1.0f / (1.0f + __expf(-x)); }
; __device__ __forceinline__ float dppf_prev(float cur, float below) { return __uint_as_float(dpp_prev(__float_as_uint(cur), __float_as_uint(below))); }
; __device__ __forceinline__ float dppf_next(float cur, float above) { return __uint_as_float(dpp_next(__float_as_uint(cur), __float_as_uint(above))); }
;     __device__ __forceinline__ void operator()(AccT& acc, const Unit& u, int wr, int wc, int fr, int fq) const {
;     ...
;                         for (int m = 0; m < 4; ++m) { const int lr = m * 16 + fr; const f32x4 gc = acc[ai][bj][m][n]; f32x4 o;
; #pragma unroll
;                             for (int j = 0; j < 4; ++j) { const float gp = dppf_prev(gc[j], m > 0 ? acc[ai][bj][m - 1][n][j] : 0.f), gn = dppf_next(gc[j], m < 3 ? acc[ai][bj][m + 1][n][j] : 0.f);
;                                 const float uu = gp * w0[j] + gc[j] * w1[j] + gn * w2[j] + b[j]; o[j] = uu * sigmoidf_(uu) * mul; }
;                             u32x2 w; w.x = cvt_pk_bf16(o[0], o[1]); w.y = cvt_pk_bf16(o[2], o[3]);
;                             *(u32x2*)(O + (size_t)(grp * 64 + lr) * NPROJ + col0 + bj * 128 + 4 * n) = w;
;                             if (m == 0 || m == 3) { if (lr < 2 || lr > 61) { u32x2 wg; wg.x = cvt_pk_bf16(gc[0], gc[1]); wg.y = cvt_pk_bf16(gc[2], gc[3]);
;                                 *(u32x2*)(HQ + (size_t)(grp * 4 + (lr < 2 ? lr : lr - 60)) * 1024 + mc + 4 * n) = wg; } } } } } }
	v_mov_b32_dpp v173, v13 row_ror:1 row_mask:0xf bank_mask:0xf
	v_mov_b32_dpp v174, v2 row_ror:15 row_mask:0xf bank_mask:0xf
	v_mov_b32_dpp v175, v3 row_ror:15 row_mask:0xf bank_mask:0xf
	v_mov_b32_dpp v176, v4 row_ror:15 row_mask:0xf bank_mask:0xf
	v_mov_b32_dpp v177, v5 row_ror:15 row_mask:0xf bank_mask:0xf
	v_mov_b32_dpp v170, v6 row_shr:1 row_mask:0xf bank_mask:0xf
	v_mov_b32_dpp v171, v7 row_shr:1 row_mask:0xf bank_mask:0xf
	v_mov_b32_dpp v172, v8 row_shr:1 row_mask:0xf bank_mask:0xf
	v_mov_b32_dpp v173, v9 row_shr:1 row_mask:0xf bank_mask:0xf
	v_mov_b32_dpp v174, v6 row_shl:1 row_mask:0xf bank_mask:0xf
	v_mov_b32_dpp v175, v7 row_shl:1 row_mask:0xf bank_mask:0xf
	v_mov_b32_dpp v176, v8 row_shl:1 row_mask:0xf bank_mask:0xf
	v_mov_b32_dpp v177, v9 row_shl:1 row_mask:0xf bank_mask:0xf
	v_pk_mul_f32 v[170:171], v[222:223], v[170:171]
	v_pk_mul_f32 v[172:173], v[224:225], v[172:173]
	v_pk_mul_f32 v[174:175], v[230:231], v[174:175]
	v_pk_mul_f32 v[176:177], v[232:233], v[176:177]
	v_pk_fma_f32 v[164:165], v[6:7], v[226:227], v[170:171]
	v_pk_fma_f32 v[166:167], v[8:9], v[228:229], v[172:173]
	v_pk_add_f32 v[164:165], v[164:165], v[174:175]
	v_pk_add_f32 v[166:167], v[166:167], v[176:177]
	v_pk_add_f32 v[164:165], v[204:205], v[164:165]
	v_pk_add_f32 v[166:167], v[206:207], v[166:167]
	v_pk_mul_f32 v[178:179], v[164:165], s[4:5] op_sel_hi:[1,0]
	v_pk_mul_f32 v[184:185], v[166:167], s[4:5] op_sel_hi:[1,0]
	v_exp_f32_e32 v178, v178
	v_exp_f32_e32 v179, v179
	v_exp_f32_e32 v184, v184
	v_exp_f32_e32 v185, v185
	v_pk_add_f32 v[178:179], v[178:179], 1.0 op_sel_hi:[1,0]
	v_pk_add_f32 v[184:185], v[184:185], 1.0 op_sel_hi:[1,0]
	v_rcp_f32_e32 v180, v178
	v_rcp_f32_e32 v181, v179
	v_rcp_f32_e32 v192, v184
	v_rcp_f32_e32 v193, v185
	v_pk_fma_f32 v[182:183], v[178:179], v[180:181], 1.0 op_sel_hi:[1,1,0] neg_lo:[1,0,0] neg_hi:[1,0,0]
	v_pk_fma_f32 v[194:195], v[184:185], v[192:193], 1.0 op_sel_hi:[1,1,0] neg_lo:[1,0,0] neg_hi:[1,0,0]
	v_pk_fma_f32 v[180:181], v[182:183], v[180:181], v[180:181]
	v_pk_fma_f32 v[192:193], v[194:195], v[192:193], v[192:193]
	v_pk_mul_f32 v[164:165], v[164:165], v[180:181]
	v_pk_mul_f32 v[166:167], v[166:167], v[192:193]
	v_pk_mul_f32 v[164:165], v[0:1], v[164:165] op_sel_hi:[0,1]
	v_pk_mul_f32 v[166:167], v[0:1], v[166:167] op_sel_hi:[0,1]
	v_cvt_pk_bf16_f32 v196, v164, v165
	v_cvt_pk_bf16_f32 v197, v166, v167
	global_store_dwordx2 v[160:161], v[196:197], off offset:264
	v_lshl_add_u64 v[160:161], v[160:161], 0, s[68:69]
	v_mov_b32_dpp v170, v6 row_ror:1 row_mask:0xf bank_mask:0xf
	v_mov_b32_dpp v171, v7 row_ror:1 row_mask:0xf bank_mask:0xf
	v_mov_b32_dpp v172, v8 row_ror:1 row_mask:0xf bank_mask:0xf
	v_mov_b32_dpp v173, v9 row_ror:1 row_mask:0xf bank_mask:0xf
	v_mov_b32_e32 v174, 0
	v_mov_b32_e32 v175, 0
	v_mov_b32_e32 v176, 0
	v_mov_b32_e32 v177, 0
	v_mov_b32_dpp v170, v2 row_shr:1 row_mask:0xf bank_mask:0xf
	v_mov_b32_dpp v171, v3 row_shr:1 row_mask:0xf bank_mask:0xf
	v_mov_b32_dpp v172, v4 row_shr:1 row_mask:0xf bank_mask:0xf
	v_mov_b32_dpp v173, v5 row_shr:1 row_mask:0xf bank_mask:0xf
	v_mov_b32_dpp v174, v2 row_shl:1 row_mask:0xf bank_mask:0xf
	v_mov_b32_dpp v175, v3 row_shl:1 row_mask:0xf bank_mask:0xf
	v_mov_b32_dpp v176, v4 row_shl:1 row_mask:0xf bank_mask:0xf
	v_mov_b32_dpp v177, v5 row_shl:1 row_mask:0xf bank_mask:0xf
	v_pk_mul_f32 v[170:171], v[222:223], v[170:171]
	v_pk_mul_f32 v[172:173], v[224:225], v[172:173]
	v_pk_mul_f32 v[174:175], v[230:231], v[174:175]
	v_pk_mul_f32 v[176:177], v[232:233], v[176:177]
	v_pk_fma_f32 v[164:165], v[2:3], v[226:227], v[170:171]
	v_pk_fma_f32 v[166:167], v[4:5], v[228:229], v[172:173]
	v_pk_add_f32 v[164:165], v[164:165], v[174:175]
	v_pk_add_f32 v[166:167], v[166:167], v[176:177]
	v_pk_add_f32 v[164:165], v[204:205], v[164:165]
	v_pk_add_f32 v[166:167], v[206:207], v[166:167]
	v_pk_mul_f32 v[178:179], v[164:165], s[4:5] op_sel_hi:[1,0]
	v_pk_mul_f32 v[184:185], v[166:167], s[4:5] op_sel_hi:[1,0]
	v_exp_f32_e32 v178, v178
	v_exp_f32_e32 v179, v179
	v_exp_f32_e32 v184, v184
	v_exp_f32_e32 v185, v185
	v_pk_add_f32 v[178:179], v[178:179], 1.0 op_sel_hi:[1,0]
	v_pk_add_f32 v[184:185], v[184:185], 1.0 op_sel_hi:[1,0]
	v_rcp_f32_e32 v180, v178
	v_rcp_f32_e32 v181, v179
	v_rcp_f32_e32 v192, v184
	v_rcp_f32_e32 v193, v185
	v_pk_fma_f32 v[182:183], v[178:179], v[180:181], 1.0 op_sel_hi:[1,1,0] neg_lo:[1,0,0] neg_hi:[1,0,0]
	v_pk_fma_f32 v[194:195], v[184:185], v[192:193], 1.0 op_sel_hi:[1,1,0] neg_lo:[1,0,0] neg_hi:[1,0,0]
	v_pk_fma_f32 v[180:181], v[182:183], v[180:181], v[180:181]
	v_pk_fma_f32 v[192:193], v[194:195], v[192:193], v[192:193]
	v_pk_mul_f32 v[164:165], v[164:165], v[180:181]
	v_pk_mul_f32 v[166:167], v[166:167], v[192:193]
	v_pk_mul_f32 v[164:165], v[0:1], v[164:165] op_sel_hi:[0,1]
	v_pk_mul_f32 v[166:167], v[0:1], v[166:167] op_sel_hi:[0,1]
	v_cvt_pk_bf16_f32 v196, v164, v165
	v_cvt_pk_bf16_f32 v197, v166, v167
	global_store_dwordx2 v[160:161], v[196:197], off offset:264
	s_add_i32 s2, s0, 2
	s_lshl_b32 s2, s2, 2
	s_add_i32 s2, s2, -12
	s_lshl_b32 s2, s2, 11
	s_ashr_i32 s3, s2, 31
	s_add_u32 s70, s48, s2
	s_addc_u32 s71, s49, s3
	v_lshlrev_b32_e32 v200, 11, v190
	v_mov_b32_e32 v201, 0
	v_lshl_add_u64 v[200:201], v[200:201], 0, s[70:71]
	v_lshl_add_u64 v[200:201], v[158:159], 1, v[200:201]
	s_mov_b64 exec, s[44:45]
	v_cvt_pk_bf16_f32 v198, v2, v3
	v_cvt_pk_bf16_f32 v199, v4, v5
	global_store_dwordx2 v[200:201], v[198:199], off offset:-3832
	s_mov_b64 exec, -1
	s_branch .LBB0_599
